# loop-edge edit: K-loop back-edge counter and pointer updates hoisted above the loop-back barrier in 11 GEMM loops
# baseline (speedup 1.0000x reference)
; #define PG8_STAGE(bufoff, gbase, voff) do { _Pragma("unroll") for (int _i = 0; _i < 2; ++_i) \
;         __builtin_amdgcn_global_load_lds((const unsigned*)((const char*)(gbase) + (voff)[_i]), (LAS unsigned*)(lds + (bufoff) + ldsw + _i * 8192), 16, 0, 0); } while (0)
; #define PG8_LDA(dst, b, h) do { _Pragma("unroll") for (int m = 0; m < 4; ++m) _Pragma("unroll") for (int k = 0; k < 2; ++k) dst[m][k] = *(const LAS bf16x8*)(lds + PG8_SA(b, h) + aoff + m * 2048 + k * 1024); } while (0)
; #define PG8_LDB(dst, b, h) do { _Pragma("unroll") for (int n = 0; n < 2; ++n) _Pragma("unroll") for (int k = 0; k < 2; ++k) dst[n][k] = *(const LAS bf16x8*)(lds + PG8_SB(b, h) + boff + n * 2048 + k * 1024); } while (0)
; #define PG8_MMA(ai, bj, At, Bt) do { __builtin_amdgcn_s_setprio(1); _Pragma("unroll") for (int m = 0; m < 4; ++m) _Pragma("unroll") for (int n = 0; n < 2; ++n) _Pragma("unroll") for (int k = 0; k < 2; ++k) \
;         acc[ai][bj][m][n] = __builtin_amdgcn_mfma_f32_16x16x32_bf16(Bt[n][k], At[m][k], acc[ai][bj][m][n], 0, 0, 0); __builtin_amdgcn_s_setprio(0); } while (0)
; #define PG8_WAIT_V(n) asm volatile("s_waitcnt vmcnt(" #n ")" ::: "memory")
; #define PG8_WAIT_L(n) asm volatile("s_waitcnt lgkmcnt(" #n ")" ::: "memory")
; #define PG8_BAR __builtin_amdgcn_s_barrier()
; #define PG8_SCHED __builtin_amdgcn_sched_barrier(0)
; template <class Epi>
; __device__ __forceinline__ void gemm_phase(LAS unsigned char* lds, const Gemm g, const int G, const int cidx, const int tid, const Epi& E) {
;     ...
;             PG8_LDB(B0, 0, 0); PG8_LDB(B1, 0, 1); PG8_SCHED; PG8_LDA(At, 0, 0); PG8_STAGE(PG8_SA(1, 1), a1 + hstepA, voffA);
;             PG8_WAIT_V(8); PG8_WAIT_L(0); PG8_BAR; PG8_MMA(0, 0, At, B0); PG8_MMA(0, 1, At, B1); PG8_BAR; PG8_SCHED;
;             PG8_LDA(At, 0, 1); PG8_STAGE(PG8_SB(0, 0), b2, voffB); PG8_STAGE(PG8_SB(0, 1), b2 + hstepB, voffB); PG8_STAGE(PG8_SA(0, 0), a2, voffA);
;             PG8_WAIT_V(8); PG8_WAIT_L(0); PG8_BAR; PG8_MMA(1, 0, At, B0); PG8_MMA(1, 1, At, B1); PG8_BAR; PG8_SCHED;
.LBB0_102:
	s_add_u32 s30, s52, 0xfffc0080
	s_addc_u32 s54, s53, -1
	s_add_i32 s66, 0, 0x10000
	s_cmp_eq_u32 s94, 12
	s_cselect_b32 s57, s13, s54
	s_cselect_b32 s56, s35, s30
	v_add_u32_e32 v150, s66, v140
	s_cselect_b32 s55, s11, s92
	s_cselect_b32 s54, s64, s65
	s_add_i32 s30, 0, 0x14000
	ds_read_b128 v[142:145], v150
	ds_read_b128 v[146:149], v150 offset:1024
	ds_read_b128 v[164:167], v150 offset:2048
	ds_read_b128 v[168:171], v150 offset:3072
	v_add_u32_e32 v150, s30, v140
	ds_read_b128 v[172:175], v150
	ds_read_b128 v[176:179], v150 offset:1024
	ds_read_b128 v[180:183], v150 offset:2048
	ds_read_b128 v[184:187], v150 offset:3072
	v_lshl_add_u64 v[150:151], s[52:53], 0, v[134:135]
	s_add_i32 m0, s19, 0xc000
	ds_read_b128 v[188:191], v141
	ds_read_b128 v[210:213], v141 offset:1024
	ds_read_b128 v[214:217], v141 offset:2048
	ds_read_b128 v[218:221], v141 offset:3072
	ds_read_b128 v[222:225], v141 offset:4096
	ds_read_b128 v[226:229], v141 offset:5120
	ds_read_b128 v[230:233], v141 offset:6144
	ds_read_b128 v[234:237], v141 offset:7168
	global_load_lds_dwordx4 v[150:151], off
	v_lshl_add_u64 v[150:151], s[52:53], 0, v[136:137]
	s_add_i32 m0, s19, 0xe000
	s_nop 0
	global_load_lds_dwordx4 v[150:151], off
	s_waitcnt vmcnt(8)
	s_waitcnt lgkmcnt(0)
	s_barrier
	s_setprio 1
	s_waitcnt lgkmcnt(0)
	v_mfma_f32_16x16x32_bf16 v[124:127], v[142:145], v[188:191], v[124:127]
	v_mfma_f32_16x16x32_bf16 v[120:123], v[164:167], v[188:191], v[120:123]
	v_mfma_f32_16x16x32_bf16 v[108:111], v[142:145], v[214:217], v[108:111]
	v_mfma_f32_16x16x32_bf16 v[104:107], v[164:167], v[214:217], v[104:107]
	v_mfma_f32_16x16x32_bf16 v[92:95], v[142:145], v[222:225], v[92:95]
	v_mfma_f32_16x16x32_bf16 v[88:91], v[164:167], v[222:225], v[88:91]
	v_mfma_f32_16x16x32_bf16 v[76:79], v[142:145], v[230:233], v[76:79]
	v_mfma_f32_16x16x32_bf16 v[72:75], v[164:167], v[230:233], v[72:75]
	v_mfma_f32_16x16x32_bf16 v[124:127], v[146:149], v[210:213], v[124:127]
	v_mfma_f32_16x16x32_bf16 v[120:123], v[168:171], v[210:213], v[120:123]
	v_mfma_f32_16x16x32_bf16 v[108:111], v[146:149], v[218:221], v[108:111]
	v_mfma_f32_16x16x32_bf16 v[104:107], v[168:171], v[218:221], v[104:107]
	v_mfma_f32_16x16x32_bf16 v[92:95], v[146:149], v[226:229], v[92:95]
	v_mfma_f32_16x16x32_bf16 v[88:91], v[168:171], v[226:229], v[88:91]
	v_mfma_f32_16x16x32_bf16 v[76:79], v[146:149], v[234:237], v[76:79]
	v_mfma_f32_16x16x32_bf16 v[72:75], v[168:171], v[234:237], v[72:75]
	s_setprio 0
	s_setprio 1
	v_mfma_f32_16x16x32_bf16 v[116:119], v[172:175], v[188:191], v[116:119]
	v_mfma_f32_16x16x32_bf16 v[112:115], v[180:183], v[188:191], v[112:115]
	v_mfma_f32_16x16x32_bf16 v[100:103], v[172:175], v[214:217], v[100:103]
	v_mfma_f32_16x16x32_bf16 v[96:99], v[180:183], v[214:217], v[96:99]
	v_mfma_f32_16x16x32_bf16 v[84:87], v[172:175], v[222:225], v[84:87]
	v_mfma_f32_16x16x32_bf16 v[80:83], v[180:183], v[222:225], v[80:83]
	v_mfma_f32_16x16x32_bf16 v[68:71], v[172:175], v[230:233], v[68:71]
	v_mfma_f32_16x16x32_bf16 v[64:67], v[180:183], v[230:233], v[64:67]
	v_mfma_f32_16x16x32_bf16 v[116:119], v[176:179], v[210:213], v[116:119]
	v_mfma_f32_16x16x32_bf16 v[112:115], v[184:187], v[210:213], v[112:115]
	v_mfma_f32_16x16x32_bf16 v[100:103], v[176:179], v[218:221], v[100:103]
	v_mfma_f32_16x16x32_bf16 v[96:99], v[184:187], v[218:221], v[96:99]
	v_mfma_f32_16x16x32_bf16 v[84:87], v[176:179], v[226:229], v[84:87]
	v_mfma_f32_16x16x32_bf16 v[80:83], v[184:187], v[226:229], v[80:83]
	v_mfma_f32_16x16x32_bf16 v[68:71], v[176:179], v[234:237], v[68:71]
	v_mfma_f32_16x16x32_bf16 v[64:67], v[184:187], v[234:237], v[64:67]
	s_setprio 0
	s_barrier
	s_add_i32 s66, s66, s25
	v_lshl_add_u64 v[150:151], s[54:55], 0, v[152:153]
	s_mov_b32 m0, s66
	ds_read_b128 v[188:191], v141 offset:16384
	ds_read_b128 v[210:213], v141 offset:17408
	ds_read_b128 v[214:217], v141 offset:18432
	ds_read_b128 v[218:221], v141 offset:19456
	ds_read_b128 v[222:225], v141 offset:20480
	ds_read_b128 v[226:229], v141 offset:21504
	ds_read_b128 v[230:233], v141 offset:22528
	ds_read_b128 v[234:237], v141 offset:23552
	global_load_lds_dwordx4 v[150:151], off
	s_add_i32 m0, s66, 0x2000
	s_add_u32 s66, s54, 0x40000
	v_lshl_add_u64 v[158:159], s[54:55], 0, v[132:133]
	s_addc_u32 s67, s55, 0
	s_add_i32 s30, s30, s25
	global_load_lds_dwordx4 v[158:159], off
	v_lshl_add_u64 v[192:193], s[66:67], 0, v[152:153]
	s_mov_b32 m0, s30
	v_lshl_add_u64 v[208:209], s[56:57], 0, v[130:131]
	global_load_lds_dwordx4 v[192:193], off
	v_lshl_add_u64 v[192:193], s[66:67], 0, v[132:133]
	s_add_i32 m0, s30, 0x2000
	s_nop 0
	global_load_lds_dwordx4 v[192:193], off
	v_lshl_add_u64 v[192:193], s[56:57], 0, v[128:129]
	s_mov_b32 m0, s19
	s_nop 0
	global_load_lds_dwordx4 v[192:193], off
	s_mov_b32 m0, s29
	s_nop 0
	global_load_lds_dwordx4 v[208:209], off
	s_waitcnt vmcnt(8)
	s_waitcnt lgkmcnt(0)
	s_barrier
; #define PG8_STAGE(bufoff, gbase, voff) do { _Pragma("unroll") for (int _i = 0; _i < 2; ++_i) \
;         __builtin_amdgcn_global_load_lds((const unsigned*)((const char*)(gbase) + (voff)[_i]), (LAS unsigned*)(lds + (bufoff) + ldsw + _i * 8192), 16, 0, 0); } while (0)
; #define PG8_LDA(dst, b, h) do { _Pragma("unroll") for (int m = 0; m < 4; ++m) _Pragma("unroll") for (int k = 0; k < 2; ++k) dst[m][k] = *(const LAS bf16x8*)(lds + PG8_SA(b, h) + aoff + m * 2048 + k * 1024); } while (0)
; #define PG8_LDB(dst, b, h) do { _Pragma("unroll") for (int n = 0; n < 2; ++n) _Pragma("unroll") for (int k = 0; k < 2; ++k) dst[n][k] = *(const LAS bf16x8*)(lds + PG8_SB(b, h) + boff + n * 2048 + k * 1024); } while (0)
; #define PG8_MMA(ai, bj, At, Bt) do { __builtin_amdgcn_s_setprio(1); _Pragma("unroll") for (int m = 0; m < 4; ++m) _Pragma("unroll") for (int n = 0; n < 2; ++n) _Pragma("unroll") for (int k = 0; k < 2; ++k) \
;         acc[ai][bj][m][n] = __builtin_amdgcn_mfma_f32_16x16x32_bf16(Bt[n][k], At[m][k], acc[ai][bj][m][n], 0, 0, 0); __builtin_amdgcn_s_setprio(0); } while (0)
; #define PG8_WAIT_V(n) asm volatile("s_waitcnt vmcnt(" #n ")" ::: "memory")
; #define PG8_WAIT_L(n) asm volatile("s_waitcnt lgkmcnt(" #n ")" ::: "memory")
; #define PG8_BAR __builtin_amdgcn_s_barrier()
; #define PG8_SCHED __builtin_amdgcn_sched_barrier(0)
; template <class Epi>
; __device__ __forceinline__ void gemm_phase(LAS unsigned char* lds, const Gemm g, const int G, const int cidx, const int tid, const Epi& E) {
;     ...
;             PG8_WAIT_V(8); PG8_WAIT_L(0); PG8_BAR; PG8_MMA(1, 0, At, B0); PG8_MMA(1, 1, At, B1); PG8_BAR; PG8_SCHED;
;             PG8_LDB(B0, 1, 0); PG8_LDB(B1, 1, 1); PG8_SCHED; PG8_LDA(At, 1, 0); PG8_STAGE(PG8_SA(0, 1), a2 + hstepA, voffA);
;             PG8_WAIT_V(8); PG8_WAIT_L(0); PG8_BAR; PG8_MMA(0, 0, At, B0); PG8_MMA(0, 1, At, B1); PG8_BAR; PG8_SCHED;
	s_setprio 1
	s_waitcnt lgkmcnt(0)
	v_mfma_f32_16x16x32_bf16 v[60:63], v[142:145], v[188:191], v[60:63]
	v_mfma_f32_16x16x32_bf16 v[56:59], v[164:167], v[188:191], v[56:59]
	v_mfma_f32_16x16x32_bf16 v[44:47], v[142:145], v[214:217], v[44:47]
	v_mfma_f32_16x16x32_bf16 v[40:43], v[164:167], v[214:217], v[40:43]
	v_mfma_f32_16x16x32_bf16 v[28:31], v[142:145], v[222:225], v[28:31]
	v_mfma_f32_16x16x32_bf16 v[24:27], v[164:167], v[222:225], v[24:27]
	v_mfma_f32_16x16x32_bf16 v[12:15], v[142:145], v[230:233], v[12:15]
	v_mfma_f32_16x16x32_bf16 v[8:11], v[164:167], v[230:233], v[8:11]
	v_mfma_f32_16x16x32_bf16 v[60:63], v[146:149], v[210:213], v[60:63]
	v_mfma_f32_16x16x32_bf16 v[56:59], v[168:171], v[210:213], v[56:59]
	v_mfma_f32_16x16x32_bf16 v[44:47], v[146:149], v[218:221], v[44:47]
	v_mfma_f32_16x16x32_bf16 v[40:43], v[168:171], v[218:221], v[40:43]
	v_mfma_f32_16x16x32_bf16 v[28:31], v[146:149], v[226:229], v[28:31]
	v_mfma_f32_16x16x32_bf16 v[24:27], v[168:171], v[226:229], v[24:27]
	v_mfma_f32_16x16x32_bf16 v[12:15], v[146:149], v[234:237], v[12:15]
	v_mfma_f32_16x16x32_bf16 v[8:11], v[168:171], v[234:237], v[8:11]
	s_setprio 0
	s_setprio 1
	v_mfma_f32_16x16x32_bf16 v[52:55], v[172:175], v[188:191], v[52:55]
	v_mfma_f32_16x16x32_bf16 v[48:51], v[180:183], v[188:191], v[48:51]
	v_mfma_f32_16x16x32_bf16 v[36:39], v[172:175], v[214:217], v[36:39]
	v_mfma_f32_16x16x32_bf16 v[32:35], v[180:183], v[214:217], v[32:35]
	v_mfma_f32_16x16x32_bf16 v[20:23], v[172:175], v[222:225], v[20:23]
	v_mfma_f32_16x16x32_bf16 v[16:19], v[180:183], v[222:225], v[16:19]
	v_mfma_f32_16x16x32_bf16 v[4:7], v[172:175], v[230:233], v[4:7]
	v_mfma_f32_16x16x32_bf16 v[0:3], v[180:183], v[230:233], v[0:3]
	v_mfma_f32_16x16x32_bf16 v[52:55], v[176:179], v[210:213], v[52:55]
	v_mfma_f32_16x16x32_bf16 v[48:51], v[184:187], v[210:213], v[48:51]
	v_mfma_f32_16x16x32_bf16 v[36:39], v[176:179], v[218:221], v[36:39]
	v_mfma_f32_16x16x32_bf16 v[32:35], v[184:187], v[218:221], v[32:35]
	v_mfma_f32_16x16x32_bf16 v[20:23], v[176:179], v[226:229], v[20:23]
	v_mfma_f32_16x16x32_bf16 v[16:19], v[184:187], v[226:229], v[16:19]
	v_mfma_f32_16x16x32_bf16 v[4:7], v[176:179], v[234:237], v[4:7]
	v_mfma_f32_16x16x32_bf16 v[0:3], v[184:187], v[234:237], v[0:3]
	s_setprio 0
	s_barrier
	s_add_i32 s30, 0, 0x18000
	v_add_u32_e32 v163, s30, v140
	s_add_i32 s66, 0, 0x1c000
	ds_read_b128 v[142:145], v163
	ds_read_b128 v[146:149], v163 offset:1024
	ds_read_b128 v[164:167], v163 offset:2048
	ds_read_b128 v[168:171], v163 offset:3072
	v_add_u32_e32 v163, s66, v140
	ds_read_b128 v[172:175], v163
	ds_read_b128 v[176:179], v163 offset:1024
	ds_read_b128 v[180:183], v163 offset:2048
	ds_read_b128 v[184:187], v163 offset:3072
	s_add_u32 s56, s56, 0x40000
	s_addc_u32 s57, s57, 0
	s_mov_b32 m0, s31
	v_lshl_add_u64 v[238:239], s[56:57], 0, v[128:129]
	ds_read_b128 v[188:191], v141 offset:32768
	ds_read_b128 v[210:213], v141 offset:33792
	ds_read_b128 v[214:217], v141 offset:34816
	ds_read_b128 v[218:221], v141 offset:35840
	ds_read_b128 v[222:225], v141 offset:36864
	ds_read_b128 v[226:229], v141 offset:37888
	ds_read_b128 v[230:233], v141 offset:38912
	ds_read_b128 v[234:237], v141 offset:39936
	global_load_lds_dwordx4 v[238:239], off
	v_lshl_add_u64 v[238:239], s[56:57], 0, v[130:131]
	s_mov_b32 m0, s58
	s_nop 0
	global_load_lds_dwordx4 v[238:239], off
	s_waitcnt vmcnt(8)
	s_waitcnt lgkmcnt(0)
	s_barrier
	s_setprio 1
	s_waitcnt lgkmcnt(0)
	v_mfma_f32_16x16x32_bf16 v[124:127], v[142:145], v[188:191], v[124:127]
	v_mfma_f32_16x16x32_bf16 v[120:123], v[164:167], v[188:191], v[120:123]
	v_mfma_f32_16x16x32_bf16 v[108:111], v[142:145], v[214:217], v[108:111]
	v_mfma_f32_16x16x32_bf16 v[104:107], v[164:167], v[214:217], v[104:107]
	v_mfma_f32_16x16x32_bf16 v[92:95], v[142:145], v[222:225], v[92:95]
	v_mfma_f32_16x16x32_bf16 v[88:91], v[164:167], v[222:225], v[88:91]
	v_mfma_f32_16x16x32_bf16 v[76:79], v[142:145], v[230:233], v[76:79]
	v_mfma_f32_16x16x32_bf16 v[72:75], v[164:167], v[230:233], v[72:75]
	v_mfma_f32_16x16x32_bf16 v[124:127], v[146:149], v[210:213], v[124:127]
	v_mfma_f32_16x16x32_bf16 v[120:123], v[168:171], v[210:213], v[120:123]
	v_mfma_f32_16x16x32_bf16 v[108:111], v[146:149], v[218:221], v[108:111]
	v_mfma_f32_16x16x32_bf16 v[104:107], v[168:171], v[218:221], v[104:107]
	v_mfma_f32_16x16x32_bf16 v[92:95], v[146:149], v[226:229], v[92:95]
	v_mfma_f32_16x16x32_bf16 v[88:91], v[168:171], v[226:229], v[88:91]
	v_mfma_f32_16x16x32_bf16 v[76:79], v[146:149], v[234:237], v[76:79]
	v_mfma_f32_16x16x32_bf16 v[72:75], v[168:171], v[234:237], v[72:75]
	s_setprio 0
	s_setprio 1
	v_mfma_f32_16x16x32_bf16 v[116:119], v[172:175], v[188:191], v[116:119]
	v_mfma_f32_16x16x32_bf16 v[112:115], v[180:183], v[188:191], v[112:115]
	v_mfma_f32_16x16x32_bf16 v[100:103], v[172:175], v[214:217], v[100:103]
	v_mfma_f32_16x16x32_bf16 v[96:99], v[180:183], v[214:217], v[96:99]
	v_mfma_f32_16x16x32_bf16 v[84:87], v[172:175], v[222:225], v[84:87]
	v_mfma_f32_16x16x32_bf16 v[80:83], v[180:183], v[222:225], v[80:83]
	v_mfma_f32_16x16x32_bf16 v[68:71], v[172:175], v[230:233], v[68:71]
	v_mfma_f32_16x16x32_bf16 v[64:67], v[180:183], v[230:233], v[64:67]
	v_mfma_f32_16x16x32_bf16 v[116:119], v[176:179], v[210:213], v[116:119]
	v_mfma_f32_16x16x32_bf16 v[112:115], v[184:187], v[210:213], v[112:115]
	v_mfma_f32_16x16x32_bf16 v[100:103], v[176:179], v[218:221], v[100:103]
	v_mfma_f32_16x16x32_bf16 v[96:99], v[184:187], v[218:221], v[96:99]
	v_mfma_f32_16x16x32_bf16 v[84:87], v[176:179], v[226:229], v[84:87]
	v_mfma_f32_16x16x32_bf16 v[80:83], v[184:187], v[226:229], v[80:83]
	v_mfma_f32_16x16x32_bf16 v[68:71], v[176:179], v[234:237], v[68:71]
	v_mfma_f32_16x16x32_bf16 v[64:67], v[184:187], v[234:237], v[64:67]
	s_setprio 0
	s_barrier
; #define PG8_STAGE(bufoff, gbase, voff) do { _Pragma("unroll") for (int _i = 0; _i < 2; ++_i) \
;         __builtin_amdgcn_global_load_lds((const unsigned*)((const char*)(gbase) + (voff)[_i]), (LAS unsigned*)(lds + (bufoff) + ldsw + _i * 8192), 16, 0, 0); } while (0)
; #define PG8_LDA(dst, b, h) do { _Pragma("unroll") for (int m = 0; m < 4; ++m) _Pragma("unroll") for (int k = 0; k < 2; ++k) dst[m][k] = *(const LAS bf16x8*)(lds + PG8_SA(b, h) + aoff + m * 2048 + k * 1024); } while (0)
; #define PG8_MMA(ai, bj, At, Bt) do { __builtin_amdgcn_s_setprio(1); _Pragma("unroll") for (int m = 0; m < 4; ++m) _Pragma("unroll") for (int n = 0; n < 2; ++n) _Pragma("unroll") for (int k = 0; k < 2; ++k) \
;         acc[ai][bj][m][n] = __builtin_amdgcn_mfma_f32_16x16x32_bf16(Bt[n][k], At[m][k], acc[ai][bj][m][n], 0, 0, 0); __builtin_amdgcn_s_setprio(0); } while (0)
; #define PG8_WAIT_V(n) asm volatile("s_waitcnt vmcnt(" #n ")" ::: "memory")
; #define PG8_WAIT_L(n) asm volatile("s_waitcnt lgkmcnt(" #n ")" ::: "memory")
; #define PG8_BAR __builtin_amdgcn_s_barrier()
; #define PG8_SCHED __builtin_amdgcn_sched_barrier(0)
; template <class Epi>
; __device__ __forceinline__ void gemm_phase(LAS unsigned char* lds, const Gemm g, const int G, const int cidx, const int tid, const Epi& E) {
;     ...
;             PG8_LDA(At, 1, 1); PG8_STAGE(PG8_SB(1, 0), b3, voffB); PG8_STAGE(PG8_SB(1, 1), b3 + hstepB, voffB); PG8_STAGE(PG8_SA(1, 0), a3, voffA);
;             PG8_WAIT_V(8); PG8_WAIT_L(0); PG8_BAR; PG8_MMA(1, 0, At, B0); PG8_MMA(1, 1, At, B1); PG8_BAR; PG8_SCHED;
;         }
	s_add_i32 s30, s30, s25
	v_lshl_add_u64 v[150:151], v[150:151], 0, s[96:97]
	s_mov_b32 m0, s30
	ds_read_b128 v[188:191], v141 offset:49152
	ds_read_b128 v[210:213], v141 offset:50176
	ds_read_b128 v[214:217], v141 offset:51200
	ds_read_b128 v[218:221], v141 offset:52224
	ds_read_b128 v[222:225], v141 offset:53248
	ds_read_b128 v[226:229], v141 offset:54272
	ds_read_b128 v[230:233], v141 offset:55296
	ds_read_b128 v[234:237], v141 offset:56320
	global_load_lds_dwordx4 v[150:151], off
	s_add_i32 m0, s30, 0x2000
	s_add_u32 s54, s54, 0x40080
	v_lshl_add_u64 v[150:151], v[158:159], 0, s[96:97]
	s_addc_u32 s55, s55, 0
	s_add_i32 s30, s66, s25
	global_load_lds_dwordx4 v[150:151], off
	v_lshl_add_u64 v[150:151], s[54:55], 0, v[152:153]
	s_mov_b32 m0, s30
	s_nop 0
	global_load_lds_dwordx4 v[150:151], off
	v_lshl_add_u64 v[150:151], s[54:55], 0, v[132:133]
	s_add_i32 m0, s30, 0x2000
	s_nop 0
	global_load_lds_dwordx4 v[150:151], off
	v_lshl_add_u64 v[150:151], v[192:193], 0, s[96:97]
	s_mov_b32 m0, s61
	s_nop 0
	global_load_lds_dwordx4 v[150:151], off
	v_lshl_add_u64 v[150:151], v[208:209], 0, s[96:97]
	s_mov_b32 m0, s62
	s_nop 0
	global_load_lds_dwordx4 v[150:151], off
	s_waitcnt vmcnt(8)
	s_waitcnt lgkmcnt(0)
	s_barrier
	s_setprio 1
	s_waitcnt lgkmcnt(0)
	v_mfma_f32_16x16x32_bf16 v[60:63], v[142:145], v[188:191], v[60:63]
	v_mfma_f32_16x16x32_bf16 v[56:59], v[164:167], v[188:191], v[56:59]
	v_mfma_f32_16x16x32_bf16 v[44:47], v[142:145], v[214:217], v[44:47]
	v_mfma_f32_16x16x32_bf16 v[40:43], v[164:167], v[214:217], v[40:43]
	v_mfma_f32_16x16x32_bf16 v[28:31], v[142:145], v[222:225], v[28:31]
	v_mfma_f32_16x16x32_bf16 v[24:27], v[164:167], v[222:225], v[24:27]
	v_mfma_f32_16x16x32_bf16 v[12:15], v[142:145], v[230:233], v[12:15]
	v_mfma_f32_16x16x32_bf16 v[8:11], v[164:167], v[230:233], v[8:11]
	v_mfma_f32_16x16x32_bf16 v[60:63], v[146:149], v[210:213], v[60:63]
	v_mfma_f32_16x16x32_bf16 v[56:59], v[168:171], v[210:213], v[56:59]
	v_mfma_f32_16x16x32_bf16 v[44:47], v[146:149], v[218:221], v[44:47]
	v_mfma_f32_16x16x32_bf16 v[40:43], v[168:171], v[218:221], v[40:43]
	v_mfma_f32_16x16x32_bf16 v[28:31], v[146:149], v[226:229], v[28:31]
	v_mfma_f32_16x16x32_bf16 v[24:27], v[168:171], v[226:229], v[24:27]
	v_mfma_f32_16x16x32_bf16 v[12:15], v[146:149], v[234:237], v[12:15]
	v_mfma_f32_16x16x32_bf16 v[8:11], v[168:171], v[234:237], v[8:11]
	s_setprio 0
	s_setprio 1
	v_mfma_f32_16x16x32_bf16 v[52:55], v[172:175], v[188:191], v[52:55]
	v_mfma_f32_16x16x32_bf16 v[48:51], v[180:183], v[188:191], v[48:51]
	v_mfma_f32_16x16x32_bf16 v[36:39], v[172:175], v[214:217], v[36:39]
	v_mfma_f32_16x16x32_bf16 v[32:35], v[180:183], v[214:217], v[32:35]
	v_mfma_f32_16x16x32_bf16 v[20:23], v[172:175], v[222:225], v[20:23]
	v_mfma_f32_16x16x32_bf16 v[16:19], v[180:183], v[222:225], v[16:19]
	v_mfma_f32_16x16x32_bf16 v[4:7], v[172:175], v[230:233], v[4:7]
	v_mfma_f32_16x16x32_bf16 v[0:3], v[180:183], v[230:233], v[0:3]
	v_mfma_f32_16x16x32_bf16 v[52:55], v[176:179], v[210:213], v[52:55]
	v_mfma_f32_16x16x32_bf16 v[48:51], v[184:187], v[210:213], v[48:51]
	v_mfma_f32_16x16x32_bf16 v[36:39], v[176:179], v[218:221], v[36:39]
	v_mfma_f32_16x16x32_bf16 v[32:35], v[184:187], v[218:221], v[32:35]
	v_mfma_f32_16x16x32_bf16 v[20:23], v[176:179], v[226:229], v[20:23]
	v_mfma_f32_16x16x32_bf16 v[16:19], v[184:187], v[226:229], v[16:19]
	v_mfma_f32_16x16x32_bf16 v[4:7], v[176:179], v[234:237], v[4:7]
	v_mfma_f32_16x16x32_bf16 v[0:3], v[184:187], v[234:237], v[0:3]
	s_setprio 0
	s_add_i32 s94, s94, 2
	s_add_u32 s52, s52, 0x100
	s_addc_u32 s53, s53, 0
	s_add_u32 s65, s65, 0x100
	s_addc_u32 s92, s92, 0
	s_barrier
	s_cmp_gt_u32 s94, 13
	s_cbranch_scc0 .LBB0_102
	s_and_b64 vcc, exec, s[8:9]
	v_readlane_b32 s94, v255, 3
	v_readlane_b32 s92, v255, 5
	v_readlane_b32 s95, v255, 4
	s_cbranch_vccz .LBB0_105
	s_barrier

; #define PG8_STAGE(bufoff, gbase, voff) do { _Pragma("unroll") for (int _i = 0; _i < 2; ++_i) \
;         __builtin_amdgcn_global_load_lds((const unsigned*)((const char*)(gbase) + (voff)[_i]), (LAS unsigned*)(lds + (bufoff) + ldsw + _i * 8192), 16, 0, 0); } while (0)
; #define PG8_LDA(dst, b, h) do { _Pragma("unroll") for (int m = 0; m < 4; ++m) _Pragma("unroll") for (int k = 0; k < 2; ++k) dst[m][k] = *(const LAS bf16x8*)(lds + PG8_SA(b, h) + aoff + m * 2048 + k * 1024); } while (0)
; #define PG8_LDB(dst, b, h) do { _Pragma("unroll") for (int n = 0; n < 2; ++n) _Pragma("unroll") for (int k = 0; k < 2; ++k) dst[n][k] = *(const LAS bf16x8*)(lds + PG8_SB(b, h) + boff + n * 2048 + k * 1024); } while (0)
; #define PG8_MMA(ai, bj, At, Bt) do { __builtin_amdgcn_s_setprio(1); _Pragma("unroll") for (int m = 0; m < 4; ++m) _Pragma("unroll") for (int n = 0; n < 2; ++n) _Pragma("unroll") for (int k = 0; k < 2; ++k) \
;         acc[ai][bj][m][n] = __builtin_amdgcn_mfma_f32_16x16x32_bf16(Bt[n][k], At[m][k], acc[ai][bj][m][n], 0, 0, 0); __builtin_amdgcn_s_setprio(0); } while (0)
; #define PG8_WAIT_V(n) asm volatile("s_waitcnt vmcnt(" #n ")" ::: "memory")
; #define PG8_WAIT_L(n) asm volatile("s_waitcnt lgkmcnt(" #n ")" ::: "memory")
; #define PG8_BAR __builtin_amdgcn_s_barrier()
; #define PG8_SCHED __builtin_amdgcn_sched_barrier(0)
; template <class Epi>
; __device__ __forceinline__ void gemm_phase(LAS unsigned char* lds, const Gemm g, const int G, const int cidx, const int tid, const Epi& E) {
;     ...
;             PG8_LDB(B0, 0, 0); PG8_LDB(B1, 0, 1); PG8_SCHED; PG8_LDA(At, 0, 0); PG8_STAGE(PG8_SA(1, 1), a1 + hstepA, voffA);
;             PG8_WAIT_V(8); PG8_WAIT_L(0); PG8_BAR; PG8_MMA(0, 0, At, B0); PG8_MMA(0, 1, At, B1); PG8_BAR; PG8_SCHED;
;             PG8_LDA(At, 0, 1); PG8_STAGE(PG8_SB(0, 0), b2, voffB); PG8_STAGE(PG8_SB(0, 1), b2 + hstepB, voffB); PG8_STAGE(PG8_SA(0, 0), a2, voffA);
;             PG8_WAIT_V(8); PG8_WAIT_L(0); PG8_BAR; PG8_MMA(1, 0, At, B0); PG8_MMA(1, 1, At, B1); PG8_BAR; PG8_SCHED;
.LBB0_130:
	s_add_u32 s10, s60, 0xfffc0080
	s_addc_u32 s11, s61, -1
	s_add_i32 s66, 0, 0x10000
	s_cmp_eq_u32 s20, 12
	s_cselect_b32 s65, s34, s11
	s_cselect_b32 s64, s35, s10
	s_cselect_b32 s63, s53, vcc_hi
	s_cselect_b32 s62, s55, vcc_lo
	s_add_i32 s67, 0, 0x14000
	v_add_u32_e32 v124, s66, v214
	v_add_u32_e32 v152, s67, v214
	ds_read_b128 v[112:115], v124
	ds_read_b128 v[116:119], v124 offset:1024
	ds_read_b128 v[120:123], v124 offset:2048
	ds_read_b128 v[124:127], v124 offset:3072
	ds_read_b128 v[128:131], v152
	ds_read_b128 v[140:143], v152 offset:1024
	ds_read_b128 v[176:179], v152 offset:2048
	ds_read_b128 v[180:183], v152 offset:3072
	v_lshl_add_u64 v[158:159], s[60:61], 0, v[172:173]
	s_add_i32 m0, s29, 0xc000
	ds_read_b128 v[184:187], v215
	ds_read_b128 v[216:219], v215 offset:1024
	ds_read_b128 v[220:223], v215 offset:2048
	ds_read_b128 v[224:227], v215 offset:3072
	ds_read_b128 v[228:231], v215 offset:4096
	ds_read_b128 v[232:235], v215 offset:5120
	ds_read_b128 v[236:239], v215 offset:6144
	ds_read_b128 v[240:243], v215 offset:7168
	global_load_lds_dwordx4 v[158:159], off
	v_lshl_add_u64 v[158:159], s[60:61], 0, v[174:175]
	s_add_i32 m0, s29, 0xe000
	s_nop 0
	global_load_lds_dwordx4 v[158:159], off
	s_waitcnt vmcnt(8)
	s_waitcnt lgkmcnt(0)
	s_barrier
	s_setprio 1
	s_waitcnt lgkmcnt(0)
	v_mfma_f32_16x16x32_bf16 v[148:151], v[112:115], v[184:187], v[148:151]
	v_mfma_f32_16x16x32_bf16 v[144:147], v[120:123], v[184:187], v[144:147]
	v_mfma_f32_16x16x32_bf16 v[108:111], v[112:115], v[220:223], v[108:111]
	v_mfma_f32_16x16x32_bf16 v[104:107], v[120:123], v[220:223], v[104:107]
	v_mfma_f32_16x16x32_bf16 v[92:95], v[112:115], v[228:231], v[92:95]
	v_mfma_f32_16x16x32_bf16 v[88:91], v[120:123], v[228:231], v[88:91]
	v_mfma_f32_16x16x32_bf16 v[76:79], v[112:115], v[236:239], v[76:79]
	v_mfma_f32_16x16x32_bf16 v[72:75], v[120:123], v[236:239], v[72:75]
	v_mfma_f32_16x16x32_bf16 v[148:151], v[116:119], v[216:219], v[148:151]
	v_mfma_f32_16x16x32_bf16 v[144:147], v[124:127], v[216:219], v[144:147]
	v_mfma_f32_16x16x32_bf16 v[108:111], v[116:119], v[224:227], v[108:111]
	v_mfma_f32_16x16x32_bf16 v[104:107], v[124:127], v[224:227], v[104:107]
	v_mfma_f32_16x16x32_bf16 v[92:95], v[116:119], v[232:235], v[92:95]
	v_mfma_f32_16x16x32_bf16 v[88:91], v[124:127], v[232:235], v[88:91]
	v_mfma_f32_16x16x32_bf16 v[76:79], v[116:119], v[240:243], v[76:79]
	v_mfma_f32_16x16x32_bf16 v[72:75], v[124:127], v[240:243], v[72:75]
	s_setprio 0
	s_setprio 1
	v_mfma_f32_16x16x32_bf16 v[136:139], v[128:131], v[184:187], v[136:139]
	v_mfma_f32_16x16x32_bf16 v[132:135], v[176:179], v[184:187], v[132:135]
	v_mfma_f32_16x16x32_bf16 v[100:103], v[128:131], v[220:223], v[100:103]
	v_mfma_f32_16x16x32_bf16 v[96:99], v[176:179], v[220:223], v[96:99]
	v_mfma_f32_16x16x32_bf16 v[84:87], v[128:131], v[228:231], v[84:87]
	v_mfma_f32_16x16x32_bf16 v[80:83], v[176:179], v[228:231], v[80:83]
	v_mfma_f32_16x16x32_bf16 v[68:71], v[128:131], v[236:239], v[68:71]
	v_mfma_f32_16x16x32_bf16 v[64:67], v[176:179], v[236:239], v[64:67]
	v_mfma_f32_16x16x32_bf16 v[136:139], v[140:143], v[216:219], v[136:139]
	v_mfma_f32_16x16x32_bf16 v[132:135], v[180:183], v[216:219], v[132:135]
	v_mfma_f32_16x16x32_bf16 v[100:103], v[140:143], v[224:227], v[100:103]
	v_mfma_f32_16x16x32_bf16 v[96:99], v[180:183], v[224:227], v[96:99]
	v_mfma_f32_16x16x32_bf16 v[84:87], v[140:143], v[232:235], v[84:87]
	v_mfma_f32_16x16x32_bf16 v[80:83], v[180:183], v[232:235], v[80:83]
	v_mfma_f32_16x16x32_bf16 v[68:71], v[140:143], v[240:243], v[68:71]
	v_mfma_f32_16x16x32_bf16 v[64:67], v[180:183], v[240:243], v[64:67]
	s_setprio 0
	s_barrier
	s_add_i32 s10, s66, s25
	v_lshl_add_u64 v[158:159], s[62:63], 0, v[166:167]
	s_mov_b32 m0, s10
	ds_read_b128 v[184:187], v215 offset:16384
	ds_read_b128 v[216:219], v215 offset:17408
	ds_read_b128 v[220:223], v215 offset:18432
	ds_read_b128 v[224:227], v215 offset:19456
	ds_read_b128 v[228:231], v215 offset:20480
	ds_read_b128 v[232:235], v215 offset:21504
	ds_read_b128 v[236:239], v215 offset:22528
	ds_read_b128 v[240:243], v215 offset:23552
	global_load_lds_dwordx4 v[158:159], off
	s_add_i32 m0, s10, 0x2000
	s_add_u32 s10, s62, 0x40000
	v_lshl_add_u64 v[188:189], s[62:63], 0, v[170:171]
	s_addc_u32 s11, s63, 0
	s_add_i32 s66, s67, s25
	global_load_lds_dwordx4 v[188:189], off
	v_lshl_add_u64 v[244:245], s[10:11], 0, v[166:167]
	s_mov_b32 m0, s66
	v_lshl_add_u64 v[246:247], s[64:65], 0, v[168:169]
	global_load_lds_dwordx4 v[244:245], off
	v_lshl_add_u64 v[244:245], s[10:11], 0, v[170:171]
	s_add_i32 m0, s66, 0x2000
	s_nop 0
	global_load_lds_dwordx4 v[244:245], off
	v_lshl_add_u64 v[244:245], s[64:65], 0, v[164:165]
	s_mov_b32 m0, s29
	s_nop 0
	global_load_lds_dwordx4 v[244:245], off
	s_mov_b32 m0, s31
	s_nop 0
	global_load_lds_dwordx4 v[246:247], off
	s_waitcnt vmcnt(8)
	s_waitcnt lgkmcnt(0)
	s_barrier
; #define PG8_STAGE(bufoff, gbase, voff) do { _Pragma("unroll") for (int _i = 0; _i < 2; ++_i) \
;         __builtin_amdgcn_global_load_lds((const unsigned*)((const char*)(gbase) + (voff)[_i]), (LAS unsigned*)(lds + (bufoff) + ldsw + _i * 8192), 16, 0, 0); } while (0)
; #define PG8_LDA(dst, b, h) do { _Pragma("unroll") for (int m = 0; m < 4; ++m) _Pragma("unroll") for (int k = 0; k < 2; ++k) dst[m][k] = *(const LAS bf16x8*)(lds + PG8_SA(b, h) + aoff + m * 2048 + k * 1024); } while (0)
; #define PG8_LDB(dst, b, h) do { _Pragma("unroll") for (int n = 0; n < 2; ++n) _Pragma("unroll") for (int k = 0; k < 2; ++k) dst[n][k] = *(const LAS bf16x8*)(lds + PG8_SB(b, h) + boff + n * 2048 + k * 1024); } while (0)
; #define PG8_MMA(ai, bj, At, Bt) do { __builtin_amdgcn_s_setprio(1); _Pragma("unroll") for (int m = 0; m < 4; ++m) _Pragma("unroll") for (int n = 0; n < 2; ++n) _Pragma("unroll") for (int k = 0; k < 2; ++k) \
;         acc[ai][bj][m][n] = __builtin_amdgcn_mfma_f32_16x16x32_bf16(Bt[n][k], At[m][k], acc[ai][bj][m][n], 0, 0, 0); __builtin_amdgcn_s_setprio(0); } while (0)
; #define PG8_WAIT_V(n) asm volatile("s_waitcnt vmcnt(" #n ")" ::: "memory")
; #define PG8_WAIT_L(n) asm volatile("s_waitcnt lgkmcnt(" #n ")" ::: "memory")
; #define PG8_BAR __builtin_amdgcn_s_barrier()
; #define PG8_SCHED __builtin_amdgcn_sched_barrier(0)
; template <class Epi>
; __device__ __forceinline__ void gemm_phase(LAS unsigned char* lds, const Gemm g, const int G, const int cidx, const int tid, const Epi& E) {
;     ...
;             PG8_WAIT_V(8); PG8_WAIT_L(0); PG8_BAR; PG8_MMA(1, 0, At, B0); PG8_MMA(1, 1, At, B1); PG8_BAR; PG8_SCHED;
;             PG8_LDB(B0, 1, 0); PG8_LDB(B1, 1, 1); PG8_SCHED; PG8_LDA(At, 1, 0); PG8_STAGE(PG8_SA(0, 1), a2 + hstepA, voffA);
;             PG8_WAIT_V(8); PG8_WAIT_L(0); PG8_BAR; PG8_MMA(0, 0, At, B0); PG8_MMA(0, 1, At, B1); PG8_BAR; PG8_SCHED;
	s_setprio 1
	s_waitcnt lgkmcnt(0)
	v_mfma_f32_16x16x32_bf16 v[60:63], v[112:115], v[184:187], v[60:63]
	v_mfma_f32_16x16x32_bf16 v[56:59], v[120:123], v[184:187], v[56:59]
	v_mfma_f32_16x16x32_bf16 v[44:47], v[112:115], v[220:223], v[44:47]
	v_mfma_f32_16x16x32_bf16 v[40:43], v[120:123], v[220:223], v[40:43]
	v_mfma_f32_16x16x32_bf16 v[28:31], v[112:115], v[228:231], v[28:31]
	v_mfma_f32_16x16x32_bf16 v[24:27], v[120:123], v[228:231], v[24:27]
	v_mfma_f32_16x16x32_bf16 v[12:15], v[112:115], v[236:239], v[12:15]
	v_mfma_f32_16x16x32_bf16 v[8:11], v[120:123], v[236:239], v[8:11]
	v_mfma_f32_16x16x32_bf16 v[60:63], v[116:119], v[216:219], v[60:63]
	v_mfma_f32_16x16x32_bf16 v[56:59], v[124:127], v[216:219], v[56:59]
	v_mfma_f32_16x16x32_bf16 v[44:47], v[116:119], v[224:227], v[44:47]
	v_mfma_f32_16x16x32_bf16 v[40:43], v[124:127], v[224:227], v[40:43]
	v_mfma_f32_16x16x32_bf16 v[28:31], v[116:119], v[232:235], v[28:31]
	v_mfma_f32_16x16x32_bf16 v[24:27], v[124:127], v[232:235], v[24:27]
	v_mfma_f32_16x16x32_bf16 v[12:15], v[116:119], v[240:243], v[12:15]
	v_mfma_f32_16x16x32_bf16 v[8:11], v[124:127], v[240:243], v[8:11]
	s_setprio 0
	s_setprio 1
	v_mfma_f32_16x16x32_bf16 v[52:55], v[128:131], v[184:187], v[52:55]
	v_mfma_f32_16x16x32_bf16 v[48:51], v[176:179], v[184:187], v[48:51]
	v_mfma_f32_16x16x32_bf16 v[36:39], v[128:131], v[220:223], v[36:39]
	v_mfma_f32_16x16x32_bf16 v[32:35], v[176:179], v[220:223], v[32:35]
	v_mfma_f32_16x16x32_bf16 v[20:23], v[128:131], v[228:231], v[20:23]
	v_mfma_f32_16x16x32_bf16 v[16:19], v[176:179], v[228:231], v[16:19]
	v_mfma_f32_16x16x32_bf16 v[4:7], v[128:131], v[236:239], v[4:7]
	v_mfma_f32_16x16x32_bf16 v[0:3], v[176:179], v[236:239], v[0:3]
	v_mfma_f32_16x16x32_bf16 v[52:55], v[140:143], v[216:219], v[52:55]
	v_mfma_f32_16x16x32_bf16 v[48:51], v[180:183], v[216:219], v[48:51]
	v_mfma_f32_16x16x32_bf16 v[36:39], v[140:143], v[224:227], v[36:39]
	v_mfma_f32_16x16x32_bf16 v[32:35], v[180:183], v[224:227], v[32:35]
	v_mfma_f32_16x16x32_bf16 v[20:23], v[140:143], v[232:235], v[20:23]
	v_mfma_f32_16x16x32_bf16 v[16:19], v[180:183], v[232:235], v[16:19]
	v_mfma_f32_16x16x32_bf16 v[4:7], v[140:143], v[240:243], v[4:7]
	v_mfma_f32_16x16x32_bf16 v[0:3], v[180:183], v[240:243], v[0:3]
	s_setprio 0
	s_barrier
	s_add_i32 s66, 0, 0x18000
	s_add_i32 s67, 0, 0x1c000
	v_add_u32_e32 v124, s66, v214
	v_add_u32_e32 v152, s67, v214
	ds_read_b128 v[112:115], v124
	ds_read_b128 v[116:119], v124 offset:1024
	ds_read_b128 v[120:123], v124 offset:2048
	ds_read_b128 v[124:127], v124 offset:3072
	ds_read_b128 v[128:131], v152
	ds_read_b128 v[140:143], v152 offset:1024
	ds_read_b128 v[176:179], v152 offset:2048
	ds_read_b128 v[180:183], v152 offset:3072
	s_add_u32 s10, s64, 0x40000
	s_addc_u32 s11, s65, 0
	s_mov_b32 m0, s94
	v_lshl_add_u64 v[248:249], s[10:11], 0, v[164:165]
	ds_read_b128 v[184:187], v215 offset:32768
	ds_read_b128 v[216:219], v215 offset:33792
	ds_read_b128 v[220:223], v215 offset:34816
	ds_read_b128 v[224:227], v215 offset:35840
	ds_read_b128 v[228:231], v215 offset:36864
	ds_read_b128 v[232:235], v215 offset:37888
	ds_read_b128 v[236:239], v215 offset:38912
	ds_read_b128 v[240:243], v215 offset:39936
	global_load_lds_dwordx4 v[248:249], off
	v_lshl_add_u64 v[248:249], s[10:11], 0, v[168:169]
	s_mov_b32 m0, s95
	s_nop 0
	global_load_lds_dwordx4 v[248:249], off
	s_waitcnt vmcnt(8)
	s_waitcnt lgkmcnt(0)
	s_barrier
	s_setprio 1
	s_waitcnt lgkmcnt(0)
	v_mfma_f32_16x16x32_bf16 v[148:151], v[112:115], v[184:187], v[148:151]
	v_mfma_f32_16x16x32_bf16 v[144:147], v[120:123], v[184:187], v[144:147]
	v_mfma_f32_16x16x32_bf16 v[108:111], v[112:115], v[220:223], v[108:111]
	v_mfma_f32_16x16x32_bf16 v[104:107], v[120:123], v[220:223], v[104:107]
	v_mfma_f32_16x16x32_bf16 v[92:95], v[112:115], v[228:231], v[92:95]
	v_mfma_f32_16x16x32_bf16 v[88:91], v[120:123], v[228:231], v[88:91]
	v_mfma_f32_16x16x32_bf16 v[76:79], v[112:115], v[236:239], v[76:79]
	v_mfma_f32_16x16x32_bf16 v[72:75], v[120:123], v[236:239], v[72:75]
	v_mfma_f32_16x16x32_bf16 v[148:151], v[116:119], v[216:219], v[148:151]
	v_mfma_f32_16x16x32_bf16 v[144:147], v[124:127], v[216:219], v[144:147]
	v_mfma_f32_16x16x32_bf16 v[108:111], v[116:119], v[224:227], v[108:111]
	v_mfma_f32_16x16x32_bf16 v[104:107], v[124:127], v[224:227], v[104:107]
	v_mfma_f32_16x16x32_bf16 v[92:95], v[116:119], v[232:235], v[92:95]
	v_mfma_f32_16x16x32_bf16 v[88:91], v[124:127], v[232:235], v[88:91]
	v_mfma_f32_16x16x32_bf16 v[76:79], v[116:119], v[240:243], v[76:79]
	v_mfma_f32_16x16x32_bf16 v[72:75], v[124:127], v[240:243], v[72:75]
	s_setprio 0
	s_setprio 1
	v_mfma_f32_16x16x32_bf16 v[136:139], v[128:131], v[184:187], v[136:139]
	v_mfma_f32_16x16x32_bf16 v[132:135], v[176:179], v[184:187], v[132:135]
	v_mfma_f32_16x16x32_bf16 v[100:103], v[128:131], v[220:223], v[100:103]
	v_mfma_f32_16x16x32_bf16 v[96:99], v[176:179], v[220:223], v[96:99]
	v_mfma_f32_16x16x32_bf16 v[84:87], v[128:131], v[228:231], v[84:87]
	v_mfma_f32_16x16x32_bf16 v[80:83], v[176:179], v[228:231], v[80:83]
	v_mfma_f32_16x16x32_bf16 v[68:71], v[128:131], v[236:239], v[68:71]
	v_mfma_f32_16x16x32_bf16 v[64:67], v[176:179], v[236:239], v[64:67]
	v_mfma_f32_16x16x32_bf16 v[136:139], v[140:143], v[216:219], v[136:139]
	v_mfma_f32_16x16x32_bf16 v[132:135], v[180:183], v[216:219], v[132:135]
	v_mfma_f32_16x16x32_bf16 v[100:103], v[140:143], v[224:227], v[100:103]
	v_mfma_f32_16x16x32_bf16 v[96:99], v[180:183], v[224:227], v[96:99]
	v_mfma_f32_16x16x32_bf16 v[84:87], v[140:143], v[232:235], v[84:87]
	v_mfma_f32_16x16x32_bf16 v[80:83], v[180:183], v[232:235], v[80:83]
	v_mfma_f32_16x16x32_bf16 v[68:71], v[140:143], v[240:243], v[68:71]
	v_mfma_f32_16x16x32_bf16 v[64:67], v[180:183], v[240:243], v[64:67]
	s_setprio 0
	s_barrier
; #define PG8_STAGE(bufoff, gbase, voff) do { _Pragma("unroll") for (int _i = 0; _i < 2; ++_i) \
;         __builtin_amdgcn_global_load_lds((const unsigned*)((const char*)(gbase) + (voff)[_i]), (LAS unsigned*)(lds + (bufoff) + ldsw + _i * 8192), 16, 0, 0); } while (0)
; #define PG8_LDA(dst, b, h) do { _Pragma("unroll") for (int m = 0; m < 4; ++m) _Pragma("unroll") for (int k = 0; k < 2; ++k) dst[m][k] = *(const LAS bf16x8*)(lds + PG8_SA(b, h) + aoff + m * 2048 + k * 1024); } while (0)
; #define PG8_MMA(ai, bj, At, Bt) do { __builtin_amdgcn_s_setprio(1); _Pragma("unroll") for (int m = 0; m < 4; ++m) _Pragma("unroll") for (int n = 0; n < 2; ++n) _Pragma("unroll") for (int k = 0; k < 2; ++k) \
;         acc[ai][bj][m][n] = __builtin_amdgcn_mfma_f32_16x16x32_bf16(Bt[n][k], At[m][k], acc[ai][bj][m][n], 0, 0, 0); __builtin_amdgcn_s_setprio(0); } while (0)
; #define PG8_WAIT_V(n) asm volatile("s_waitcnt vmcnt(" #n ")" ::: "memory")
; #define PG8_WAIT_L(n) asm volatile("s_waitcnt lgkmcnt(" #n ")" ::: "memory")
; #define PG8_BAR __builtin_amdgcn_s_barrier()
; #define PG8_SCHED __builtin_amdgcn_sched_barrier(0)
; template <class Epi>
; __device__ __forceinline__ void gemm_phase(LAS unsigned char* lds, const Gemm g, const int G, const int cidx, const int tid, const Epi& E) {
;     ...
;             PG8_LDA(At, 1, 1); PG8_STAGE(PG8_SB(1, 0), b3, voffB); PG8_STAGE(PG8_SB(1, 1), b3 + hstepB, voffB); PG8_STAGE(PG8_SA(1, 0), a3, voffA);
;             PG8_WAIT_V(8); PG8_WAIT_L(0); PG8_BAR; PG8_MMA(1, 0, At, B0); PG8_MMA(1, 1, At, B1); PG8_BAR; PG8_SCHED;
;         }
	s_add_i32 s10, s66, s25
	v_lshl_add_u64 v[158:159], v[158:159], 0, s[96:97]
	s_mov_b32 m0, s10
	ds_read_b128 v[184:187], v215 offset:49152
	ds_read_b128 v[216:219], v215 offset:50176
	ds_read_b128 v[220:223], v215 offset:51200
	ds_read_b128 v[224:227], v215 offset:52224
	ds_read_b128 v[228:231], v215 offset:53248
	ds_read_b128 v[232:235], v215 offset:54272
	ds_read_b128 v[236:239], v215 offset:55296
	ds_read_b128 v[240:243], v215 offset:56320
	global_load_lds_dwordx4 v[158:159], off
	s_add_i32 m0, s10, 0x2000
	s_add_u32 s10, s62, 0x40080
	v_lshl_add_u64 v[158:159], v[188:189], 0, s[96:97]
	s_addc_u32 s11, s63, 0
	s_add_i32 s62, s67, s25
	global_load_lds_dwordx4 v[158:159], off
	v_lshl_add_u64 v[158:159], s[10:11], 0, v[166:167]
	s_mov_b32 m0, s62
	s_nop 0
	global_load_lds_dwordx4 v[158:159], off
	v_lshl_add_u64 v[158:159], s[10:11], 0, v[170:171]
	s_add_i32 m0, s62, 0x2000
	s_nop 0
	global_load_lds_dwordx4 v[158:159], off
	v_lshl_add_u64 v[158:159], v[244:245], 0, s[96:97]
	s_mov_b32 m0, s12
	s_nop 0
	global_load_lds_dwordx4 v[158:159], off
	v_lshl_add_u64 v[158:159], v[246:247], 0, s[96:97]
	s_mov_b32 m0, s13
	s_nop 0
	global_load_lds_dwordx4 v[158:159], off
	s_waitcnt vmcnt(8)
	s_waitcnt lgkmcnt(0)
	s_barrier
	s_setprio 1
	s_waitcnt lgkmcnt(0)
	v_mfma_f32_16x16x32_bf16 v[60:63], v[112:115], v[184:187], v[60:63]
	v_mfma_f32_16x16x32_bf16 v[56:59], v[120:123], v[184:187], v[56:59]
	v_mfma_f32_16x16x32_bf16 v[44:47], v[112:115], v[220:223], v[44:47]
	v_mfma_f32_16x16x32_bf16 v[40:43], v[120:123], v[220:223], v[40:43]
	v_mfma_f32_16x16x32_bf16 v[28:31], v[112:115], v[228:231], v[28:31]
	v_mfma_f32_16x16x32_bf16 v[24:27], v[120:123], v[228:231], v[24:27]
	v_mfma_f32_16x16x32_bf16 v[12:15], v[112:115], v[236:239], v[12:15]
	v_mfma_f32_16x16x32_bf16 v[8:11], v[120:123], v[236:239], v[8:11]
	v_mfma_f32_16x16x32_bf16 v[60:63], v[116:119], v[216:219], v[60:63]
	v_mfma_f32_16x16x32_bf16 v[56:59], v[124:127], v[216:219], v[56:59]
	v_mfma_f32_16x16x32_bf16 v[44:47], v[116:119], v[224:227], v[44:47]
	v_mfma_f32_16x16x32_bf16 v[40:43], v[124:127], v[224:227], v[40:43]
	v_mfma_f32_16x16x32_bf16 v[28:31], v[116:119], v[232:235], v[28:31]
	v_mfma_f32_16x16x32_bf16 v[24:27], v[124:127], v[232:235], v[24:27]
	v_mfma_f32_16x16x32_bf16 v[12:15], v[116:119], v[240:243], v[12:15]
	v_mfma_f32_16x16x32_bf16 v[8:11], v[124:127], v[240:243], v[8:11]
	s_setprio 0
	s_setprio 1
	v_mfma_f32_16x16x32_bf16 v[52:55], v[128:131], v[184:187], v[52:55]
	v_mfma_f32_16x16x32_bf16 v[48:51], v[176:179], v[184:187], v[48:51]
	v_mfma_f32_16x16x32_bf16 v[36:39], v[128:131], v[220:223], v[36:39]
	v_mfma_f32_16x16x32_bf16 v[32:35], v[176:179], v[220:223], v[32:35]
	v_mfma_f32_16x16x32_bf16 v[20:23], v[128:131], v[228:231], v[20:23]
	v_mfma_f32_16x16x32_bf16 v[16:19], v[176:179], v[228:231], v[16:19]
	v_mfma_f32_16x16x32_bf16 v[4:7], v[128:131], v[236:239], v[4:7]
	v_mfma_f32_16x16x32_bf16 v[0:3], v[176:179], v[236:239], v[0:3]
	v_mfma_f32_16x16x32_bf16 v[52:55], v[140:143], v[216:219], v[52:55]
	v_mfma_f32_16x16x32_bf16 v[48:51], v[180:183], v[216:219], v[48:51]
	v_mfma_f32_16x16x32_bf16 v[36:39], v[140:143], v[224:227], v[36:39]
	v_mfma_f32_16x16x32_bf16 v[32:35], v[180:183], v[224:227], v[32:35]
	v_mfma_f32_16x16x32_bf16 v[20:23], v[140:143], v[232:235], v[20:23]
	v_mfma_f32_16x16x32_bf16 v[16:19], v[180:183], v[232:235], v[16:19]
	v_mfma_f32_16x16x32_bf16 v[4:7], v[140:143], v[240:243], v[4:7]
	v_mfma_f32_16x16x32_bf16 v[0:3], v[180:183], v[240:243], v[0:3]
	s_setprio 0
	s_add_i32 s20, s20, 2
	s_add_u32 s60, s60, 0x100
	s_addc_u32 s61, s61, 0
	s_add_u32 vcc_lo, vcc_lo, 0x100
	s_addc_u32 vcc_hi, vcc_hi, 0
	s_barrier
	s_cmp_gt_u32 s20, 13
	s_cbranch_scc0 .LBB0_130
	s_and_b64 vcc, exec, s[16:17]
	s_cbranch_vccz .LBB0_133
	s_barrier

; #define PG8_STAGE(bufoff, gbase, voff) do { _Pragma("unroll") for (int _i = 0; _i < 2; ++_i) \
;         __builtin_amdgcn_global_load_lds((const unsigned*)((const char*)(gbase) + (voff)[_i]), (LAS unsigned*)(lds + (bufoff) + ldsw + _i * 8192), 16, 0, 0); } while (0)
; #define PG8_LDA(dst, b, h) do { _Pragma("unroll") for (int m = 0; m < 4; ++m) _Pragma("unroll") for (int k = 0; k < 2; ++k) dst[m][k] = *(const LAS bf16x8*)(lds + PG8_SA(b, h) + aoff + m * 2048 + k * 1024); } while (0)
; #define PG8_LDB(dst, b, h) do { _Pragma("unroll") for (int n = 0; n < 2; ++n) _Pragma("unroll") for (int k = 0; k < 2; ++k) dst[n][k] = *(const LAS bf16x8*)(lds + PG8_SB(b, h) + boff + n * 2048 + k * 1024); } while (0)
; #define PG8_MMA(ai, bj, At, Bt) do { __builtin_amdgcn_s_setprio(1); _Pragma("unroll") for (int m = 0; m < 4; ++m) _Pragma("unroll") for (int n = 0; n < 2; ++n) _Pragma("unroll") for (int k = 0; k < 2; ++k) \
;         acc[ai][bj][m][n] = __builtin_amdgcn_mfma_f32_16x16x32_bf16(Bt[n][k], At[m][k], acc[ai][bj][m][n], 0, 0, 0); __builtin_amdgcn_s_setprio(0); } while (0)
; #define PG8_WAIT_V(n) asm volatile("s_waitcnt vmcnt(" #n ")" ::: "memory")
; #define PG8_WAIT_L(n) asm volatile("s_waitcnt lgkmcnt(" #n ")" ::: "memory")
; #define PG8_BAR __builtin_amdgcn_s_barrier()
; #define PG8_SCHED __builtin_amdgcn_sched_barrier(0)
; template <class Epi>
; __device__ __forceinline__ void gemm_phase(LAS unsigned char* lds, const Gemm g, const int G, const int cidx, const int tid, const Epi& E) {
;     ...
;             PG8_LDB(B0, 0, 0); PG8_LDB(B1, 0, 1); PG8_SCHED; PG8_LDA(At, 0, 0); PG8_STAGE(PG8_SA(1, 1), a1 + hstepA, voffA);
;             PG8_WAIT_V(8); PG8_WAIT_L(0); PG8_BAR; PG8_MMA(0, 0, At, B0); PG8_MMA(0, 1, At, B1); PG8_BAR; PG8_SCHED;
;             PG8_LDA(At, 0, 1); PG8_STAGE(PG8_SB(0, 0), b2, voffB); PG8_STAGE(PG8_SB(0, 1), b2 + hstepB, voffB); PG8_STAGE(PG8_SA(0, 0), a2, voffA);
;             PG8_WAIT_V(8); PG8_WAIT_L(0); PG8_BAR; PG8_MMA(1, 0, At, B0); PG8_MMA(1, 1, At, B1); PG8_BAR; PG8_SCHED;
.LBB0_161:
	s_add_u32 s10, s58, 0xfffc0080
	s_addc_u32 s60, s59, -1
	s_add_i32 s66, 0, 0x10000
	s_cmp_eq_u32 s20, 12
	s_cselect_b32 s63, s34, s60
	s_cselect_b32 s62, s35, s10
	s_cselect_b32 s61, s19, s95
	s_cselect_b32 s60, s53, s94
	s_add_i32 s10, 0, 0x14000
	v_add_u32_e32 v124, s66, v214
	v_add_u32_e32 v152, s10, v214
	ds_read_b128 v[112:115], v124
	ds_read_b128 v[116:119], v124 offset:1024
	ds_read_b128 v[120:123], v124 offset:2048
	ds_read_b128 v[124:127], v124 offset:3072
	ds_read_b128 v[128:131], v152
	ds_read_b128 v[140:143], v152 offset:1024
	ds_read_b128 v[176:179], v152 offset:2048
	ds_read_b128 v[180:183], v152 offset:3072
	v_lshl_add_u64 v[158:159], s[58:59], 0, v[172:173]
	s_add_i32 m0, s24, 0xc000
	ds_read_b128 v[184:187], v215
	ds_read_b128 v[216:219], v215 offset:1024
	ds_read_b128 v[220:223], v215 offset:2048
	ds_read_b128 v[224:227], v215 offset:3072
	ds_read_b128 v[228:231], v215 offset:4096
	ds_read_b128 v[232:235], v215 offset:5120
	ds_read_b128 v[236:239], v215 offset:6144
	ds_read_b128 v[240:243], v215 offset:7168
	global_load_lds_dwordx4 v[158:159], off
	v_lshl_add_u64 v[158:159], s[58:59], 0, v[174:175]
	s_add_i32 m0, s24, 0xe000
	s_nop 0
	global_load_lds_dwordx4 v[158:159], off
	s_waitcnt vmcnt(8)
	s_waitcnt lgkmcnt(0)
	s_barrier
	s_setprio 1
	s_waitcnt lgkmcnt(0)
	v_mfma_f32_16x16x32_bf16 v[148:151], v[112:115], v[184:187], v[148:151]
	v_mfma_f32_16x16x32_bf16 v[144:147], v[120:123], v[184:187], v[144:147]
	v_mfma_f32_16x16x32_bf16 v[108:111], v[112:115], v[220:223], v[108:111]
	v_mfma_f32_16x16x32_bf16 v[104:107], v[120:123], v[220:223], v[104:107]
	v_mfma_f32_16x16x32_bf16 v[92:95], v[112:115], v[228:231], v[92:95]
	v_mfma_f32_16x16x32_bf16 v[88:91], v[120:123], v[228:231], v[88:91]
	v_mfma_f32_16x16x32_bf16 v[76:79], v[112:115], v[236:239], v[76:79]
	v_mfma_f32_16x16x32_bf16 v[72:75], v[120:123], v[236:239], v[72:75]
	v_mfma_f32_16x16x32_bf16 v[148:151], v[116:119], v[216:219], v[148:151]
	v_mfma_f32_16x16x32_bf16 v[144:147], v[124:127], v[216:219], v[144:147]
	v_mfma_f32_16x16x32_bf16 v[108:111], v[116:119], v[224:227], v[108:111]
	v_mfma_f32_16x16x32_bf16 v[104:107], v[124:127], v[224:227], v[104:107]
	v_mfma_f32_16x16x32_bf16 v[92:95], v[116:119], v[232:235], v[92:95]
	v_mfma_f32_16x16x32_bf16 v[88:91], v[124:127], v[232:235], v[88:91]
	v_mfma_f32_16x16x32_bf16 v[76:79], v[116:119], v[240:243], v[76:79]
	v_mfma_f32_16x16x32_bf16 v[72:75], v[124:127], v[240:243], v[72:75]
	s_setprio 0
	s_setprio 1
	v_mfma_f32_16x16x32_bf16 v[136:139], v[128:131], v[184:187], v[136:139]
	v_mfma_f32_16x16x32_bf16 v[132:135], v[176:179], v[184:187], v[132:135]
	v_mfma_f32_16x16x32_bf16 v[100:103], v[128:131], v[220:223], v[100:103]
	v_mfma_f32_16x16x32_bf16 v[96:99], v[176:179], v[220:223], v[96:99]
	v_mfma_f32_16x16x32_bf16 v[84:87], v[128:131], v[228:231], v[84:87]
	v_mfma_f32_16x16x32_bf16 v[80:83], v[176:179], v[228:231], v[80:83]
	v_mfma_f32_16x16x32_bf16 v[68:71], v[128:131], v[236:239], v[68:71]
	v_mfma_f32_16x16x32_bf16 v[64:67], v[176:179], v[236:239], v[64:67]
	v_mfma_f32_16x16x32_bf16 v[136:139], v[140:143], v[216:219], v[136:139]
	v_mfma_f32_16x16x32_bf16 v[132:135], v[180:183], v[216:219], v[132:135]
	v_mfma_f32_16x16x32_bf16 v[100:103], v[140:143], v[224:227], v[100:103]
	v_mfma_f32_16x16x32_bf16 v[96:99], v[180:183], v[224:227], v[96:99]
	v_mfma_f32_16x16x32_bf16 v[84:87], v[140:143], v[232:235], v[84:87]
	v_mfma_f32_16x16x32_bf16 v[80:83], v[180:183], v[232:235], v[80:83]
	v_mfma_f32_16x16x32_bf16 v[68:71], v[140:143], v[240:243], v[68:71]
	v_mfma_f32_16x16x32_bf16 v[64:67], v[180:183], v[240:243], v[64:67]
	s_setprio 0
	s_barrier
	s_add_i32 s66, s66, s11
	v_lshl_add_u64 v[158:159], s[60:61], 0, v[166:167]
	s_mov_b32 m0, s66
	ds_read_b128 v[184:187], v215 offset:16384
	ds_read_b128 v[216:219], v215 offset:17408
	ds_read_b128 v[220:223], v215 offset:18432
	ds_read_b128 v[224:227], v215 offset:19456
	ds_read_b128 v[228:231], v215 offset:20480
	ds_read_b128 v[232:235], v215 offset:21504
	ds_read_b128 v[236:239], v215 offset:22528
	ds_read_b128 v[240:243], v215 offset:23552
	global_load_lds_dwordx4 v[158:159], off
	s_add_i32 m0, s66, 0x2000
	s_add_u32 vcc_lo, s60, 0x40000
	v_lshl_add_u64 v[188:189], s[60:61], 0, v[170:171]
	s_addc_u32 vcc_hi, s61, 0
	s_add_i32 s10, s10, s11
	global_load_lds_dwordx4 v[188:189], off
	v_lshl_add_u64 v[244:245], vcc, 0, v[166:167]
	s_mov_b32 m0, s10
	v_lshl_add_u64 v[246:247], s[62:63], 0, v[168:169]
	global_load_lds_dwordx4 v[244:245], off
	v_lshl_add_u64 v[244:245], vcc, 0, v[170:171]
	s_add_i32 m0, s10, 0x2000
	s_nop 0
	global_load_lds_dwordx4 v[244:245], off
	v_lshl_add_u64 v[244:245], s[62:63], 0, v[164:165]
	s_mov_b32 m0, s24
	s_nop 0
	global_load_lds_dwordx4 v[244:245], off
	s_mov_b32 m0, s25
	s_nop 0
	global_load_lds_dwordx4 v[246:247], off
	s_waitcnt vmcnt(8)
	s_waitcnt lgkmcnt(0)
	s_barrier
; #define PG8_STAGE(bufoff, gbase, voff) do { _Pragma("unroll") for (int _i = 0; _i < 2; ++_i) \
;         __builtin_amdgcn_global_load_lds((const unsigned*)((const char*)(gbase) + (voff)[_i]), (LAS unsigned*)(lds + (bufoff) + ldsw + _i * 8192), 16, 0, 0); } while (0)
; #define PG8_LDA(dst, b, h) do { _Pragma("unroll") for (int m = 0; m < 4; ++m) _Pragma("unroll") for (int k = 0; k < 2; ++k) dst[m][k] = *(const LAS bf16x8*)(lds + PG8_SA(b, h) + aoff + m * 2048 + k * 1024); } while (0)
; #define PG8_LDB(dst, b, h) do { _Pragma("unroll") for (int n = 0; n < 2; ++n) _Pragma("unroll") for (int k = 0; k < 2; ++k) dst[n][k] = *(const LAS bf16x8*)(lds + PG8_SB(b, h) + boff + n * 2048 + k * 1024); } while (0)
; #define PG8_MMA(ai, bj, At, Bt) do { __builtin_amdgcn_s_setprio(1); _Pragma("unroll") for (int m = 0; m < 4; ++m) _Pragma("unroll") for (int n = 0; n < 2; ++n) _Pragma("unroll") for (int k = 0; k < 2; ++k) \
;         acc[ai][bj][m][n] = __builtin_amdgcn_mfma_f32_16x16x32_bf16(Bt[n][k], At[m][k], acc[ai][bj][m][n], 0, 0, 0); __builtin_amdgcn_s_setprio(0); } while (0)
; #define PG8_WAIT_V(n) asm volatile("s_waitcnt vmcnt(" #n ")" ::: "memory")
; #define PG8_WAIT_L(n) asm volatile("s_waitcnt lgkmcnt(" #n ")" ::: "memory")
; #define PG8_BAR __builtin_amdgcn_s_barrier()
; #define PG8_SCHED __builtin_amdgcn_sched_barrier(0)
; template <class Epi>
; __device__ __forceinline__ void gemm_phase(LAS unsigned char* lds, const Gemm g, const int G, const int cidx, const int tid, const Epi& E) {
;     ...
;             PG8_WAIT_V(8); PG8_WAIT_L(0); PG8_BAR; PG8_MMA(1, 0, At, B0); PG8_MMA(1, 1, At, B1); PG8_BAR; PG8_SCHED;
;             PG8_LDB(B0, 1, 0); PG8_LDB(B1, 1, 1); PG8_SCHED; PG8_LDA(At, 1, 0); PG8_STAGE(PG8_SA(0, 1), a2 + hstepA, voffA);
;             PG8_WAIT_V(8); PG8_WAIT_L(0); PG8_BAR; PG8_MMA(0, 0, At, B0); PG8_MMA(0, 1, At, B1); PG8_BAR; PG8_SCHED;
	s_setprio 1
	s_waitcnt lgkmcnt(0)
	v_mfma_f32_16x16x32_bf16 v[60:63], v[112:115], v[184:187], v[60:63]
	v_mfma_f32_16x16x32_bf16 v[56:59], v[120:123], v[184:187], v[56:59]
	v_mfma_f32_16x16x32_bf16 v[44:47], v[112:115], v[220:223], v[44:47]
	v_mfma_f32_16x16x32_bf16 v[40:43], v[120:123], v[220:223], v[40:43]
	v_mfma_f32_16x16x32_bf16 v[28:31], v[112:115], v[228:231], v[28:31]
	v_mfma_f32_16x16x32_bf16 v[24:27], v[120:123], v[228:231], v[24:27]
	v_mfma_f32_16x16x32_bf16 v[12:15], v[112:115], v[236:239], v[12:15]
	v_mfma_f32_16x16x32_bf16 v[8:11], v[120:123], v[236:239], v[8:11]
	v_mfma_f32_16x16x32_bf16 v[60:63], v[116:119], v[216:219], v[60:63]
	v_mfma_f32_16x16x32_bf16 v[56:59], v[124:127], v[216:219], v[56:59]
	v_mfma_f32_16x16x32_bf16 v[44:47], v[116:119], v[224:227], v[44:47]
	v_mfma_f32_16x16x32_bf16 v[40:43], v[124:127], v[224:227], v[40:43]
	v_mfma_f32_16x16x32_bf16 v[28:31], v[116:119], v[232:235], v[28:31]
	v_mfma_f32_16x16x32_bf16 v[24:27], v[124:127], v[232:235], v[24:27]
	v_mfma_f32_16x16x32_bf16 v[12:15], v[116:119], v[240:243], v[12:15]
	v_mfma_f32_16x16x32_bf16 v[8:11], v[124:127], v[240:243], v[8:11]
	s_setprio 0
	s_setprio 1
	v_mfma_f32_16x16x32_bf16 v[52:55], v[128:131], v[184:187], v[52:55]
	v_mfma_f32_16x16x32_bf16 v[48:51], v[176:179], v[184:187], v[48:51]
	v_mfma_f32_16x16x32_bf16 v[36:39], v[128:131], v[220:223], v[36:39]
	v_mfma_f32_16x16x32_bf16 v[32:35], v[176:179], v[220:223], v[32:35]
	v_mfma_f32_16x16x32_bf16 v[20:23], v[128:131], v[228:231], v[20:23]
	v_mfma_f32_16x16x32_bf16 v[16:19], v[176:179], v[228:231], v[16:19]
	v_mfma_f32_16x16x32_bf16 v[4:7], v[128:131], v[236:239], v[4:7]
	v_mfma_f32_16x16x32_bf16 v[0:3], v[176:179], v[236:239], v[0:3]
	v_mfma_f32_16x16x32_bf16 v[52:55], v[140:143], v[216:219], v[52:55]
	v_mfma_f32_16x16x32_bf16 v[48:51], v[180:183], v[216:219], v[48:51]
	v_mfma_f32_16x16x32_bf16 v[36:39], v[140:143], v[224:227], v[36:39]
	v_mfma_f32_16x16x32_bf16 v[32:35], v[180:183], v[224:227], v[32:35]
	v_mfma_f32_16x16x32_bf16 v[20:23], v[140:143], v[232:235], v[20:23]
	v_mfma_f32_16x16x32_bf16 v[16:19], v[180:183], v[232:235], v[16:19]
	v_mfma_f32_16x16x32_bf16 v[4:7], v[140:143], v[240:243], v[4:7]
	v_mfma_f32_16x16x32_bf16 v[0:3], v[180:183], v[240:243], v[0:3]
	s_setprio 0
	s_barrier
	s_add_i32 s10, 0, 0x18000
	s_add_i32 s66, 0, 0x1c000
	v_add_u32_e32 v124, s10, v214
	v_add_u32_e32 v152, s66, v214
	ds_read_b128 v[112:115], v124
	ds_read_b128 v[116:119], v124 offset:1024
	ds_read_b128 v[120:123], v124 offset:2048
	ds_read_b128 v[124:127], v124 offset:3072
	ds_read_b128 v[128:131], v152
	ds_read_b128 v[140:143], v152 offset:1024
	ds_read_b128 v[176:179], v152 offset:2048
	ds_read_b128 v[180:183], v152 offset:3072
	s_add_u32 s62, s62, 0x40000
	s_addc_u32 s63, s63, 0
	s_mov_b32 m0, s29
	v_lshl_add_u64 v[248:249], s[62:63], 0, v[164:165]
	ds_read_b128 v[184:187], v215 offset:32768
	ds_read_b128 v[216:219], v215 offset:33792
	ds_read_b128 v[220:223], v215 offset:34816
	ds_read_b128 v[224:227], v215 offset:35840
	ds_read_b128 v[228:231], v215 offset:36864
	ds_read_b128 v[232:235], v215 offset:37888
	ds_read_b128 v[236:239], v215 offset:38912
	ds_read_b128 v[240:243], v215 offset:39936
	global_load_lds_dwordx4 v[248:249], off
	v_lshl_add_u64 v[248:249], s[62:63], 0, v[168:169]
	s_mov_b32 m0, s31
	s_nop 0
	global_load_lds_dwordx4 v[248:249], off
	s_waitcnt vmcnt(8)
	s_waitcnt lgkmcnt(0)
	s_barrier
	s_setprio 1
	s_waitcnt lgkmcnt(0)
	v_mfma_f32_16x16x32_bf16 v[148:151], v[112:115], v[184:187], v[148:151]
	v_mfma_f32_16x16x32_bf16 v[144:147], v[120:123], v[184:187], v[144:147]
	v_mfma_f32_16x16x32_bf16 v[108:111], v[112:115], v[220:223], v[108:111]
	v_mfma_f32_16x16x32_bf16 v[104:107], v[120:123], v[220:223], v[104:107]
	v_mfma_f32_16x16x32_bf16 v[92:95], v[112:115], v[228:231], v[92:95]
	v_mfma_f32_16x16x32_bf16 v[88:91], v[120:123], v[228:231], v[88:91]
	v_mfma_f32_16x16x32_bf16 v[76:79], v[112:115], v[236:239], v[76:79]
	v_mfma_f32_16x16x32_bf16 v[72:75], v[120:123], v[236:239], v[72:75]
	v_mfma_f32_16x16x32_bf16 v[148:151], v[116:119], v[216:219], v[148:151]
	v_mfma_f32_16x16x32_bf16 v[144:147], v[124:127], v[216:219], v[144:147]
	v_mfma_f32_16x16x32_bf16 v[108:111], v[116:119], v[224:227], v[108:111]
	v_mfma_f32_16x16x32_bf16 v[104:107], v[124:127], v[224:227], v[104:107]
	v_mfma_f32_16x16x32_bf16 v[92:95], v[116:119], v[232:235], v[92:95]
	v_mfma_f32_16x16x32_bf16 v[88:91], v[124:127], v[232:235], v[88:91]
	v_mfma_f32_16x16x32_bf16 v[76:79], v[116:119], v[240:243], v[76:79]
	v_mfma_f32_16x16x32_bf16 v[72:75], v[124:127], v[240:243], v[72:75]
	s_setprio 0
	s_setprio 1
	v_mfma_f32_16x16x32_bf16 v[136:139], v[128:131], v[184:187], v[136:139]
	v_mfma_f32_16x16x32_bf16 v[132:135], v[176:179], v[184:187], v[132:135]
	v_mfma_f32_16x16x32_bf16 v[100:103], v[128:131], v[220:223], v[100:103]
	v_mfma_f32_16x16x32_bf16 v[96:99], v[176:179], v[220:223], v[96:99]
	v_mfma_f32_16x16x32_bf16 v[84:87], v[128:131], v[228:231], v[84:87]
	v_mfma_f32_16x16x32_bf16 v[80:83], v[176:179], v[228:231], v[80:83]
	v_mfma_f32_16x16x32_bf16 v[68:71], v[128:131], v[236:239], v[68:71]
	v_mfma_f32_16x16x32_bf16 v[64:67], v[176:179], v[236:239], v[64:67]
	v_mfma_f32_16x16x32_bf16 v[136:139], v[140:143], v[216:219], v[136:139]
	v_mfma_f32_16x16x32_bf16 v[132:135], v[180:183], v[216:219], v[132:135]
	v_mfma_f32_16x16x32_bf16 v[100:103], v[140:143], v[224:227], v[100:103]
	v_mfma_f32_16x16x32_bf16 v[96:99], v[180:183], v[224:227], v[96:99]
	v_mfma_f32_16x16x32_bf16 v[84:87], v[140:143], v[232:235], v[84:87]
	v_mfma_f32_16x16x32_bf16 v[80:83], v[180:183], v[232:235], v[80:83]
	v_mfma_f32_16x16x32_bf16 v[68:71], v[140:143], v[240:243], v[68:71]
	v_mfma_f32_16x16x32_bf16 v[64:67], v[180:183], v[240:243], v[64:67]
	s_setprio 0
	s_barrier
; #define PG8_STAGE(bufoff, gbase, voff) do { _Pragma("unroll") for (int _i = 0; _i < 2; ++_i) \
;         __builtin_amdgcn_global_load_lds((const unsigned*)((const char*)(gbase) + (voff)[_i]), (LAS unsigned*)(lds + (bufoff) + ldsw + _i * 8192), 16, 0, 0); } while (0)
; #define PG8_LDA(dst, b, h) do { _Pragma("unroll") for (int m = 0; m < 4; ++m) _Pragma("unroll") for (int k = 0; k < 2; ++k) dst[m][k] = *(const LAS bf16x8*)(lds + PG8_SA(b, h) + aoff + m * 2048 + k * 1024); } while (0)
; #define PG8_MMA(ai, bj, At, Bt) do { __builtin_amdgcn_s_setprio(1); _Pragma("unroll") for (int m = 0; m < 4; ++m) _Pragma("unroll") for (int n = 0; n < 2; ++n) _Pragma("unroll") for (int k = 0; k < 2; ++k) \
;         acc[ai][bj][m][n] = __builtin_amdgcn_mfma_f32_16x16x32_bf16(Bt[n][k], At[m][k], acc[ai][bj][m][n], 0, 0, 0); __builtin_amdgcn_s_setprio(0); } while (0)
; #define PG8_WAIT_V(n) asm volatile("s_waitcnt vmcnt(" #n ")" ::: "memory")
; #define PG8_WAIT_L(n) asm volatile("s_waitcnt lgkmcnt(" #n ")" ::: "memory")
; #define PG8_BAR __builtin_amdgcn_s_barrier()
; #define PG8_SCHED __builtin_amdgcn_sched_barrier(0)
; template <class Epi>
; __device__ __forceinline__ void gemm_phase(LAS unsigned char* lds, const Gemm g, const int G, const int cidx, const int tid, const Epi& E) {
;     ...
;             PG8_LDA(At, 1, 1); PG8_STAGE(PG8_SB(1, 0), b3, voffB); PG8_STAGE(PG8_SB(1, 1), b3 + hstepB, voffB); PG8_STAGE(PG8_SA(1, 0), a3, voffA);
;             PG8_WAIT_V(8); PG8_WAIT_L(0); PG8_BAR; PG8_MMA(1, 0, At, B0); PG8_MMA(1, 1, At, B1); PG8_BAR; PG8_SCHED;
;         }
	s_add_i32 s10, s10, s11
	v_lshl_add_u64 v[158:159], v[158:159], 0, s[96:97]
	s_mov_b32 m0, s10
	ds_read_b128 v[184:187], v215 offset:49152
	ds_read_b128 v[216:219], v215 offset:50176
	ds_read_b128 v[220:223], v215 offset:51200
	ds_read_b128 v[224:227], v215 offset:52224
	ds_read_b128 v[228:231], v215 offset:53248
	ds_read_b128 v[232:235], v215 offset:54272
	ds_read_b128 v[236:239], v215 offset:55296
	ds_read_b128 v[240:243], v215 offset:56320
	global_load_lds_dwordx4 v[158:159], off
	s_add_i32 m0, s10, 0x2000
	s_add_u32 s60, s60, 0x40080
	v_lshl_add_u64 v[158:159], v[188:189], 0, s[96:97]
	s_addc_u32 s61, s61, 0
	s_add_i32 s10, s66, s11
	global_load_lds_dwordx4 v[158:159], off
	v_lshl_add_u64 v[158:159], s[60:61], 0, v[166:167]
	s_mov_b32 m0, s10
	s_nop 0
	global_load_lds_dwordx4 v[158:159], off
	v_lshl_add_u64 v[158:159], s[60:61], 0, v[170:171]
	s_add_i32 m0, s10, 0x2000
	s_nop 0
	global_load_lds_dwordx4 v[158:159], off
	v_lshl_add_u64 v[158:159], v[244:245], 0, s[96:97]
	s_mov_b32 m0, s12
	s_nop 0
	global_load_lds_dwordx4 v[158:159], off
	v_lshl_add_u64 v[158:159], v[246:247], 0, s[96:97]
	s_mov_b32 m0, s13
	s_nop 0
	global_load_lds_dwordx4 v[158:159], off
	s_waitcnt vmcnt(8)
	s_waitcnt lgkmcnt(0)
	s_barrier
	s_setprio 1
	s_waitcnt lgkmcnt(0)
	v_mfma_f32_16x16x32_bf16 v[60:63], v[112:115], v[184:187], v[60:63]
	v_mfma_f32_16x16x32_bf16 v[56:59], v[120:123], v[184:187], v[56:59]
	v_mfma_f32_16x16x32_bf16 v[44:47], v[112:115], v[220:223], v[44:47]
	v_mfma_f32_16x16x32_bf16 v[40:43], v[120:123], v[220:223], v[40:43]
	v_mfma_f32_16x16x32_bf16 v[28:31], v[112:115], v[228:231], v[28:31]
	v_mfma_f32_16x16x32_bf16 v[24:27], v[120:123], v[228:231], v[24:27]
	v_mfma_f32_16x16x32_bf16 v[12:15], v[112:115], v[236:239], v[12:15]
	v_mfma_f32_16x16x32_bf16 v[8:11], v[120:123], v[236:239], v[8:11]
	v_mfma_f32_16x16x32_bf16 v[60:63], v[116:119], v[216:219], v[60:63]
	v_mfma_f32_16x16x32_bf16 v[56:59], v[124:127], v[216:219], v[56:59]
	v_mfma_f32_16x16x32_bf16 v[44:47], v[116:119], v[224:227], v[44:47]
	v_mfma_f32_16x16x32_bf16 v[40:43], v[124:127], v[224:227], v[40:43]
	v_mfma_f32_16x16x32_bf16 v[28:31], v[116:119], v[232:235], v[28:31]
	v_mfma_f32_16x16x32_bf16 v[24:27], v[124:127], v[232:235], v[24:27]
	v_mfma_f32_16x16x32_bf16 v[12:15], v[116:119], v[240:243], v[12:15]
	v_mfma_f32_16x16x32_bf16 v[8:11], v[124:127], v[240:243], v[8:11]
	s_setprio 0
	s_setprio 1
	v_mfma_f32_16x16x32_bf16 v[52:55], v[128:131], v[184:187], v[52:55]
	v_mfma_f32_16x16x32_bf16 v[48:51], v[176:179], v[184:187], v[48:51]
	v_mfma_f32_16x16x32_bf16 v[36:39], v[128:131], v[220:223], v[36:39]
	v_mfma_f32_16x16x32_bf16 v[32:35], v[176:179], v[220:223], v[32:35]
	v_mfma_f32_16x16x32_bf16 v[20:23], v[128:131], v[228:231], v[20:23]
	v_mfma_f32_16x16x32_bf16 v[16:19], v[176:179], v[228:231], v[16:19]
	v_mfma_f32_16x16x32_bf16 v[4:7], v[128:131], v[236:239], v[4:7]
	v_mfma_f32_16x16x32_bf16 v[0:3], v[176:179], v[236:239], v[0:3]
	v_mfma_f32_16x16x32_bf16 v[52:55], v[140:143], v[216:219], v[52:55]
	v_mfma_f32_16x16x32_bf16 v[48:51], v[180:183], v[216:219], v[48:51]
	v_mfma_f32_16x16x32_bf16 v[36:39], v[140:143], v[224:227], v[36:39]
	v_mfma_f32_16x16x32_bf16 v[32:35], v[180:183], v[224:227], v[32:35]
	v_mfma_f32_16x16x32_bf16 v[20:23], v[140:143], v[232:235], v[20:23]
	v_mfma_f32_16x16x32_bf16 v[16:19], v[180:183], v[232:235], v[16:19]
	v_mfma_f32_16x16x32_bf16 v[4:7], v[140:143], v[240:243], v[4:7]
	v_mfma_f32_16x16x32_bf16 v[0:3], v[180:183], v[240:243], v[0:3]
	s_setprio 0
	s_add_i32 s20, s20, 2
	s_add_u32 s58, s58, 0x100
	s_addc_u32 s59, s59, 0
	s_add_u32 s94, s94, 0x100
	s_addc_u32 s95, s95, 0
	s_barrier
	s_cmp_gt_u32 s20, 13
	s_cbranch_scc0 .LBB0_161
	s_and_b64 vcc, exec, s[16:17]
	s_cbranch_vccz .LBB0_164
	s_barrier

; #define PG8_STAGE(bufoff, gbase, voff) do { _Pragma("unroll") for (int _i = 0; _i < 2; ++_i) \
;         __builtin_amdgcn_global_load_lds((const unsigned*)((const char*)(gbase) + (voff)[_i]), (LAS unsigned*)(lds + (bufoff) + ldsw + _i * 8192), 16, 0, 0); } while (0)
; #define PG8_LDA(dst, b, h) do { _Pragma("unroll") for (int m = 0; m < 4; ++m) _Pragma("unroll") for (int k = 0; k < 2; ++k) dst[m][k] = *(const LAS bf16x8*)(lds + PG8_SA(b, h) + aoff + m * 2048 + k * 1024); } while (0)
; #define PG8_LDB(dst, b, h) do { _Pragma("unroll") for (int n = 0; n < 2; ++n) _Pragma("unroll") for (int k = 0; k < 2; ++k) dst[n][k] = *(const LAS bf16x8*)(lds + PG8_SB(b, h) + boff + n * 2048 + k * 1024); } while (0)
; #define PG8_MMA(ai, bj, At, Bt) do { __builtin_amdgcn_s_setprio(1); _Pragma("unroll") for (int m = 0; m < 4; ++m) _Pragma("unroll") for (int n = 0; n < 2; ++n) _Pragma("unroll") for (int k = 0; k < 2; ++k) \
;         acc[ai][bj][m][n] = __builtin_amdgcn_mfma_f32_16x16x32_bf16(Bt[n][k], At[m][k], acc[ai][bj][m][n], 0, 0, 0); __builtin_amdgcn_s_setprio(0); } while (0)
; #define PG8_WAIT_V(n) asm volatile("s_waitcnt vmcnt(" #n ")" ::: "memory")
; #define PG8_WAIT_L(n) asm volatile("s_waitcnt lgkmcnt(" #n ")" ::: "memory")
; #define PG8_BAR __builtin_amdgcn_s_barrier()
; #define PG8_SCHED __builtin_amdgcn_sched_barrier(0)
; template <class Epi>
; __device__ __forceinline__ void gemm_phase(LAS unsigned char* lds, const Gemm g, const int G, const int cidx, const int tid, const Epi& E) {
;     ...
;             PG8_LDB(B0, 0, 0); PG8_LDB(B1, 0, 1); PG8_SCHED; PG8_LDA(At, 0, 0); PG8_STAGE(PG8_SA(1, 1), a1 + hstepA, voffA);
;             PG8_WAIT_V(8); PG8_WAIT_L(0); PG8_BAR; PG8_MMA(0, 0, At, B0); PG8_MMA(0, 1, At, B1); PG8_BAR; PG8_SCHED;
;             PG8_LDA(At, 0, 1); PG8_STAGE(PG8_SB(0, 0), b2, voffB); PG8_STAGE(PG8_SB(0, 1), b2 + hstepB, voffB); PG8_STAGE(PG8_SA(0, 0), a2, voffA);
;             PG8_WAIT_V(8); PG8_WAIT_L(0); PG8_BAR; PG8_MMA(1, 0, At, B0); PG8_MMA(1, 1, At, B1); PG8_BAR; PG8_SCHED;
.LBB0_206:
	s_add_u32 s58, s56, 0xfffc0080
	s_addc_u32 s59, s57, -1
	s_add_i32 s66, 0, 0x10000
	s_cmp_eq_u32 s1, 12
	s_cselect_b32 s61, s17, s59
	s_cselect_b32 s60, s35, s58
	s_cselect_b32 s59, s15, s0
	s_cselect_b32 s58, vcc_lo, vcc_hi
	s_add_i32 s30, 0, 0x14000
	v_add_u32_e32 v144, s66, v130
	v_add_u32_e32 v158, s30, v130
	ds_read_b128 v[132:135], v144
	ds_read_b128 v[136:139], v144 offset:1024
	ds_read_b128 v[140:143], v144 offset:2048
	ds_read_b128 v[144:147], v144 offset:3072
	ds_read_b128 v[148:151], v158
	ds_read_b128 v[172:175], v158 offset:1024
	ds_read_b128 v[176:179], v158 offset:2048
	ds_read_b128 v[180:183], v158 offset:3072
	v_lshl_add_u64 v[158:159], s[56:57], 0, v[152:153]
	s_add_i32 m0, s31, 0xc000
	ds_read_b128 v[184:187], v131
	ds_read_b128 v[210:213], v131 offset:1024
	ds_read_b128 v[214:217], v131 offset:2048
	ds_read_b128 v[218:221], v131 offset:3072
	ds_read_b128 v[222:225], v131 offset:4096
	ds_read_b128 v[226:229], v131 offset:5120
	ds_read_b128 v[230:233], v131 offset:6144
	ds_read_b128 v[234:237], v131 offset:7168
	global_load_lds_dwordx4 v[158:159], off
	v_lshl_add_u64 v[158:159], s[56:57], 0, v[128:129]
	s_add_i32 m0, s31, 0xe000
	s_nop 0
	global_load_lds_dwordx4 v[158:159], off
	s_waitcnt vmcnt(8)
	s_waitcnt lgkmcnt(0)
	s_barrier
	s_setprio 1
	s_waitcnt lgkmcnt(0)
	v_mfma_f32_16x16x32_bf16 v[124:127], v[132:135], v[184:187], v[124:127]
	v_mfma_f32_16x16x32_bf16 v[120:123], v[140:143], v[184:187], v[120:123]
	v_mfma_f32_16x16x32_bf16 v[108:111], v[132:135], v[214:217], v[108:111]
	v_mfma_f32_16x16x32_bf16 v[104:107], v[140:143], v[214:217], v[104:107]
	v_mfma_f32_16x16x32_bf16 v[92:95], v[132:135], v[222:225], v[92:95]
	v_mfma_f32_16x16x32_bf16 v[88:91], v[140:143], v[222:225], v[88:91]
	v_mfma_f32_16x16x32_bf16 v[76:79], v[132:135], v[230:233], v[76:79]
	v_mfma_f32_16x16x32_bf16 v[72:75], v[140:143], v[230:233], v[72:75]
	v_mfma_f32_16x16x32_bf16 v[124:127], v[136:139], v[210:213], v[124:127]
	v_mfma_f32_16x16x32_bf16 v[120:123], v[144:147], v[210:213], v[120:123]
	v_mfma_f32_16x16x32_bf16 v[108:111], v[136:139], v[218:221], v[108:111]
	v_mfma_f32_16x16x32_bf16 v[104:107], v[144:147], v[218:221], v[104:107]
	v_mfma_f32_16x16x32_bf16 v[92:95], v[136:139], v[226:229], v[92:95]
	v_mfma_f32_16x16x32_bf16 v[88:91], v[144:147], v[226:229], v[88:91]
	v_mfma_f32_16x16x32_bf16 v[76:79], v[136:139], v[234:237], v[76:79]
	v_mfma_f32_16x16x32_bf16 v[72:75], v[144:147], v[234:237], v[72:75]
	s_setprio 0
	s_setprio 1
	v_mfma_f32_16x16x32_bf16 v[116:119], v[148:151], v[184:187], v[116:119]
	v_mfma_f32_16x16x32_bf16 v[112:115], v[176:179], v[184:187], v[112:115]
	v_mfma_f32_16x16x32_bf16 v[100:103], v[148:151], v[214:217], v[100:103]
	v_mfma_f32_16x16x32_bf16 v[96:99], v[176:179], v[214:217], v[96:99]
	v_mfma_f32_16x16x32_bf16 v[84:87], v[148:151], v[222:225], v[84:87]
	v_mfma_f32_16x16x32_bf16 v[80:83], v[176:179], v[222:225], v[80:83]
	v_mfma_f32_16x16x32_bf16 v[68:71], v[148:151], v[230:233], v[68:71]
	v_mfma_f32_16x16x32_bf16 v[64:67], v[176:179], v[230:233], v[64:67]
	v_mfma_f32_16x16x32_bf16 v[116:119], v[172:175], v[210:213], v[116:119]
	v_mfma_f32_16x16x32_bf16 v[112:115], v[180:183], v[210:213], v[112:115]
	v_mfma_f32_16x16x32_bf16 v[100:103], v[172:175], v[218:221], v[100:103]
	v_mfma_f32_16x16x32_bf16 v[96:99], v[180:183], v[218:221], v[96:99]
	v_mfma_f32_16x16x32_bf16 v[84:87], v[172:175], v[226:229], v[84:87]
	v_mfma_f32_16x16x32_bf16 v[80:83], v[180:183], v[226:229], v[80:83]
	v_mfma_f32_16x16x32_bf16 v[68:71], v[172:175], v[234:237], v[68:71]
	v_mfma_f32_16x16x32_bf16 v[64:67], v[180:183], v[234:237], v[64:67]
	s_setprio 0
	s_barrier
	s_add_i32 s66, s66, s29
	v_lshl_add_u64 v[158:159], s[58:59], 0, v[166:167]
	s_mov_b32 m0, s66
	ds_read_b128 v[184:187], v131 offset:16384
	ds_read_b128 v[210:213], v131 offset:17408
	ds_read_b128 v[214:217], v131 offset:18432
	ds_read_b128 v[218:221], v131 offset:19456
	ds_read_b128 v[222:225], v131 offset:20480
	ds_read_b128 v[226:229], v131 offset:21504
	ds_read_b128 v[230:233], v131 offset:22528
	ds_read_b128 v[234:237], v131 offset:23552
	global_load_lds_dwordx4 v[158:159], off
	s_add_i32 m0, s66, 0x2000
	s_add_u32 s66, s58, 0x40000
	v_lshl_add_u64 v[188:189], s[58:59], 0, v[170:171]
	s_addc_u32 s67, s59, 0
	s_add_i32 s30, s30, s29
	global_load_lds_dwordx4 v[188:189], off
	v_lshl_add_u64 v[192:193], s[66:67], 0, v[166:167]
	s_mov_b32 m0, s30
	v_lshl_add_u64 v[208:209], s[60:61], 0, v[168:169]
	global_load_lds_dwordx4 v[192:193], off
	v_lshl_add_u64 v[192:193], s[66:67], 0, v[170:171]
	s_add_i32 m0, s30, 0x2000
	s_nop 0
	global_load_lds_dwordx4 v[192:193], off
	v_lshl_add_u64 v[192:193], s[60:61], 0, v[164:165]
	s_mov_b32 m0, s31
	s_nop 0
	global_load_lds_dwordx4 v[192:193], off
	s_mov_b32 m0, s55
	s_nop 0
	global_load_lds_dwordx4 v[208:209], off
	s_waitcnt vmcnt(8)
	s_waitcnt lgkmcnt(0)
	s_barrier
; #define PG8_STAGE(bufoff, gbase, voff) do { _Pragma("unroll") for (int _i = 0; _i < 2; ++_i) \
;         __builtin_amdgcn_global_load_lds((const unsigned*)((const char*)(gbase) + (voff)[_i]), (LAS unsigned*)(lds + (bufoff) + ldsw + _i * 8192), 16, 0, 0); } while (0)
; #define PG8_LDA(dst, b, h) do { _Pragma("unroll") for (int m = 0; m < 4; ++m) _Pragma("unroll") for (int k = 0; k < 2; ++k) dst[m][k] = *(const LAS bf16x8*)(lds + PG8_SA(b, h) + aoff + m * 2048 + k * 1024); } while (0)
; #define PG8_LDB(dst, b, h) do { _Pragma("unroll") for (int n = 0; n < 2; ++n) _Pragma("unroll") for (int k = 0; k < 2; ++k) dst[n][k] = *(const LAS bf16x8*)(lds + PG8_SB(b, h) + boff + n * 2048 + k * 1024); } while (0)
; #define PG8_MMA(ai, bj, At, Bt) do { __builtin_amdgcn_s_setprio(1); _Pragma("unroll") for (int m = 0; m < 4; ++m) _Pragma("unroll") for (int n = 0; n < 2; ++n) _Pragma("unroll") for (int k = 0; k < 2; ++k) \
;         acc[ai][bj][m][n] = __builtin_amdgcn_mfma_f32_16x16x32_bf16(Bt[n][k], At[m][k], acc[ai][bj][m][n], 0, 0, 0); __builtin_amdgcn_s_setprio(0); } while (0)
; #define PG8_WAIT_V(n) asm volatile("s_waitcnt vmcnt(" #n ")" ::: "memory")
; #define PG8_WAIT_L(n) asm volatile("s_waitcnt lgkmcnt(" #n ")" ::: "memory")
; #define PG8_BAR __builtin_amdgcn_s_barrier()
; #define PG8_SCHED __builtin_amdgcn_sched_barrier(0)
; template <class Epi>
; __device__ __forceinline__ void gemm_phase(LAS unsigned char* lds, const Gemm g, const int G, const int cidx, const int tid, const Epi& E) {
;     ...
;             PG8_WAIT_V(8); PG8_WAIT_L(0); PG8_BAR; PG8_MMA(1, 0, At, B0); PG8_MMA(1, 1, At, B1); PG8_BAR; PG8_SCHED;
;             PG8_LDB(B0, 1, 0); PG8_LDB(B1, 1, 1); PG8_SCHED; PG8_LDA(At, 1, 0); PG8_STAGE(PG8_SA(0, 1), a2 + hstepA, voffA);
;             PG8_WAIT_V(8); PG8_WAIT_L(0); PG8_BAR; PG8_MMA(0, 0, At, B0); PG8_MMA(0, 1, At, B1); PG8_BAR; PG8_SCHED;
	s_setprio 1
	s_waitcnt lgkmcnt(0)
	v_mfma_f32_16x16x32_bf16 v[60:63], v[132:135], v[184:187], v[60:63]
	v_mfma_f32_16x16x32_bf16 v[56:59], v[140:143], v[184:187], v[56:59]
	v_mfma_f32_16x16x32_bf16 v[44:47], v[132:135], v[214:217], v[44:47]
	v_mfma_f32_16x16x32_bf16 v[40:43], v[140:143], v[214:217], v[40:43]
	v_mfma_f32_16x16x32_bf16 v[28:31], v[132:135], v[222:225], v[28:31]
	v_mfma_f32_16x16x32_bf16 v[24:27], v[140:143], v[222:225], v[24:27]
	v_mfma_f32_16x16x32_bf16 v[12:15], v[132:135], v[230:233], v[12:15]
	v_mfma_f32_16x16x32_bf16 v[8:11], v[140:143], v[230:233], v[8:11]
	v_mfma_f32_16x16x32_bf16 v[60:63], v[136:139], v[210:213], v[60:63]
	v_mfma_f32_16x16x32_bf16 v[56:59], v[144:147], v[210:213], v[56:59]
	v_mfma_f32_16x16x32_bf16 v[44:47], v[136:139], v[218:221], v[44:47]
	v_mfma_f32_16x16x32_bf16 v[40:43], v[144:147], v[218:221], v[40:43]
	v_mfma_f32_16x16x32_bf16 v[28:31], v[136:139], v[226:229], v[28:31]
	v_mfma_f32_16x16x32_bf16 v[24:27], v[144:147], v[226:229], v[24:27]
	v_mfma_f32_16x16x32_bf16 v[12:15], v[136:139], v[234:237], v[12:15]
	v_mfma_f32_16x16x32_bf16 v[8:11], v[144:147], v[234:237], v[8:11]
	s_setprio 0
	s_setprio 1
	v_mfma_f32_16x16x32_bf16 v[52:55], v[148:151], v[184:187], v[52:55]
	v_mfma_f32_16x16x32_bf16 v[48:51], v[176:179], v[184:187], v[48:51]
	v_mfma_f32_16x16x32_bf16 v[36:39], v[148:151], v[214:217], v[36:39]
	v_mfma_f32_16x16x32_bf16 v[32:35], v[176:179], v[214:217], v[32:35]
	v_mfma_f32_16x16x32_bf16 v[20:23], v[148:151], v[222:225], v[20:23]
	v_mfma_f32_16x16x32_bf16 v[16:19], v[176:179], v[222:225], v[16:19]
	v_mfma_f32_16x16x32_bf16 v[4:7], v[148:151], v[230:233], v[4:7]
	v_mfma_f32_16x16x32_bf16 v[0:3], v[176:179], v[230:233], v[0:3]
	v_mfma_f32_16x16x32_bf16 v[52:55], v[172:175], v[210:213], v[52:55]
	v_mfma_f32_16x16x32_bf16 v[48:51], v[180:183], v[210:213], v[48:51]
	v_mfma_f32_16x16x32_bf16 v[36:39], v[172:175], v[218:221], v[36:39]
	v_mfma_f32_16x16x32_bf16 v[32:35], v[180:183], v[218:221], v[32:35]
	v_mfma_f32_16x16x32_bf16 v[20:23], v[172:175], v[226:229], v[20:23]
	v_mfma_f32_16x16x32_bf16 v[16:19], v[180:183], v[226:229], v[16:19]
	v_mfma_f32_16x16x32_bf16 v[4:7], v[172:175], v[234:237], v[4:7]
	v_mfma_f32_16x16x32_bf16 v[0:3], v[180:183], v[234:237], v[0:3]
	s_setprio 0
	s_barrier
	s_add_i32 s30, 0, 0x18000
	s_add_i32 s66, 0, 0x1c000
	v_add_u32_e32 v144, s30, v130
	v_add_u32_e32 v180, s66, v130
	ds_read_b128 v[132:135], v144
	ds_read_b128 v[136:139], v144 offset:1024
	ds_read_b128 v[140:143], v144 offset:2048
	ds_read_b128 v[144:147], v144 offset:3072
	ds_read_b128 v[148:151], v180
	ds_read_b128 v[172:175], v180 offset:1024
	ds_read_b128 v[176:179], v180 offset:2048
	ds_read_b128 v[180:183], v180 offset:3072
	s_add_u32 s60, s60, 0x40000
	s_addc_u32 s61, s61, 0
	s_mov_b32 m0, s62
	v_lshl_add_u64 v[238:239], s[60:61], 0, v[164:165]
	ds_read_b128 v[184:187], v131 offset:32768
	ds_read_b128 v[210:213], v131 offset:33792
	ds_read_b128 v[214:217], v131 offset:34816
	ds_read_b128 v[218:221], v131 offset:35840
	ds_read_b128 v[222:225], v131 offset:36864
	ds_read_b128 v[226:229], v131 offset:37888
	ds_read_b128 v[230:233], v131 offset:38912
	ds_read_b128 v[234:237], v131 offset:39936
	global_load_lds_dwordx4 v[238:239], off
	v_lshl_add_u64 v[238:239], s[60:61], 0, v[168:169]
	s_mov_b32 m0, s63
	s_nop 0
	global_load_lds_dwordx4 v[238:239], off
	s_waitcnt vmcnt(8)
	s_waitcnt lgkmcnt(0)
	s_barrier
	s_setprio 1
	s_waitcnt lgkmcnt(0)
	v_mfma_f32_16x16x32_bf16 v[124:127], v[132:135], v[184:187], v[124:127]
	v_mfma_f32_16x16x32_bf16 v[120:123], v[140:143], v[184:187], v[120:123]
	v_mfma_f32_16x16x32_bf16 v[108:111], v[132:135], v[214:217], v[108:111]
	v_mfma_f32_16x16x32_bf16 v[104:107], v[140:143], v[214:217], v[104:107]
	v_mfma_f32_16x16x32_bf16 v[92:95], v[132:135], v[222:225], v[92:95]
	v_mfma_f32_16x16x32_bf16 v[88:91], v[140:143], v[222:225], v[88:91]
	v_mfma_f32_16x16x32_bf16 v[76:79], v[132:135], v[230:233], v[76:79]
	v_mfma_f32_16x16x32_bf16 v[72:75], v[140:143], v[230:233], v[72:75]
	v_mfma_f32_16x16x32_bf16 v[124:127], v[136:139], v[210:213], v[124:127]
	v_mfma_f32_16x16x32_bf16 v[120:123], v[144:147], v[210:213], v[120:123]
	v_mfma_f32_16x16x32_bf16 v[108:111], v[136:139], v[218:221], v[108:111]
	v_mfma_f32_16x16x32_bf16 v[104:107], v[144:147], v[218:221], v[104:107]
	v_mfma_f32_16x16x32_bf16 v[92:95], v[136:139], v[226:229], v[92:95]
	v_mfma_f32_16x16x32_bf16 v[88:91], v[144:147], v[226:229], v[88:91]
	v_mfma_f32_16x16x32_bf16 v[76:79], v[136:139], v[234:237], v[76:79]
	v_mfma_f32_16x16x32_bf16 v[72:75], v[144:147], v[234:237], v[72:75]
	s_setprio 0
	s_setprio 1
	v_mfma_f32_16x16x32_bf16 v[116:119], v[148:151], v[184:187], v[116:119]
	v_mfma_f32_16x16x32_bf16 v[112:115], v[176:179], v[184:187], v[112:115]
	v_mfma_f32_16x16x32_bf16 v[100:103], v[148:151], v[214:217], v[100:103]
	v_mfma_f32_16x16x32_bf16 v[96:99], v[176:179], v[214:217], v[96:99]
	v_mfma_f32_16x16x32_bf16 v[84:87], v[148:151], v[222:225], v[84:87]
	v_mfma_f32_16x16x32_bf16 v[80:83], v[176:179], v[222:225], v[80:83]
	v_mfma_f32_16x16x32_bf16 v[68:71], v[148:151], v[230:233], v[68:71]
	v_mfma_f32_16x16x32_bf16 v[64:67], v[176:179], v[230:233], v[64:67]
	v_mfma_f32_16x16x32_bf16 v[116:119], v[172:175], v[210:213], v[116:119]
	v_mfma_f32_16x16x32_bf16 v[112:115], v[180:183], v[210:213], v[112:115]
	v_mfma_f32_16x16x32_bf16 v[100:103], v[172:175], v[218:221], v[100:103]
	v_mfma_f32_16x16x32_bf16 v[96:99], v[180:183], v[218:221], v[96:99]
	v_mfma_f32_16x16x32_bf16 v[84:87], v[172:175], v[226:229], v[84:87]
	v_mfma_f32_16x16x32_bf16 v[80:83], v[180:183], v[226:229], v[80:83]
	v_mfma_f32_16x16x32_bf16 v[68:71], v[172:175], v[234:237], v[68:71]
	v_mfma_f32_16x16x32_bf16 v[64:67], v[180:183], v[234:237], v[64:67]
	s_setprio 0
	s_barrier
; #define PG8_STAGE(bufoff, gbase, voff) do { _Pragma("unroll") for (int _i = 0; _i < 2; ++_i) \
;         __builtin_amdgcn_global_load_lds((const unsigned*)((const char*)(gbase) + (voff)[_i]), (LAS unsigned*)(lds + (bufoff) + ldsw + _i * 8192), 16, 0, 0); } while (0)
; #define PG8_LDA(dst, b, h) do { _Pragma("unroll") for (int m = 0; m < 4; ++m) _Pragma("unroll") for (int k = 0; k < 2; ++k) dst[m][k] = *(const LAS bf16x8*)(lds + PG8_SA(b, h) + aoff + m * 2048 + k * 1024); } while (0)
; #define PG8_MMA(ai, bj, At, Bt) do { __builtin_amdgcn_s_setprio(1); _Pragma("unroll") for (int m = 0; m < 4; ++m) _Pragma("unroll") for (int n = 0; n < 2; ++n) _Pragma("unroll") for (int k = 0; k < 2; ++k) \
;         acc[ai][bj][m][n] = __builtin_amdgcn_mfma_f32_16x16x32_bf16(Bt[n][k], At[m][k], acc[ai][bj][m][n], 0, 0, 0); __builtin_amdgcn_s_setprio(0); } while (0)
; #define PG8_WAIT_V(n) asm volatile("s_waitcnt vmcnt(" #n ")" ::: "memory")
; #define PG8_WAIT_L(n) asm volatile("s_waitcnt lgkmcnt(" #n ")" ::: "memory")
; #define PG8_BAR __builtin_amdgcn_s_barrier()
; #define PG8_SCHED __builtin_amdgcn_sched_barrier(0)
; template <class Epi>
; __device__ __forceinline__ void gemm_phase(LAS unsigned char* lds, const Gemm g, const int G, const int cidx, const int tid, const Epi& E) {
;     ...
;         for (int t = 0; t < nt; t += 2) {
;     ...
;             PG8_LDA(At, 1, 1); PG8_STAGE(PG8_SB(1, 0), b3, voffB); PG8_STAGE(PG8_SB(1, 1), b3 + hstepB, voffB); PG8_STAGE(PG8_SA(1, 0), a3, voffA);
;             PG8_WAIT_V(8); PG8_WAIT_L(0); PG8_BAR; PG8_MMA(1, 0, At, B0); PG8_MMA(1, 1, At, B1); PG8_BAR; PG8_SCHED;
	s_add_i32 s30, s30, s29
	v_lshl_add_u64 v[158:159], v[158:159], 0, s[96:97]
	s_mov_b32 m0, s30
	ds_read_b128 v[184:187], v131 offset:49152
	ds_read_b128 v[210:213], v131 offset:50176
	ds_read_b128 v[214:217], v131 offset:51200
	ds_read_b128 v[218:221], v131 offset:52224
	ds_read_b128 v[222:225], v131 offset:53248
	ds_read_b128 v[226:229], v131 offset:54272
	ds_read_b128 v[230:233], v131 offset:55296
	ds_read_b128 v[234:237], v131 offset:56320
	global_load_lds_dwordx4 v[158:159], off
	s_add_i32 m0, s30, 0x2000
	s_add_u32 s58, s58, 0x40080
	v_lshl_add_u64 v[158:159], v[188:189], 0, s[96:97]
	s_addc_u32 s59, s59, 0
	s_add_i32 s30, s66, s29
	global_load_lds_dwordx4 v[158:159], off
	v_lshl_add_u64 v[158:159], s[58:59], 0, v[166:167]
	s_mov_b32 m0, s30
	s_nop 0
	global_load_lds_dwordx4 v[158:159], off
	v_lshl_add_u64 v[158:159], s[58:59], 0, v[170:171]
	s_add_i32 m0, s30, 0x2000
	s_nop 0
	global_load_lds_dwordx4 v[158:159], off
	v_lshl_add_u64 v[158:159], v[192:193], 0, s[96:97]
	s_mov_b32 m0, s92
	s_nop 0
	global_load_lds_dwordx4 v[158:159], off
	v_lshl_add_u64 v[158:159], v[208:209], 0, s[96:97]
	s_mov_b32 m0, s94
	s_nop 0
	global_load_lds_dwordx4 v[158:159], off
	s_waitcnt vmcnt(8)
	s_waitcnt lgkmcnt(0)
	s_barrier
	s_setprio 1
	s_waitcnt lgkmcnt(0)
	v_mfma_f32_16x16x32_bf16 v[60:63], v[132:135], v[184:187], v[60:63]
	v_mfma_f32_16x16x32_bf16 v[56:59], v[140:143], v[184:187], v[56:59]
	v_mfma_f32_16x16x32_bf16 v[44:47], v[132:135], v[214:217], v[44:47]
	v_mfma_f32_16x16x32_bf16 v[40:43], v[140:143], v[214:217], v[40:43]
	v_mfma_f32_16x16x32_bf16 v[28:31], v[132:135], v[222:225], v[28:31]
	v_mfma_f32_16x16x32_bf16 v[24:27], v[140:143], v[222:225], v[24:27]
	v_mfma_f32_16x16x32_bf16 v[12:15], v[132:135], v[230:233], v[12:15]
	v_mfma_f32_16x16x32_bf16 v[8:11], v[140:143], v[230:233], v[8:11]
	v_mfma_f32_16x16x32_bf16 v[60:63], v[136:139], v[210:213], v[60:63]
	v_mfma_f32_16x16x32_bf16 v[56:59], v[144:147], v[210:213], v[56:59]
	v_mfma_f32_16x16x32_bf16 v[44:47], v[136:139], v[218:221], v[44:47]
	v_mfma_f32_16x16x32_bf16 v[40:43], v[144:147], v[218:221], v[40:43]
	v_mfma_f32_16x16x32_bf16 v[28:31], v[136:139], v[226:229], v[28:31]
	v_mfma_f32_16x16x32_bf16 v[24:27], v[144:147], v[226:229], v[24:27]
	v_mfma_f32_16x16x32_bf16 v[12:15], v[136:139], v[234:237], v[12:15]
	v_mfma_f32_16x16x32_bf16 v[8:11], v[144:147], v[234:237], v[8:11]
	s_setprio 0
	s_setprio 1
	v_mfma_f32_16x16x32_bf16 v[52:55], v[148:151], v[184:187], v[52:55]
	v_mfma_f32_16x16x32_bf16 v[48:51], v[176:179], v[184:187], v[48:51]
	v_mfma_f32_16x16x32_bf16 v[36:39], v[148:151], v[214:217], v[36:39]
	v_mfma_f32_16x16x32_bf16 v[32:35], v[176:179], v[214:217], v[32:35]
	v_mfma_f32_16x16x32_bf16 v[20:23], v[148:151], v[222:225], v[20:23]
	v_mfma_f32_16x16x32_bf16 v[16:19], v[176:179], v[222:225], v[16:19]
	v_mfma_f32_16x16x32_bf16 v[4:7], v[148:151], v[230:233], v[4:7]
	v_mfma_f32_16x16x32_bf16 v[0:3], v[176:179], v[230:233], v[0:3]
	v_mfma_f32_16x16x32_bf16 v[52:55], v[172:175], v[210:213], v[52:55]
	v_mfma_f32_16x16x32_bf16 v[48:51], v[180:183], v[210:213], v[48:51]
	v_mfma_f32_16x16x32_bf16 v[36:39], v[172:175], v[218:221], v[36:39]
	v_mfma_f32_16x16x32_bf16 v[32:35], v[180:183], v[218:221], v[32:35]
	v_mfma_f32_16x16x32_bf16 v[20:23], v[172:175], v[226:229], v[20:23]
	v_mfma_f32_16x16x32_bf16 v[16:19], v[180:183], v[226:229], v[16:19]
	v_mfma_f32_16x16x32_bf16 v[4:7], v[172:175], v[234:237], v[4:7]
	v_mfma_f32_16x16x32_bf16 v[0:3], v[180:183], v[234:237], v[0:3]
	s_setprio 0
	s_add_i32 s1, s1, 2
	s_add_u32 s56, s56, 0x100
	s_addc_u32 s57, s57, 0
	s_add_u32 vcc_hi, vcc_hi, 0x100
	s_addc_u32 s0, s0, 0
	s_barrier
	s_cmp_gt_u32 s1, 13
	s_cbranch_scc0 .LBB0_206
	s_and_b64 vcc, exec, s[12:13]
	s_cbranch_vccz .LBB0_209
	s_barrier

; #define PG8_STAGE(bufoff, gbase, voff) do { _Pragma("unroll") for (int _i = 0; _i < 2; ++_i) \
;         __builtin_amdgcn_global_load_lds((const unsigned*)((const char*)(gbase) + (voff)[_i]), (LAS unsigned*)(lds + (bufoff) + ldsw + _i * 8192), 16, 0, 0); } while (0)
; #define PG8_LDA(dst, b, h) do { _Pragma("unroll") for (int m = 0; m < 4; ++m) _Pragma("unroll") for (int k = 0; k < 2; ++k) dst[m][k] = *(const LAS bf16x8*)(lds + PG8_SA(b, h) + aoff + m * 2048 + k * 1024); } while (0)
; #define PG8_LDB(dst, b, h) do { _Pragma("unroll") for (int n = 0; n < 2; ++n) _Pragma("unroll") for (int k = 0; k < 2; ++k) dst[n][k] = *(const LAS bf16x8*)(lds + PG8_SB(b, h) + boff + n * 2048 + k * 1024); } while (0)
; #define PG8_MMA(ai, bj, At, Bt) do { __builtin_amdgcn_s_setprio(1); _Pragma("unroll") for (int m = 0; m < 4; ++m) _Pragma("unroll") for (int n = 0; n < 2; ++n) _Pragma("unroll") for (int k = 0; k < 2; ++k) \
;         acc[ai][bj][m][n] = __builtin_amdgcn_mfma_f32_16x16x32_bf16(Bt[n][k], At[m][k], acc[ai][bj][m][n], 0, 0, 0); __builtin_amdgcn_s_setprio(0); } while (0)
; #define PG8_WAIT_V(n) asm volatile("s_waitcnt vmcnt(" #n ")" ::: "memory")
; #define PG8_WAIT_L(n) asm volatile("s_waitcnt lgkmcnt(" #n ")" ::: "memory")
; #define PG8_BAR __builtin_amdgcn_s_barrier()
; #define PG8_SCHED __builtin_amdgcn_sched_barrier(0)
; template <class Epi>
; __device__ __forceinline__ void gemm_phase(LAS unsigned char* lds, const Gemm g, const int G, const int cidx, const int tid, const Epi& E) {
;     ...
;             const bool last = (t == nt - 2);
;             const char* a1 = cA + (size_t)(t + 1) * kstep;
;             const char* a2 = last ? nA : cA + (size_t)(t + 2) * kstep; const char* b2 = last ? nB : cB + (size_t)(t + 2) * kstep;
;             const char* a3 = a2 + kstep; const char* b3 = b2 + kstep;
;             PG8_LDB(B0, 0, 0); PG8_LDB(B1, 0, 1); PG8_SCHED; PG8_LDA(At, 0, 0); PG8_STAGE(PG8_SA(1, 1), a1 + hstepA, voffA);
;             PG8_WAIT_V(8); PG8_WAIT_L(0); PG8_BAR; PG8_MMA(0, 0, At, B0); PG8_MMA(0, 1, At, B1); PG8_BAR; PG8_SCHED;
;             PG8_LDA(At, 0, 1); PG8_STAGE(PG8_SB(0, 0), b2, voffB); PG8_STAGE(PG8_SB(0, 1), b2 + hstepB, voffB); PG8_STAGE(PG8_SA(0, 0), a2, voffA);
.LBB0_232:
	s_add_u32 s8, s54, 0xfffe0080
	s_addc_u32 s9, s55, -1
	s_add_i32 s66, 0, 0x10000
	s_cmp_eq_u32 vcc_lo, 4
	s_cselect_b32 s59, s15, s9
	s_cselect_b32 s58, s35, s8
	v_add_u32_e32 v150, s66, v169
	s_cselect_b32 s57, s13, s95
	s_cselect_b32 s56, s92, s94
	s_add_i32 s67, 0, 0x14000
	ds_read_b128 v[128:131], v150
	ds_read_b128 v[132:135], v150 offset:1024
	ds_read_b128 v[146:149], v150 offset:2048
	ds_read_b128 v[164:167], v150 offset:3072
	v_add_u32_e32 v150, s67, v169
	ds_read_b128 v[172:175], v150
	ds_read_b128 v[176:179], v150 offset:1024
	ds_read_b128 v[180:183], v150 offset:2048
	ds_read_b128 v[184:187], v150 offset:3072
	v_lshl_add_u64 v[150:151], s[54:55], 0, v[142:143]
	s_add_i32 m0, s29, 0xc000
	ds_read_b128 v[188:191], v170
	ds_read_b128 v[210:213], v170 offset:1024
	ds_read_b128 v[214:217], v170 offset:2048
	ds_read_b128 v[218:221], v170 offset:3072
	ds_read_b128 v[222:225], v170 offset:4096
	ds_read_b128 v[226:229], v170 offset:5120
	ds_read_b128 v[230:233], v170 offset:6144
	ds_read_b128 v[234:237], v170 offset:7168
	global_load_lds_dwordx4 v[150:151], off
	v_lshl_add_u64 v[150:151], s[54:55], 0, v[144:145]
	s_add_i32 m0, s29, 0xe000
	s_nop 0
	global_load_lds_dwordx4 v[150:151], off
	s_waitcnt vmcnt(8)
	s_waitcnt lgkmcnt(0)
	s_barrier
	s_setprio 1
	s_waitcnt lgkmcnt(0)
	v_mfma_f32_16x16x32_bf16 v[124:127], v[128:131], v[188:191], v[124:127]
	v_mfma_f32_16x16x32_bf16 v[120:123], v[146:149], v[188:191], v[120:123]
	v_mfma_f32_16x16x32_bf16 v[108:111], v[128:131], v[214:217], v[108:111]
	v_mfma_f32_16x16x32_bf16 v[104:107], v[146:149], v[214:217], v[104:107]
	v_mfma_f32_16x16x32_bf16 v[92:95], v[128:131], v[222:225], v[92:95]
	v_mfma_f32_16x16x32_bf16 v[88:91], v[146:149], v[222:225], v[88:91]
	v_mfma_f32_16x16x32_bf16 v[76:79], v[128:131], v[230:233], v[76:79]
	v_mfma_f32_16x16x32_bf16 v[72:75], v[146:149], v[230:233], v[72:75]
	v_mfma_f32_16x16x32_bf16 v[124:127], v[132:135], v[210:213], v[124:127]
	v_mfma_f32_16x16x32_bf16 v[120:123], v[164:167], v[210:213], v[120:123]
	v_mfma_f32_16x16x32_bf16 v[108:111], v[132:135], v[218:221], v[108:111]
	v_mfma_f32_16x16x32_bf16 v[104:107], v[164:167], v[218:221], v[104:107]
	v_mfma_f32_16x16x32_bf16 v[92:95], v[132:135], v[226:229], v[92:95]
	v_mfma_f32_16x16x32_bf16 v[88:91], v[164:167], v[226:229], v[88:91]
	v_mfma_f32_16x16x32_bf16 v[76:79], v[132:135], v[234:237], v[76:79]
	v_mfma_f32_16x16x32_bf16 v[72:75], v[164:167], v[234:237], v[72:75]
	s_setprio 0
	s_setprio 1
	v_mfma_f32_16x16x32_bf16 v[116:119], v[172:175], v[188:191], v[116:119]
	v_mfma_f32_16x16x32_bf16 v[112:115], v[180:183], v[188:191], v[112:115]
	v_mfma_f32_16x16x32_bf16 v[100:103], v[172:175], v[214:217], v[100:103]
	v_mfma_f32_16x16x32_bf16 v[96:99], v[180:183], v[214:217], v[96:99]
	v_mfma_f32_16x16x32_bf16 v[84:87], v[172:175], v[222:225], v[84:87]
	v_mfma_f32_16x16x32_bf16 v[80:83], v[180:183], v[222:225], v[80:83]
	v_mfma_f32_16x16x32_bf16 v[68:71], v[172:175], v[230:233], v[68:71]
	v_mfma_f32_16x16x32_bf16 v[64:67], v[180:183], v[230:233], v[64:67]
	v_mfma_f32_16x16x32_bf16 v[116:119], v[176:179], v[210:213], v[116:119]
	v_mfma_f32_16x16x32_bf16 v[112:115], v[184:187], v[210:213], v[112:115]
	v_mfma_f32_16x16x32_bf16 v[100:103], v[176:179], v[218:221], v[100:103]
	v_mfma_f32_16x16x32_bf16 v[96:99], v[184:187], v[218:221], v[96:99]
	v_mfma_f32_16x16x32_bf16 v[84:87], v[176:179], v[226:229], v[84:87]
	v_mfma_f32_16x16x32_bf16 v[80:83], v[184:187], v[226:229], v[80:83]
	v_mfma_f32_16x16x32_bf16 v[68:71], v[176:179], v[234:237], v[68:71]
	v_mfma_f32_16x16x32_bf16 v[64:67], v[184:187], v[234:237], v[64:67]
	s_setprio 0
	s_barrier
	s_add_i32 s8, s66, s25
	v_lshl_add_u64 v[150:151], s[56:57], 0, v[152:153]
	s_mov_b32 m0, s8
	ds_read_b128 v[188:191], v170 offset:16384
	ds_read_b128 v[210:213], v170 offset:17408
	ds_read_b128 v[214:217], v170 offset:18432
	ds_read_b128 v[218:221], v170 offset:19456
	ds_read_b128 v[222:225], v170 offset:20480
	ds_read_b128 v[226:229], v170 offset:21504
	ds_read_b128 v[230:233], v170 offset:22528
	ds_read_b128 v[234:237], v170 offset:23552
	global_load_lds_dwordx4 v[150:151], off
	s_add_i32 m0, s8, 0x2000
	s_add_u32 s8, s56, 0x20000
	v_lshl_add_u64 v[158:159], s[56:57], 0, v[140:141]
	s_addc_u32 s9, s57, 0
	s_add_i32 s66, s67, s25
	global_load_lds_dwordx4 v[158:159], off
	v_lshl_add_u64 v[192:193], s[8:9], 0, v[152:153]
	s_mov_b32 m0, s66
	v_lshl_add_u64 v[208:209], s[58:59], 0, v[138:139]
	global_load_lds_dwordx4 v[192:193], off
	v_lshl_add_u64 v[192:193], s[8:9], 0, v[140:141]
	s_add_i32 m0, s66, 0x2000
	s_nop 0
	global_load_lds_dwordx4 v[192:193], off
	v_lshl_add_u64 v[192:193], s[58:59], 0, v[136:137]
	s_mov_b32 m0, s29
	s_nop 0
	global_load_lds_dwordx4 v[192:193], off
	s_mov_b32 m0, s31
	s_nop 0
	global_load_lds_dwordx4 v[208:209], off
	s_waitcnt vmcnt(8)
	s_waitcnt lgkmcnt(0)
	s_barrier
; #define PG8_STAGE(bufoff, gbase, voff) do { _Pragma("unroll") for (int _i = 0; _i < 2; ++_i) \
;         __builtin_amdgcn_global_load_lds((const unsigned*)((const char*)(gbase) + (voff)[_i]), (LAS unsigned*)(lds + (bufoff) + ldsw + _i * 8192), 16, 0, 0); } while (0)
; #define PG8_LDA(dst, b, h) do { _Pragma("unroll") for (int m = 0; m < 4; ++m) _Pragma("unroll") for (int k = 0; k < 2; ++k) dst[m][k] = *(const LAS bf16x8*)(lds + PG8_SA(b, h) + aoff + m * 2048 + k * 1024); } while (0)
; #define PG8_LDB(dst, b, h) do { _Pragma("unroll") for (int n = 0; n < 2; ++n) _Pragma("unroll") for (int k = 0; k < 2; ++k) dst[n][k] = *(const LAS bf16x8*)(lds + PG8_SB(b, h) + boff + n * 2048 + k * 1024); } while (0)
; #define PG8_MMA(ai, bj, At, Bt) do { __builtin_amdgcn_s_setprio(1); _Pragma("unroll") for (int m = 0; m < 4; ++m) _Pragma("unroll") for (int n = 0; n < 2; ++n) _Pragma("unroll") for (int k = 0; k < 2; ++k) \
;         acc[ai][bj][m][n] = __builtin_amdgcn_mfma_f32_16x16x32_bf16(Bt[n][k], At[m][k], acc[ai][bj][m][n], 0, 0, 0); __builtin_amdgcn_s_setprio(0); } while (0)
; #define PG8_WAIT_V(n) asm volatile("s_waitcnt vmcnt(" #n ")" ::: "memory")
; #define PG8_WAIT_L(n) asm volatile("s_waitcnt lgkmcnt(" #n ")" ::: "memory")
; #define PG8_BAR __builtin_amdgcn_s_barrier()
; #define PG8_SCHED __builtin_amdgcn_sched_barrier(0)
; template <class Epi>
; __device__ __forceinline__ void gemm_phase(LAS unsigned char* lds, const Gemm g, const int G, const int cidx, const int tid, const Epi& E) {
;     ...
;             PG8_WAIT_V(8); PG8_WAIT_L(0); PG8_BAR; PG8_MMA(1, 0, At, B0); PG8_MMA(1, 1, At, B1); PG8_BAR; PG8_SCHED;
;             PG8_LDB(B0, 1, 0); PG8_LDB(B1, 1, 1); PG8_SCHED; PG8_LDA(At, 1, 0); PG8_STAGE(PG8_SA(0, 1), a2 + hstepA, voffA);
;             PG8_WAIT_V(8); PG8_WAIT_L(0); PG8_BAR; PG8_MMA(0, 0, At, B0); PG8_MMA(0, 1, At, B1); PG8_BAR; PG8_SCHED;
	s_setprio 1
	s_waitcnt lgkmcnt(0)
	v_mfma_f32_16x16x32_bf16 v[60:63], v[128:131], v[188:191], v[60:63]
	v_mfma_f32_16x16x32_bf16 v[56:59], v[146:149], v[188:191], v[56:59]
	v_mfma_f32_16x16x32_bf16 v[44:47], v[128:131], v[214:217], v[44:47]
	v_mfma_f32_16x16x32_bf16 v[40:43], v[146:149], v[214:217], v[40:43]
	v_mfma_f32_16x16x32_bf16 v[28:31], v[128:131], v[222:225], v[28:31]
	v_mfma_f32_16x16x32_bf16 v[24:27], v[146:149], v[222:225], v[24:27]
	v_mfma_f32_16x16x32_bf16 v[12:15], v[128:131], v[230:233], v[12:15]
	v_mfma_f32_16x16x32_bf16 v[8:11], v[146:149], v[230:233], v[8:11]
	v_mfma_f32_16x16x32_bf16 v[60:63], v[132:135], v[210:213], v[60:63]
	v_mfma_f32_16x16x32_bf16 v[56:59], v[164:167], v[210:213], v[56:59]
	v_mfma_f32_16x16x32_bf16 v[44:47], v[132:135], v[218:221], v[44:47]
	v_mfma_f32_16x16x32_bf16 v[40:43], v[164:167], v[218:221], v[40:43]
	v_mfma_f32_16x16x32_bf16 v[28:31], v[132:135], v[226:229], v[28:31]
	v_mfma_f32_16x16x32_bf16 v[24:27], v[164:167], v[226:229], v[24:27]
	v_mfma_f32_16x16x32_bf16 v[12:15], v[132:135], v[234:237], v[12:15]
	v_mfma_f32_16x16x32_bf16 v[8:11], v[164:167], v[234:237], v[8:11]
	s_setprio 0
	s_setprio 1
	v_mfma_f32_16x16x32_bf16 v[52:55], v[172:175], v[188:191], v[52:55]
	v_mfma_f32_16x16x32_bf16 v[48:51], v[180:183], v[188:191], v[48:51]
	v_mfma_f32_16x16x32_bf16 v[36:39], v[172:175], v[214:217], v[36:39]
	v_mfma_f32_16x16x32_bf16 v[32:35], v[180:183], v[214:217], v[32:35]
	v_mfma_f32_16x16x32_bf16 v[20:23], v[172:175], v[222:225], v[20:23]
	v_mfma_f32_16x16x32_bf16 v[16:19], v[180:183], v[222:225], v[16:19]
	v_mfma_f32_16x16x32_bf16 v[4:7], v[172:175], v[230:233], v[4:7]
	v_mfma_f32_16x16x32_bf16 v[0:3], v[180:183], v[230:233], v[0:3]
	v_mfma_f32_16x16x32_bf16 v[52:55], v[176:179], v[210:213], v[52:55]
	v_mfma_f32_16x16x32_bf16 v[48:51], v[184:187], v[210:213], v[48:51]
	v_mfma_f32_16x16x32_bf16 v[36:39], v[176:179], v[218:221], v[36:39]
	v_mfma_f32_16x16x32_bf16 v[32:35], v[184:187], v[218:221], v[32:35]
	v_mfma_f32_16x16x32_bf16 v[20:23], v[176:179], v[226:229], v[20:23]
	v_mfma_f32_16x16x32_bf16 v[16:19], v[184:187], v[226:229], v[16:19]
	v_mfma_f32_16x16x32_bf16 v[4:7], v[176:179], v[234:237], v[4:7]
	v_mfma_f32_16x16x32_bf16 v[0:3], v[184:187], v[234:237], v[0:3]
	s_setprio 0
	s_barrier
	s_add_i32 s66, 0, 0x18000
	s_add_i32 s67, 0, 0x1c000
	v_add_u32_e32 v164, s66, v169
	v_add_u32_e32 v171, s67, v169
	ds_read_b128 v[128:131], v164
	ds_read_b128 v[132:135], v164 offset:1024
	ds_read_b128 v[146:149], v164 offset:2048
	ds_read_b128 v[164:167], v164 offset:3072
	ds_read_b128 v[172:175], v171
	ds_read_b128 v[176:179], v171 offset:1024
	ds_read_b128 v[180:183], v171 offset:2048
	ds_read_b128 v[184:187], v171 offset:3072
	s_add_u32 s8, s58, 0x20000
	s_addc_u32 s9, s59, 0
	s_mov_b32 m0, s53
	v_lshl_add_u64 v[238:239], s[8:9], 0, v[136:137]
	ds_read_b128 v[188:191], v170 offset:32768
	ds_read_b128 v[210:213], v170 offset:33792
	ds_read_b128 v[214:217], v170 offset:34816
	ds_read_b128 v[218:221], v170 offset:35840
	ds_read_b128 v[222:225], v170 offset:36864
	ds_read_b128 v[226:229], v170 offset:37888
	ds_read_b128 v[230:233], v170 offset:38912
	ds_read_b128 v[234:237], v170 offset:39936
	global_load_lds_dwordx4 v[238:239], off
	v_lshl_add_u64 v[238:239], s[8:9], 0, v[138:139]
	s_mov_b32 m0, s60
	s_nop 0
	global_load_lds_dwordx4 v[238:239], off
	s_waitcnt vmcnt(8)
	s_waitcnt lgkmcnt(0)
	s_barrier
	s_setprio 1
	s_waitcnt lgkmcnt(0)
	v_mfma_f32_16x16x32_bf16 v[124:127], v[128:131], v[188:191], v[124:127]
	v_mfma_f32_16x16x32_bf16 v[120:123], v[146:149], v[188:191], v[120:123]
	v_mfma_f32_16x16x32_bf16 v[108:111], v[128:131], v[214:217], v[108:111]
	v_mfma_f32_16x16x32_bf16 v[104:107], v[146:149], v[214:217], v[104:107]
	v_mfma_f32_16x16x32_bf16 v[92:95], v[128:131], v[222:225], v[92:95]
	v_mfma_f32_16x16x32_bf16 v[88:91], v[146:149], v[222:225], v[88:91]
	v_mfma_f32_16x16x32_bf16 v[76:79], v[128:131], v[230:233], v[76:79]
	v_mfma_f32_16x16x32_bf16 v[72:75], v[146:149], v[230:233], v[72:75]
	v_mfma_f32_16x16x32_bf16 v[124:127], v[132:135], v[210:213], v[124:127]
	v_mfma_f32_16x16x32_bf16 v[120:123], v[164:167], v[210:213], v[120:123]
	v_mfma_f32_16x16x32_bf16 v[108:111], v[132:135], v[218:221], v[108:111]
	v_mfma_f32_16x16x32_bf16 v[104:107], v[164:167], v[218:221], v[104:107]
	v_mfma_f32_16x16x32_bf16 v[92:95], v[132:135], v[226:229], v[92:95]
	v_mfma_f32_16x16x32_bf16 v[88:91], v[164:167], v[226:229], v[88:91]
	v_mfma_f32_16x16x32_bf16 v[76:79], v[132:135], v[234:237], v[76:79]
	v_mfma_f32_16x16x32_bf16 v[72:75], v[164:167], v[234:237], v[72:75]
	s_setprio 0
	s_setprio 1
	v_mfma_f32_16x16x32_bf16 v[116:119], v[172:175], v[188:191], v[116:119]
	v_mfma_f32_16x16x32_bf16 v[112:115], v[180:183], v[188:191], v[112:115]
	v_mfma_f32_16x16x32_bf16 v[100:103], v[172:175], v[214:217], v[100:103]
	v_mfma_f32_16x16x32_bf16 v[96:99], v[180:183], v[214:217], v[96:99]
	v_mfma_f32_16x16x32_bf16 v[84:87], v[172:175], v[222:225], v[84:87]
	v_mfma_f32_16x16x32_bf16 v[80:83], v[180:183], v[222:225], v[80:83]
	v_mfma_f32_16x16x32_bf16 v[68:71], v[172:175], v[230:233], v[68:71]
	v_mfma_f32_16x16x32_bf16 v[64:67], v[180:183], v[230:233], v[64:67]
	v_mfma_f32_16x16x32_bf16 v[116:119], v[176:179], v[210:213], v[116:119]
	v_mfma_f32_16x16x32_bf16 v[112:115], v[184:187], v[210:213], v[112:115]
	v_mfma_f32_16x16x32_bf16 v[100:103], v[176:179], v[218:221], v[100:103]
	v_mfma_f32_16x16x32_bf16 v[96:99], v[184:187], v[218:221], v[96:99]
	v_mfma_f32_16x16x32_bf16 v[84:87], v[176:179], v[226:229], v[84:87]
	v_mfma_f32_16x16x32_bf16 v[80:83], v[184:187], v[226:229], v[80:83]
	v_mfma_f32_16x16x32_bf16 v[68:71], v[176:179], v[234:237], v[68:71]
	v_mfma_f32_16x16x32_bf16 v[64:67], v[184:187], v[234:237], v[64:67]
	s_setprio 0
	s_barrier
; #define PG8_STAGE(bufoff, gbase, voff) do { _Pragma("unroll") for (int _i = 0; _i < 2; ++_i) \
;         __builtin_amdgcn_global_load_lds((const unsigned*)((const char*)(gbase) + (voff)[_i]), (LAS unsigned*)(lds + (bufoff) + ldsw + _i * 8192), 16, 0, 0); } while (0)
; #define PG8_LDA(dst, b, h) do { _Pragma("unroll") for (int m = 0; m < 4; ++m) _Pragma("unroll") for (int k = 0; k < 2; ++k) dst[m][k] = *(const LAS bf16x8*)(lds + PG8_SA(b, h) + aoff + m * 2048 + k * 1024); } while (0)
; #define PG8_MMA(ai, bj, At, Bt) do { __builtin_amdgcn_s_setprio(1); _Pragma("unroll") for (int m = 0; m < 4; ++m) _Pragma("unroll") for (int n = 0; n < 2; ++n) _Pragma("unroll") for (int k = 0; k < 2; ++k) \
;         acc[ai][bj][m][n] = __builtin_amdgcn_mfma_f32_16x16x32_bf16(Bt[n][k], At[m][k], acc[ai][bj][m][n], 0, 0, 0); __builtin_amdgcn_s_setprio(0); } while (0)
; #define PG8_WAIT_V(n) asm volatile("s_waitcnt vmcnt(" #n ")" ::: "memory")
; #define PG8_WAIT_L(n) asm volatile("s_waitcnt lgkmcnt(" #n ")" ::: "memory")
; #define PG8_BAR __builtin_amdgcn_s_barrier()
; #define PG8_SCHED __builtin_amdgcn_sched_barrier(0)
; template <class Epi>
; __device__ __forceinline__ void gemm_phase(LAS unsigned char* lds, const Gemm g, const int G, const int cidx, const int tid, const Epi& E) {
;     ...
;         for (int t = 0; t < nt; t += 2) {
;     ...
;             PG8_LDA(At, 1, 1); PG8_STAGE(PG8_SB(1, 0), b3, voffB); PG8_STAGE(PG8_SB(1, 1), b3 + hstepB, voffB); PG8_STAGE(PG8_SA(1, 0), a3, voffA);
;             PG8_WAIT_V(8); PG8_WAIT_L(0); PG8_BAR; PG8_MMA(1, 0, At, B0); PG8_MMA(1, 1, At, B1); PG8_BAR; PG8_SCHED;
	s_add_i32 s8, s66, s25
	v_lshl_add_u64 v[150:151], v[150:151], 0, s[96:97]
	s_mov_b32 m0, s8
	ds_read_b128 v[188:191], v170 offset:49152
	ds_read_b128 v[210:213], v170 offset:50176
	ds_read_b128 v[214:217], v170 offset:51200
	ds_read_b128 v[218:221], v170 offset:52224
	ds_read_b128 v[222:225], v170 offset:53248
	ds_read_b128 v[226:229], v170 offset:54272
	ds_read_b128 v[230:233], v170 offset:55296
	ds_read_b128 v[234:237], v170 offset:56320
	global_load_lds_dwordx4 v[150:151], off
	s_add_i32 m0, s8, 0x2000
	s_add_u32 s8, s56, 0x20080
	v_lshl_add_u64 v[150:151], v[158:159], 0, s[96:97]
	s_addc_u32 s9, s57, 0
	s_add_i32 s56, s67, s25
	global_load_lds_dwordx4 v[150:151], off
	v_lshl_add_u64 v[150:151], s[8:9], 0, v[152:153]
	s_mov_b32 m0, s56
	s_nop 0
	global_load_lds_dwordx4 v[150:151], off
	v_lshl_add_u64 v[150:151], s[8:9], 0, v[140:141]
	s_add_i32 m0, s56, 0x2000
	s_nop 0
	global_load_lds_dwordx4 v[150:151], off
	v_lshl_add_u64 v[150:151], v[192:193], 0, s[96:97]
	s_mov_b32 m0, s63
	s_nop 0
	global_load_lds_dwordx4 v[150:151], off
	v_lshl_add_u64 v[150:151], v[208:209], 0, s[96:97]
	s_mov_b32 m0, s64
	s_nop 0
	global_load_lds_dwordx4 v[150:151], off
	s_waitcnt vmcnt(8)
	s_waitcnt lgkmcnt(0)
	s_barrier
	s_setprio 1
	s_waitcnt lgkmcnt(0)
	v_mfma_f32_16x16x32_bf16 v[60:63], v[128:131], v[188:191], v[60:63]
	v_mfma_f32_16x16x32_bf16 v[56:59], v[146:149], v[188:191], v[56:59]
	v_mfma_f32_16x16x32_bf16 v[44:47], v[128:131], v[214:217], v[44:47]
	v_mfma_f32_16x16x32_bf16 v[40:43], v[146:149], v[214:217], v[40:43]
	v_mfma_f32_16x16x32_bf16 v[28:31], v[128:131], v[222:225], v[28:31]
	v_mfma_f32_16x16x32_bf16 v[24:27], v[146:149], v[222:225], v[24:27]
	v_mfma_f32_16x16x32_bf16 v[12:15], v[128:131], v[230:233], v[12:15]
	v_mfma_f32_16x16x32_bf16 v[8:11], v[146:149], v[230:233], v[8:11]
	v_mfma_f32_16x16x32_bf16 v[60:63], v[132:135], v[210:213], v[60:63]
	v_mfma_f32_16x16x32_bf16 v[56:59], v[164:167], v[210:213], v[56:59]
	v_mfma_f32_16x16x32_bf16 v[44:47], v[132:135], v[218:221], v[44:47]
	v_mfma_f32_16x16x32_bf16 v[40:43], v[164:167], v[218:221], v[40:43]
	v_mfma_f32_16x16x32_bf16 v[28:31], v[132:135], v[226:229], v[28:31]
	v_mfma_f32_16x16x32_bf16 v[24:27], v[164:167], v[226:229], v[24:27]
	v_mfma_f32_16x16x32_bf16 v[12:15], v[132:135], v[234:237], v[12:15]
	v_mfma_f32_16x16x32_bf16 v[8:11], v[164:167], v[234:237], v[8:11]
	s_setprio 0
	s_setprio 1
	v_mfma_f32_16x16x32_bf16 v[52:55], v[172:175], v[188:191], v[52:55]
	v_mfma_f32_16x16x32_bf16 v[48:51], v[180:183], v[188:191], v[48:51]
	v_mfma_f32_16x16x32_bf16 v[36:39], v[172:175], v[214:217], v[36:39]
	v_mfma_f32_16x16x32_bf16 v[32:35], v[180:183], v[214:217], v[32:35]
	v_mfma_f32_16x16x32_bf16 v[20:23], v[172:175], v[222:225], v[20:23]
	v_mfma_f32_16x16x32_bf16 v[16:19], v[180:183], v[222:225], v[16:19]
	v_mfma_f32_16x16x32_bf16 v[4:7], v[172:175], v[230:233], v[4:7]
	v_mfma_f32_16x16x32_bf16 v[0:3], v[180:183], v[230:233], v[0:3]
	v_mfma_f32_16x16x32_bf16 v[52:55], v[176:179], v[210:213], v[52:55]
	v_mfma_f32_16x16x32_bf16 v[48:51], v[184:187], v[210:213], v[48:51]
	v_mfma_f32_16x16x32_bf16 v[36:39], v[176:179], v[218:221], v[36:39]
	v_mfma_f32_16x16x32_bf16 v[32:35], v[184:187], v[218:221], v[32:35]
	v_mfma_f32_16x16x32_bf16 v[20:23], v[176:179], v[226:229], v[20:23]
	v_mfma_f32_16x16x32_bf16 v[16:19], v[184:187], v[226:229], v[16:19]
	v_mfma_f32_16x16x32_bf16 v[4:7], v[176:179], v[234:237], v[4:7]
	v_mfma_f32_16x16x32_bf16 v[0:3], v[184:187], v[234:237], v[0:3]
	s_setprio 0
	s_add_i32 vcc_lo, vcc_lo, 2
	s_add_u32 s54, s54, 0x100
	s_addc_u32 s55, s55, 0
	s_add_u32 s94, s94, 0x100
	s_addc_u32 s95, s95, 0
	s_barrier
	s_cmp_gt_u32 vcc_lo, 5
	s_cbranch_scc0 .LBB0_232
	s_and_b64 vcc, exec, s[10:11]
	v_readlane_b32 s94, v255, 3
	v_readlane_b32 s92, v255, 5
	v_readlane_b32 s95, v255, 4
	s_cbranch_vccz .LBB0_235
	s_barrier

; #define PG8_STAGE(bufoff, gbase, voff) do { _Pragma("unroll") for (int _i = 0; _i < 2; ++_i) \
;         __builtin_amdgcn_global_load_lds((const unsigned*)((const char*)(gbase) + (voff)[_i]), (LAS unsigned*)(lds + (bufoff) + ldsw + _i * 8192), 16, 0, 0); } while (0)
; #define PG8_LDA(dst, b, h) do { _Pragma("unroll") for (int m = 0; m < 4; ++m) _Pragma("unroll") for (int k = 0; k < 2; ++k) dst[m][k] = *(const LAS bf16x8*)(lds + PG8_SA(b, h) + aoff + m * 2048 + k * 1024); } while (0)
; #define PG8_LDB(dst, b, h) do { _Pragma("unroll") for (int n = 0; n < 2; ++n) _Pragma("unroll") for (int k = 0; k < 2; ++k) dst[n][k] = *(const LAS bf16x8*)(lds + PG8_SB(b, h) + boff + n * 2048 + k * 1024); } while (0)
; #define PG8_MMA(ai, bj, At, Bt) do { __builtin_amdgcn_s_setprio(1); _Pragma("unroll") for (int m = 0; m < 4; ++m) _Pragma("unroll") for (int n = 0; n < 2; ++n) _Pragma("unroll") for (int k = 0; k < 2; ++k) \
;         acc[ai][bj][m][n] = __builtin_amdgcn_mfma_f32_16x16x32_bf16(Bt[n][k], At[m][k], acc[ai][bj][m][n], 0, 0, 0); __builtin_amdgcn_s_setprio(0); } while (0)
; #define PG8_WAIT_V(n) asm volatile("s_waitcnt vmcnt(" #n ")" ::: "memory")
; #define PG8_WAIT_L(n) asm volatile("s_waitcnt lgkmcnt(" #n ")" ::: "memory")
; #define PG8_BAR __builtin_amdgcn_s_barrier()
; #define PG8_SCHED __builtin_amdgcn_sched_barrier(0)
; template <class Epi>
; __device__ __forceinline__ void gemm_phase(LAS unsigned char* lds, const Gemm g, const int G, const int cidx, const int tid, const Epi& E) {
;     ...
;             const bool last = (t == nt - 2);
;             const char* a1 = cA + (size_t)(t + 1) * kstep;
;             const char* a2 = last ? nA : cA + (size_t)(t + 2) * kstep; const char* b2 = last ? nB : cB + (size_t)(t + 2) * kstep;
;             const char* a3 = a2 + kstep; const char* b3 = b2 + kstep;
;             PG8_LDB(B0, 0, 0); PG8_LDB(B1, 0, 1); PG8_SCHED; PG8_LDA(At, 0, 0); PG8_STAGE(PG8_SA(1, 1), a1 + hstepA, voffA);
;             PG8_WAIT_V(8); PG8_WAIT_L(0); PG8_BAR; PG8_MMA(0, 0, At, B0); PG8_MMA(0, 1, At, B1); PG8_BAR; PG8_SCHED;
;             PG8_LDA(At, 0, 1); PG8_STAGE(PG8_SB(0, 0), b2, voffB); PG8_STAGE(PG8_SB(0, 1), b2 + hstepB, voffB); PG8_STAGE(PG8_SA(0, 0), a2, voffA);
.LBB0_264:
	s_add_u32 s8, s6, 0x100
	s_addc_u32 s9, s7, 0
	s_add_i32 s18, 0, 0x10000
	s_cmp_eq_u32 s17, 2
	s_cselect_b32 s13, s57, s9
	s_cselect_b32 s12, s56, s8
	s_cselect_b32 s11, s59, s16
	s_cselect_b32 s10, s58, s15
	s_add_i32 s19, 0, 0x14000
	v_add_u32_e32 v140, s18, v183
	v_add_u32_e32 v152, s19, v183
	ds_read_b128 v[104:107], v140
	ds_read_b128 v[108:111], v140 offset:1024
	ds_read_b128 v[136:139], v140 offset:2048
	ds_read_b128 v[140:143], v140 offset:3072
	ds_read_b128 v[144:147], v152
	ds_read_b128 v[148:151], v152 offset:1024
	ds_read_b128 v[176:179], v152 offset:2048
	ds_read_b128 v[186:189], v152 offset:3072
	v_lshl_add_u64 v[180:181], s[6:7], 0, v[172:173]
	s_add_i32 m0, s31, 0xc000
	ds_read_b128 v[190:193], v184
	ds_read_b128 v[210:213], v184 offset:1024
	ds_read_b128 v[214:217], v184 offset:2048
	ds_read_b128 v[218:221], v184 offset:3072
	ds_read_b128 v[222:225], v184 offset:4096
	ds_read_b128 v[226:229], v184 offset:5120
	ds_read_b128 v[230:233], v184 offset:6144
	ds_read_b128 v[234:237], v184 offset:7168
	global_load_lds_dwordx4 v[180:181], off
	v_lshl_add_u64 v[180:181], s[6:7], 0, v[174:175]
	s_add_i32 m0, s31, 0xe000
	s_nop 0
	global_load_lds_dwordx4 v[180:181], off
	s_waitcnt vmcnt(8)
	s_waitcnt lgkmcnt(0)
	s_barrier
	s_setprio 1
	s_waitcnt lgkmcnt(0)
	v_mfma_f32_16x16x32_bf16 v[132:135], v[104:107], v[190:193], v[132:135]
	v_mfma_f32_16x16x32_bf16 v[128:131], v[136:139], v[190:193], v[128:131]
	v_mfma_f32_16x16x32_bf16 v[124:127], v[104:107], v[214:217], v[124:127]
	v_mfma_f32_16x16x32_bf16 v[120:123], v[136:139], v[214:217], v[120:123]
	v_mfma_f32_16x16x32_bf16 v[116:119], v[104:107], v[222:225], v[116:119]
	v_mfma_f32_16x16x32_bf16 v[112:115], v[136:139], v[222:225], v[112:115]
	v_mfma_f32_16x16x32_bf16 v[100:103], v[104:107], v[230:233], v[100:103]
	v_mfma_f32_16x16x32_bf16 v[96:99], v[136:139], v[230:233], v[96:99]
	v_mfma_f32_16x16x32_bf16 v[132:135], v[108:111], v[210:213], v[132:135]
	v_mfma_f32_16x16x32_bf16 v[128:131], v[140:143], v[210:213], v[128:131]
	v_mfma_f32_16x16x32_bf16 v[124:127], v[108:111], v[218:221], v[124:127]
	v_mfma_f32_16x16x32_bf16 v[120:123], v[140:143], v[218:221], v[120:123]
	v_mfma_f32_16x16x32_bf16 v[116:119], v[108:111], v[226:229], v[116:119]
	v_mfma_f32_16x16x32_bf16 v[112:115], v[140:143], v[226:229], v[112:115]
	v_mfma_f32_16x16x32_bf16 v[100:103], v[108:111], v[234:237], v[100:103]
	v_mfma_f32_16x16x32_bf16 v[96:99], v[140:143], v[234:237], v[96:99]
	s_setprio 0
	s_setprio 1
	v_mfma_f32_16x16x32_bf16 v[60:63], v[144:147], v[190:193], v[60:63]
	v_mfma_f32_16x16x32_bf16 v[56:59], v[176:179], v[190:193], v[56:59]
	v_mfma_f32_16x16x32_bf16 v[52:55], v[144:147], v[214:217], v[52:55]
	v_mfma_f32_16x16x32_bf16 v[48:51], v[176:179], v[214:217], v[48:51]
	v_mfma_f32_16x16x32_bf16 v[44:47], v[144:147], v[222:225], v[44:47]
	v_mfma_f32_16x16x32_bf16 v[40:43], v[176:179], v[222:225], v[40:43]
	v_mfma_f32_16x16x32_bf16 v[36:39], v[144:147], v[230:233], v[36:39]
	v_mfma_f32_16x16x32_bf16 v[32:35], v[176:179], v[230:233], v[32:35]
	v_mfma_f32_16x16x32_bf16 v[60:63], v[148:151], v[210:213], v[60:63]
	v_mfma_f32_16x16x32_bf16 v[56:59], v[186:189], v[210:213], v[56:59]
	v_mfma_f32_16x16x32_bf16 v[52:55], v[148:151], v[218:221], v[52:55]
	v_mfma_f32_16x16x32_bf16 v[48:51], v[186:189], v[218:221], v[48:51]
	v_mfma_f32_16x16x32_bf16 v[44:47], v[148:151], v[226:229], v[44:47]
	v_mfma_f32_16x16x32_bf16 v[40:43], v[186:189], v[226:229], v[40:43]
	v_mfma_f32_16x16x32_bf16 v[36:39], v[148:151], v[234:237], v[36:39]
	v_mfma_f32_16x16x32_bf16 v[32:35], v[186:189], v[234:237], v[32:35]
	s_setprio 0
	s_barrier
	s_add_i32 s6, s18, s21
	v_lshl_add_u64 v[180:181], s[10:11], 0, v[166:167]
	s_mov_b32 m0, s6
	ds_read_b128 v[190:193], v184 offset:16384
	ds_read_b128 v[210:213], v184 offset:17408
	ds_read_b128 v[214:217], v184 offset:18432
	ds_read_b128 v[218:221], v184 offset:19456
	ds_read_b128 v[222:225], v184 offset:20480
	ds_read_b128 v[226:229], v184 offset:21504
	ds_read_b128 v[230:233], v184 offset:22528
	ds_read_b128 v[234:237], v184 offset:23552
	global_load_lds_dwordx4 v[180:181], off
	s_add_i32 m0, s6, 0x2000
	s_add_u32 s6, s10, 0x18000
	v_lshl_add_u64 v[238:239], s[10:11], 0, v[170:171]
	s_addc_u32 s7, s11, 0
	s_add_i32 s18, s19, s21
	global_load_lds_dwordx4 v[238:239], off
	v_lshl_add_u64 v[240:241], s[6:7], 0, v[166:167]
	s_mov_b32 m0, s18
	v_lshl_add_u64 v[242:243], s[12:13], 0, v[168:169]
	global_load_lds_dwordx4 v[240:241], off
	v_lshl_add_u64 v[240:241], s[6:7], 0, v[170:171]
	s_add_i32 m0, s18, 0x2000
	s_nop 0
	global_load_lds_dwordx4 v[240:241], off
	v_lshl_add_u64 v[240:241], s[12:13], 0, v[164:165]
	s_mov_b32 m0, s31
	s_nop 0
	global_load_lds_dwordx4 v[240:241], off
	s_mov_b32 m0, s20
	s_nop 0
	global_load_lds_dwordx4 v[242:243], off
	s_waitcnt vmcnt(8)
	s_waitcnt lgkmcnt(0)
	s_barrier
; #define PG8_STAGE(bufoff, gbase, voff) do { _Pragma("unroll") for (int _i = 0; _i < 2; ++_i) \
;         __builtin_amdgcn_global_load_lds((const unsigned*)((const char*)(gbase) + (voff)[_i]), (LAS unsigned*)(lds + (bufoff) + ldsw + _i * 8192), 16, 0, 0); } while (0)
; #define PG8_LDA(dst, b, h) do { _Pragma("unroll") for (int m = 0; m < 4; ++m) _Pragma("unroll") for (int k = 0; k < 2; ++k) dst[m][k] = *(const LAS bf16x8*)(lds + PG8_SA(b, h) + aoff + m * 2048 + k * 1024); } while (0)
; #define PG8_LDB(dst, b, h) do { _Pragma("unroll") for (int n = 0; n < 2; ++n) _Pragma("unroll") for (int k = 0; k < 2; ++k) dst[n][k] = *(const LAS bf16x8*)(lds + PG8_SB(b, h) + boff + n * 2048 + k * 1024); } while (0)
; #define PG8_MMA(ai, bj, At, Bt) do { __builtin_amdgcn_s_setprio(1); _Pragma("unroll") for (int m = 0; m < 4; ++m) _Pragma("unroll") for (int n = 0; n < 2; ++n) _Pragma("unroll") for (int k = 0; k < 2; ++k) \
;         acc[ai][bj][m][n] = __builtin_amdgcn_mfma_f32_16x16x32_bf16(Bt[n][k], At[m][k], acc[ai][bj][m][n], 0, 0, 0); __builtin_amdgcn_s_setprio(0); } while (0)
; #define PG8_WAIT_V(n) asm volatile("s_waitcnt vmcnt(" #n ")" ::: "memory")
; #define PG8_WAIT_L(n) asm volatile("s_waitcnt lgkmcnt(" #n ")" ::: "memory")
; #define PG8_BAR __builtin_amdgcn_s_barrier()
; #define PG8_SCHED __builtin_amdgcn_sched_barrier(0)
; template <class Epi>
; __device__ __forceinline__ void gemm_phase(LAS unsigned char* lds, const Gemm g, const int G, const int cidx, const int tid, const Epi& E) {
;     ...
;             PG8_WAIT_V(8); PG8_WAIT_L(0); PG8_BAR; PG8_MMA(1, 0, At, B0); PG8_MMA(1, 1, At, B1); PG8_BAR; PG8_SCHED;
;             PG8_LDB(B0, 1, 0); PG8_LDB(B1, 1, 1); PG8_SCHED; PG8_LDA(At, 1, 0); PG8_STAGE(PG8_SA(0, 1), a2 + hstepA, voffA);
;             PG8_WAIT_V(8); PG8_WAIT_L(0); PG8_BAR; PG8_MMA(0, 0, At, B0); PG8_MMA(0, 1, At, B1); PG8_BAR; PG8_SCHED;
	s_setprio 1
	s_waitcnt lgkmcnt(0)
	v_mfma_f32_16x16x32_bf16 v[92:95], v[104:107], v[190:193], v[92:95]
	v_mfma_f32_16x16x32_bf16 v[88:91], v[136:139], v[190:193], v[88:91]
	v_mfma_f32_16x16x32_bf16 v[84:87], v[104:107], v[214:217], v[84:87]
	v_mfma_f32_16x16x32_bf16 v[80:83], v[136:139], v[214:217], v[80:83]
	v_mfma_f32_16x16x32_bf16 v[76:79], v[104:107], v[222:225], v[76:79]
	v_mfma_f32_16x16x32_bf16 v[72:75], v[136:139], v[222:225], v[72:75]
	v_mfma_f32_16x16x32_bf16 v[68:71], v[104:107], v[230:233], v[68:71]
	v_mfma_f32_16x16x32_bf16 v[64:67], v[136:139], v[230:233], v[64:67]
	v_mfma_f32_16x16x32_bf16 v[92:95], v[108:111], v[210:213], v[92:95]
	v_mfma_f32_16x16x32_bf16 v[88:91], v[140:143], v[210:213], v[88:91]
	v_mfma_f32_16x16x32_bf16 v[84:87], v[108:111], v[218:221], v[84:87]
	v_mfma_f32_16x16x32_bf16 v[80:83], v[140:143], v[218:221], v[80:83]
	v_mfma_f32_16x16x32_bf16 v[76:79], v[108:111], v[226:229], v[76:79]
	v_mfma_f32_16x16x32_bf16 v[72:75], v[140:143], v[226:229], v[72:75]
	v_mfma_f32_16x16x32_bf16 v[68:71], v[108:111], v[234:237], v[68:71]
	v_mfma_f32_16x16x32_bf16 v[64:67], v[140:143], v[234:237], v[64:67]
	s_setprio 0
	s_setprio 1
	v_mfma_f32_16x16x32_bf16 v[28:31], v[144:147], v[190:193], v[28:31]
	v_mfma_f32_16x16x32_bf16 v[24:27], v[176:179], v[190:193], v[24:27]
	v_mfma_f32_16x16x32_bf16 v[20:23], v[144:147], v[214:217], v[20:23]
	v_mfma_f32_16x16x32_bf16 v[16:19], v[176:179], v[214:217], v[16:19]
	v_mfma_f32_16x16x32_bf16 v[12:15], v[144:147], v[222:225], v[12:15]
	v_mfma_f32_16x16x32_bf16 v[8:11], v[176:179], v[222:225], v[8:11]
	v_mfma_f32_16x16x32_bf16 v[4:7], v[144:147], v[230:233], v[4:7]
	v_mfma_f32_16x16x32_bf16 v[0:3], v[176:179], v[230:233], v[0:3]
	v_mfma_f32_16x16x32_bf16 v[28:31], v[148:151], v[210:213], v[28:31]
	v_mfma_f32_16x16x32_bf16 v[24:27], v[186:189], v[210:213], v[24:27]
	v_mfma_f32_16x16x32_bf16 v[20:23], v[148:151], v[218:221], v[20:23]
	v_mfma_f32_16x16x32_bf16 v[16:19], v[186:189], v[218:221], v[16:19]
	v_mfma_f32_16x16x32_bf16 v[12:15], v[148:151], v[226:229], v[12:15]
	v_mfma_f32_16x16x32_bf16 v[8:11], v[186:189], v[226:229], v[8:11]
	v_mfma_f32_16x16x32_bf16 v[4:7], v[148:151], v[234:237], v[4:7]
	v_mfma_f32_16x16x32_bf16 v[0:3], v[186:189], v[234:237], v[0:3]
	s_setprio 0
	s_barrier
	s_add_i32 s18, 0, 0x18000
	s_add_i32 s19, 0, 0x1c000
	v_add_u32_e32 v140, s18, v183
	v_add_u32_e32 v152, s19, v183
	ds_read_b128 v[104:107], v140
	ds_read_b128 v[108:111], v140 offset:1024
	ds_read_b128 v[136:139], v140 offset:2048
	ds_read_b128 v[140:143], v140 offset:3072
	ds_read_b128 v[144:147], v152
	ds_read_b128 v[148:151], v152 offset:1024
	ds_read_b128 v[176:179], v152 offset:2048
	ds_read_b128 v[186:189], v152 offset:3072
	s_add_u32 s6, s12, 0x30000
	s_addc_u32 s7, s13, 0
	s_mov_b32 m0, s52
	v_lshl_add_u64 v[244:245], s[6:7], 0, v[164:165]
	ds_read_b128 v[190:193], v184 offset:32768
	ds_read_b128 v[210:213], v184 offset:33792
	ds_read_b128 v[214:217], v184 offset:34816
	ds_read_b128 v[218:221], v184 offset:35840
	ds_read_b128 v[222:225], v184 offset:36864
	ds_read_b128 v[226:229], v184 offset:37888
	ds_read_b128 v[230:233], v184 offset:38912
	ds_read_b128 v[234:237], v184 offset:39936
	global_load_lds_dwordx4 v[244:245], off
	v_lshl_add_u64 v[244:245], s[6:7], 0, v[168:169]
	s_mov_b32 m0, s53
	s_nop 0
	global_load_lds_dwordx4 v[244:245], off
	s_waitcnt vmcnt(8)
	s_waitcnt lgkmcnt(0)
	s_barrier
	s_setprio 1
	s_waitcnt lgkmcnt(0)
	v_mfma_f32_16x16x32_bf16 v[132:135], v[104:107], v[190:193], v[132:135]
	v_mfma_f32_16x16x32_bf16 v[128:131], v[136:139], v[190:193], v[128:131]
	v_mfma_f32_16x16x32_bf16 v[124:127], v[104:107], v[214:217], v[124:127]
	v_mfma_f32_16x16x32_bf16 v[120:123], v[136:139], v[214:217], v[120:123]
	v_mfma_f32_16x16x32_bf16 v[116:119], v[104:107], v[222:225], v[116:119]
	v_mfma_f32_16x16x32_bf16 v[112:115], v[136:139], v[222:225], v[112:115]
	v_mfma_f32_16x16x32_bf16 v[100:103], v[104:107], v[230:233], v[100:103]
	v_mfma_f32_16x16x32_bf16 v[96:99], v[136:139], v[230:233], v[96:99]
	v_mfma_f32_16x16x32_bf16 v[132:135], v[108:111], v[210:213], v[132:135]
	v_mfma_f32_16x16x32_bf16 v[128:131], v[140:143], v[210:213], v[128:131]
	v_mfma_f32_16x16x32_bf16 v[124:127], v[108:111], v[218:221], v[124:127]
	v_mfma_f32_16x16x32_bf16 v[120:123], v[140:143], v[218:221], v[120:123]
	v_mfma_f32_16x16x32_bf16 v[116:119], v[108:111], v[226:229], v[116:119]
	v_mfma_f32_16x16x32_bf16 v[112:115], v[140:143], v[226:229], v[112:115]
	v_mfma_f32_16x16x32_bf16 v[100:103], v[108:111], v[234:237], v[100:103]
	v_mfma_f32_16x16x32_bf16 v[96:99], v[140:143], v[234:237], v[96:99]
	s_setprio 0
	s_setprio 1
	v_mfma_f32_16x16x32_bf16 v[60:63], v[144:147], v[190:193], v[60:63]
	v_mfma_f32_16x16x32_bf16 v[56:59], v[176:179], v[190:193], v[56:59]
	v_mfma_f32_16x16x32_bf16 v[52:55], v[144:147], v[214:217], v[52:55]
	v_mfma_f32_16x16x32_bf16 v[48:51], v[176:179], v[214:217], v[48:51]
	v_mfma_f32_16x16x32_bf16 v[44:47], v[144:147], v[222:225], v[44:47]
	v_mfma_f32_16x16x32_bf16 v[40:43], v[176:179], v[222:225], v[40:43]
	v_mfma_f32_16x16x32_bf16 v[36:39], v[144:147], v[230:233], v[36:39]
	v_mfma_f32_16x16x32_bf16 v[32:35], v[176:179], v[230:233], v[32:35]
	v_mfma_f32_16x16x32_bf16 v[60:63], v[148:151], v[210:213], v[60:63]
	v_mfma_f32_16x16x32_bf16 v[56:59], v[186:189], v[210:213], v[56:59]
	v_mfma_f32_16x16x32_bf16 v[52:55], v[148:151], v[218:221], v[52:55]
	v_mfma_f32_16x16x32_bf16 v[48:51], v[186:189], v[218:221], v[48:51]
	v_mfma_f32_16x16x32_bf16 v[44:47], v[148:151], v[226:229], v[44:47]
	v_mfma_f32_16x16x32_bf16 v[40:43], v[186:189], v[226:229], v[40:43]
	v_mfma_f32_16x16x32_bf16 v[36:39], v[148:151], v[234:237], v[36:39]
	v_mfma_f32_16x16x32_bf16 v[32:35], v[186:189], v[234:237], v[32:35]
	s_setprio 0
	s_barrier
; #define PG8_STAGE(bufoff, gbase, voff) do { _Pragma("unroll") for (int _i = 0; _i < 2; ++_i) \
;         __builtin_amdgcn_global_load_lds((const unsigned*)((const char*)(gbase) + (voff)[_i]), (LAS unsigned*)(lds + (bufoff) + ldsw + _i * 8192), 16, 0, 0); } while (0)
; #define PG8_LDA(dst, b, h) do { _Pragma("unroll") for (int m = 0; m < 4; ++m) _Pragma("unroll") for (int k = 0; k < 2; ++k) dst[m][k] = *(const LAS bf16x8*)(lds + PG8_SA(b, h) + aoff + m * 2048 + k * 1024); } while (0)
; #define PG8_MMA(ai, bj, At, Bt) do { __builtin_amdgcn_s_setprio(1); _Pragma("unroll") for (int m = 0; m < 4; ++m) _Pragma("unroll") for (int n = 0; n < 2; ++n) _Pragma("unroll") for (int k = 0; k < 2; ++k) \
;         acc[ai][bj][m][n] = __builtin_amdgcn_mfma_f32_16x16x32_bf16(Bt[n][k], At[m][k], acc[ai][bj][m][n], 0, 0, 0); __builtin_amdgcn_s_setprio(0); } while (0)
; #define PG8_WAIT_V(n) asm volatile("s_waitcnt vmcnt(" #n ")" ::: "memory")
; #define PG8_WAIT_L(n) asm volatile("s_waitcnt lgkmcnt(" #n ")" ::: "memory")
; #define PG8_BAR __builtin_amdgcn_s_barrier()
; #define PG8_SCHED __builtin_amdgcn_sched_barrier(0)
; template <class Epi>
; __device__ __forceinline__ void gemm_phase(LAS unsigned char* lds, const Gemm g, const int G, const int cidx, const int tid, const Epi& E) {
;     ...
;         for (int t = 0; t < nt; t += 2) {
;     ...
;             PG8_LDA(At, 1, 1); PG8_STAGE(PG8_SB(1, 0), b3, voffB); PG8_STAGE(PG8_SB(1, 1), b3 + hstepB, voffB); PG8_STAGE(PG8_SA(1, 0), a3, voffA);
;             PG8_WAIT_V(8); PG8_WAIT_L(0); PG8_BAR; PG8_MMA(1, 0, At, B0); PG8_MMA(1, 1, At, B1); PG8_BAR; PG8_SCHED;
	s_add_i32 s6, s18, s21
	v_lshl_add_u64 v[180:181], v[180:181], 0, s[96:97]
	s_mov_b32 m0, s6
	ds_read_b128 v[190:193], v184 offset:49152
	ds_read_b128 v[210:213], v184 offset:50176
	ds_read_b128 v[214:217], v184 offset:51200
	ds_read_b128 v[218:221], v184 offset:52224
	ds_read_b128 v[222:225], v184 offset:53248
	ds_read_b128 v[226:229], v184 offset:54272
	ds_read_b128 v[230:233], v184 offset:55296
	ds_read_b128 v[234:237], v184 offset:56320
	global_load_lds_dwordx4 v[180:181], off
	s_add_i32 m0, s6, 0x2000
	s_add_u32 s6, s10, 0x18080
	v_lshl_add_u64 v[180:181], v[238:239], 0, s[96:97]
	s_addc_u32 s7, s11, 0
	s_add_i32 s10, s19, s21
	global_load_lds_dwordx4 v[180:181], off
	v_lshl_add_u64 v[180:181], s[6:7], 0, v[166:167]
	s_mov_b32 m0, s10
	s_nop 0
	global_load_lds_dwordx4 v[180:181], off
	v_lshl_add_u64 v[180:181], s[6:7], 0, v[170:171]
	s_add_i32 m0, s10, 0x2000
	s_nop 0
	global_load_lds_dwordx4 v[180:181], off
	v_lshl_add_u64 v[180:181], v[240:241], 0, s[96:97]
	s_mov_b32 m0, s94
	s_nop 0
	global_load_lds_dwordx4 v[180:181], off
	v_lshl_add_u64 v[180:181], v[242:243], 0, s[96:97]
	s_mov_b32 m0, s95
	s_nop 0
	global_load_lds_dwordx4 v[180:181], off
	s_waitcnt vmcnt(8)
	s_waitcnt lgkmcnt(0)
	s_barrier
	s_setprio 1
	s_waitcnt lgkmcnt(0)
	v_mfma_f32_16x16x32_bf16 v[92:95], v[104:107], v[190:193], v[92:95]
	v_mfma_f32_16x16x32_bf16 v[88:91], v[136:139], v[190:193], v[88:91]
	v_mfma_f32_16x16x32_bf16 v[84:87], v[104:107], v[214:217], v[84:87]
	v_mfma_f32_16x16x32_bf16 v[80:83], v[136:139], v[214:217], v[80:83]
	v_mfma_f32_16x16x32_bf16 v[76:79], v[104:107], v[222:225], v[76:79]
	v_mfma_f32_16x16x32_bf16 v[72:75], v[136:139], v[222:225], v[72:75]
	v_mfma_f32_16x16x32_bf16 v[68:71], v[104:107], v[230:233], v[68:71]
	v_mfma_f32_16x16x32_bf16 v[64:67], v[136:139], v[230:233], v[64:67]
	v_mfma_f32_16x16x32_bf16 v[92:95], v[108:111], v[210:213], v[92:95]
	v_mfma_f32_16x16x32_bf16 v[88:91], v[140:143], v[210:213], v[88:91]
	v_mfma_f32_16x16x32_bf16 v[84:87], v[108:111], v[218:221], v[84:87]
	v_mfma_f32_16x16x32_bf16 v[80:83], v[140:143], v[218:221], v[80:83]
	v_mfma_f32_16x16x32_bf16 v[76:79], v[108:111], v[226:229], v[76:79]
	v_mfma_f32_16x16x32_bf16 v[72:75], v[140:143], v[226:229], v[72:75]
	v_mfma_f32_16x16x32_bf16 v[68:71], v[108:111], v[234:237], v[68:71]
	v_mfma_f32_16x16x32_bf16 v[64:67], v[140:143], v[234:237], v[64:67]
	s_setprio 0
	s_setprio 1
	v_mfma_f32_16x16x32_bf16 v[28:31], v[144:147], v[190:193], v[28:31]
	v_mfma_f32_16x16x32_bf16 v[24:27], v[176:179], v[190:193], v[24:27]
	v_mfma_f32_16x16x32_bf16 v[20:23], v[144:147], v[214:217], v[20:23]
	v_mfma_f32_16x16x32_bf16 v[16:19], v[176:179], v[214:217], v[16:19]
	v_mfma_f32_16x16x32_bf16 v[12:15], v[144:147], v[222:225], v[12:15]
	v_mfma_f32_16x16x32_bf16 v[8:11], v[176:179], v[222:225], v[8:11]
	v_mfma_f32_16x16x32_bf16 v[4:7], v[144:147], v[230:233], v[4:7]
	v_mfma_f32_16x16x32_bf16 v[0:3], v[176:179], v[230:233], v[0:3]
	v_mfma_f32_16x16x32_bf16 v[28:31], v[148:151], v[210:213], v[28:31]
	v_mfma_f32_16x16x32_bf16 v[24:27], v[186:189], v[210:213], v[24:27]
	v_mfma_f32_16x16x32_bf16 v[20:23], v[148:151], v[218:221], v[20:23]
	v_mfma_f32_16x16x32_bf16 v[16:19], v[186:189], v[218:221], v[16:19]
	v_mfma_f32_16x16x32_bf16 v[12:15], v[148:151], v[226:229], v[12:15]
	v_mfma_f32_16x16x32_bf16 v[8:11], v[186:189], v[226:229], v[8:11]
	v_mfma_f32_16x16x32_bf16 v[4:7], v[148:151], v[234:237], v[4:7]
	v_mfma_f32_16x16x32_bf16 v[0:3], v[186:189], v[234:237], v[0:3]
	s_setprio 0
	s_add_i32 s17, s17, 2
	s_add_u32 s15, s15, 0x100
	s_addc_u32 s16, s16, 0
	s_barrier
	s_cmp_gt_u32 s17, 3
	s_mov_b64 s[6:7], s[8:9]
	s_cbranch_scc0 .LBB0_264
	v_readlane_b32 s6, v255, 36
	v_readlane_b32 s7, v255, 37
	s_and_b64 vcc, exec, s[6:7]
	s_cbranch_vccz .LBB0_267
	s_barrier

; #define PG8_STAGE(bufoff, gbase, voff) do { _Pragma("unroll") for (int _i = 0; _i < 2; ++_i) \
;         __builtin_amdgcn_global_load_lds((const unsigned*)((const char*)(gbase) + (voff)[_i]), (LAS unsigned*)(lds + (bufoff) + ldsw + _i * 8192), 16, 0, 0); } while (0)
; #define PG8_LDA(dst, b, h) do { _Pragma("unroll") for (int m = 0; m < 4; ++m) _Pragma("unroll") for (int k = 0; k < 2; ++k) dst[m][k] = *(const LAS bf16x8*)(lds + PG8_SA(b, h) + aoff + m * 2048 + k * 1024); } while (0)
; #define PG8_LDB(dst, b, h) do { _Pragma("unroll") for (int n = 0; n < 2; ++n) _Pragma("unroll") for (int k = 0; k < 2; ++k) dst[n][k] = *(const LAS bf16x8*)(lds + PG8_SB(b, h) + boff + n * 2048 + k * 1024); } while (0)
; #define PG8_MMA(ai, bj, At, Bt) do { __builtin_amdgcn_s_setprio(1); _Pragma("unroll") for (int m = 0; m < 4; ++m) _Pragma("unroll") for (int n = 0; n < 2; ++n) _Pragma("unroll") for (int k = 0; k < 2; ++k) \
;         acc[ai][bj][m][n] = __builtin_amdgcn_mfma_f32_16x16x32_bf16(Bt[n][k], At[m][k], acc[ai][bj][m][n], 0, 0, 0); __builtin_amdgcn_s_setprio(0); } while (0)
; #define PG8_WAIT_V(n) asm volatile("s_waitcnt vmcnt(" #n ")" ::: "memory")
; #define PG8_WAIT_L(n) asm volatile("s_waitcnt lgkmcnt(" #n ")" ::: "memory")
; #define PG8_BAR __builtin_amdgcn_s_barrier()
; #define PG8_SCHED __builtin_amdgcn_sched_barrier(0)
; template <class Epi>
; __device__ __forceinline__ void gemm_phase(LAS unsigned char* lds, const Gemm g, const int G, const int cidx, const int tid, const Epi& E) {
;     ...
;             const bool last = (t == nt - 2);
;             const char* a1 = cA + (size_t)(t + 1) * kstep;
;             const char* a2 = last ? nA : cA + (size_t)(t + 2) * kstep; const char* b2 = last ? nB : cB + (size_t)(t + 2) * kstep;
;             const char* a3 = a2 + kstep; const char* b3 = b2 + kstep;
;             PG8_LDB(B0, 0, 0); PG8_LDB(B1, 0, 1); PG8_SCHED; PG8_LDA(At, 0, 0); PG8_STAGE(PG8_SA(1, 1), a1 + hstepA, voffA);
;             PG8_WAIT_V(8); PG8_WAIT_L(0); PG8_BAR; PG8_MMA(0, 0, At, B0); PG8_MMA(0, 1, At, B1); PG8_BAR; PG8_SCHED;
;             PG8_LDA(At, 0, 1); PG8_STAGE(PG8_SB(0, 0), b2, voffB); PG8_STAGE(PG8_SB(0, 1), b2 + hstepB, voffB); PG8_STAGE(PG8_SA(0, 0), a2, voffA);
.LBB0_361:
	s_add_i32 s13, 0, 0x10000
	s_mov_b64 s[6:7], 0x100
	s_cmp_eq_u32 s12, 2
	v_lshl_add_u64 v[106:107], v[104:105], 0, s[6:7]
	s_cselect_b64 vcc, -1, 0
	s_cselect_b32 s7, s1, s11
	s_cselect_b32 s6, s0, s10
	s_add_i32 s16, 0, 0x14000
	v_add_u32_e32 v144, s13, v190
	v_add_u32_e32 v152, s16, v190
	ds_read_b128 v[108:111], v144
	ds_read_b128 v[136:139], v144 offset:1024
	ds_read_b128 v[140:143], v144 offset:2048
	ds_read_b128 v[144:147], v144 offset:3072
	ds_read_b128 v[148:151], v152
	ds_read_b128 v[182:185], v152 offset:1024
	ds_read_b128 v[210:213], v152 offset:2048
	ds_read_b128 v[214:217], v152 offset:3072
	v_cndmask_b32_e32 v187, v107, v181, vcc
	v_cndmask_b32_e32 v186, v106, v180, vcc
	v_lshl_add_u64 v[192:193], v[104:105], 0, v[176:177]
	s_add_i32 m0, s21, 0xc000
	ds_read_b128 v[218:221], v191
	ds_read_b128 v[222:225], v191 offset:1024
	ds_read_b128 v[226:229], v191 offset:2048
	ds_read_b128 v[230:233], v191 offset:3072
	ds_read_b128 v[234:237], v191 offset:4096
	ds_read_b128 v[238:241], v191 offset:5120
	ds_read_b128 v[242:245], v191 offset:6144
	ds_read_b128 v[246:249], v191 offset:7168
	global_load_lds_dwordx4 v[192:193], off
	v_lshl_add_u64 v[104:105], v[104:105], 0, v[178:179]
	s_add_i32 m0, s21, 0xe000
	s_nop 0
	global_load_lds_dwordx4 v[104:105], off
	s_waitcnt vmcnt(8)
	s_waitcnt lgkmcnt(0)
	s_barrier
	s_setprio 1
	s_waitcnt lgkmcnt(0)
	v_mfma_f32_16x16x32_bf16 v[132:135], v[108:111], v[218:221], v[132:135]
	v_mfma_f32_16x16x32_bf16 v[128:131], v[140:143], v[218:221], v[128:131]
	v_mfma_f32_16x16x32_bf16 v[124:127], v[108:111], v[226:229], v[124:127]
	v_mfma_f32_16x16x32_bf16 v[120:123], v[140:143], v[226:229], v[120:123]
	v_mfma_f32_16x16x32_bf16 v[116:119], v[108:111], v[234:237], v[116:119]
	v_mfma_f32_16x16x32_bf16 v[112:115], v[140:143], v[234:237], v[112:115]
	v_mfma_f32_16x16x32_bf16 v[100:103], v[108:111], v[242:245], v[100:103]
	v_mfma_f32_16x16x32_bf16 v[96:99], v[140:143], v[242:245], v[96:99]
	v_mfma_f32_16x16x32_bf16 v[132:135], v[136:139], v[222:225], v[132:135]
	v_mfma_f32_16x16x32_bf16 v[128:131], v[144:147], v[222:225], v[128:131]
	v_mfma_f32_16x16x32_bf16 v[124:127], v[136:139], v[230:233], v[124:127]
	v_mfma_f32_16x16x32_bf16 v[120:123], v[144:147], v[230:233], v[120:123]
	v_mfma_f32_16x16x32_bf16 v[116:119], v[136:139], v[238:241], v[116:119]
	v_mfma_f32_16x16x32_bf16 v[112:115], v[144:147], v[238:241], v[112:115]
	v_mfma_f32_16x16x32_bf16 v[100:103], v[136:139], v[246:249], v[100:103]
	v_mfma_f32_16x16x32_bf16 v[96:99], v[144:147], v[246:249], v[96:99]
	s_setprio 0
	s_setprio 1
	v_mfma_f32_16x16x32_bf16 v[60:63], v[148:151], v[218:221], v[60:63]
	v_mfma_f32_16x16x32_bf16 v[56:59], v[210:213], v[218:221], v[56:59]
	v_mfma_f32_16x16x32_bf16 v[52:55], v[148:151], v[226:229], v[52:55]
	v_mfma_f32_16x16x32_bf16 v[48:51], v[210:213], v[226:229], v[48:51]
	v_mfma_f32_16x16x32_bf16 v[44:47], v[148:151], v[234:237], v[44:47]
	v_mfma_f32_16x16x32_bf16 v[40:43], v[210:213], v[234:237], v[40:43]
	v_mfma_f32_16x16x32_bf16 v[36:39], v[148:151], v[242:245], v[36:39]
	v_mfma_f32_16x16x32_bf16 v[32:35], v[210:213], v[242:245], v[32:35]
	v_mfma_f32_16x16x32_bf16 v[60:63], v[182:185], v[222:225], v[60:63]
	v_mfma_f32_16x16x32_bf16 v[56:59], v[214:217], v[222:225], v[56:59]
	v_mfma_f32_16x16x32_bf16 v[52:55], v[182:185], v[230:233], v[52:55]
	v_mfma_f32_16x16x32_bf16 v[48:51], v[214:217], v[230:233], v[48:51]
	v_mfma_f32_16x16x32_bf16 v[44:47], v[182:185], v[238:241], v[44:47]
	v_mfma_f32_16x16x32_bf16 v[40:43], v[214:217], v[238:241], v[40:43]
	v_mfma_f32_16x16x32_bf16 v[36:39], v[182:185], v[246:249], v[36:39]
	v_mfma_f32_16x16x32_bf16 v[32:35], v[214:217], v[246:249], v[32:35]
	s_setprio 0
	s_barrier
	s_add_i32 s13, s13, s65
	v_lshl_add_u64 v[104:105], s[6:7], 0, v[168:169]
	s_mov_b32 m0, s13
	ds_read_b128 v[218:221], v191 offset:16384
	ds_read_b128 v[222:225], v191 offset:17408
	ds_read_b128 v[226:229], v191 offset:18432
	ds_read_b128 v[230:233], v191 offset:19456
	ds_read_b128 v[234:237], v191 offset:20480
	ds_read_b128 v[238:241], v191 offset:21504
	ds_read_b128 v[242:245], v191 offset:22528
	ds_read_b128 v[246:249], v191 offset:23552
	global_load_lds_dwordx4 v[104:105], off
	s_add_i32 m0, s13, 0x2000
	s_add_u32 s14, s6, 0x18000
	v_lshl_add_u64 v[192:193], s[6:7], 0, v[172:173]
	s_addc_u32 s15, s7, 0
	s_add_i32 s13, s16, s65
	global_load_lds_dwordx4 v[192:193], off
	v_lshl_add_u64 v[250:251], s[14:15], 0, v[168:169]
	s_mov_b32 m0, s13
	v_lshl_add_u64 v[208:209], v[186:187], 0, v[170:171]
	global_load_lds_dwordx4 v[250:251], off
	v_lshl_add_u64 v[250:251], s[14:15], 0, v[172:173]
	s_add_i32 m0, s13, 0x2000
	s_nop 0
	global_load_lds_dwordx4 v[250:251], off
	v_lshl_add_u64 v[250:251], v[186:187], 0, v[166:167]
	s_mov_b32 m0, s21
	s_nop 0
	global_load_lds_dwordx4 v[250:251], off
	s_mov_b32 m0, s64
	s_nop 0
	global_load_lds_dwordx4 v[208:209], off
	s_waitcnt vmcnt(8)
	s_waitcnt lgkmcnt(0)
	s_barrier
; #define PG8_STAGE(bufoff, gbase, voff) do { _Pragma("unroll") for (int _i = 0; _i < 2; ++_i) \
;         __builtin_amdgcn_global_load_lds((const unsigned*)((const char*)(gbase) + (voff)[_i]), (LAS unsigned*)(lds + (bufoff) + ldsw + _i * 8192), 16, 0, 0); } while (0)
; #define PG8_LDA(dst, b, h) do { _Pragma("unroll") for (int m = 0; m < 4; ++m) _Pragma("unroll") for (int k = 0; k < 2; ++k) dst[m][k] = *(const LAS bf16x8*)(lds + PG8_SA(b, h) + aoff + m * 2048 + k * 1024); } while (0)
; #define PG8_LDB(dst, b, h) do { _Pragma("unroll") for (int n = 0; n < 2; ++n) _Pragma("unroll") for (int k = 0; k < 2; ++k) dst[n][k] = *(const LAS bf16x8*)(lds + PG8_SB(b, h) + boff + n * 2048 + k * 1024); } while (0)
; #define PG8_MMA(ai, bj, At, Bt) do { __builtin_amdgcn_s_setprio(1); _Pragma("unroll") for (int m = 0; m < 4; ++m) _Pragma("unroll") for (int n = 0; n < 2; ++n) _Pragma("unroll") for (int k = 0; k < 2; ++k) \
;         acc[ai][bj][m][n] = __builtin_amdgcn_mfma_f32_16x16x32_bf16(Bt[n][k], At[m][k], acc[ai][bj][m][n], 0, 0, 0); __builtin_amdgcn_s_setprio(0); } while (0)
; #define PG8_WAIT_V(n) asm volatile("s_waitcnt vmcnt(" #n ")" ::: "memory")
; #define PG8_WAIT_L(n) asm volatile("s_waitcnt lgkmcnt(" #n ")" ::: "memory")
; #define PG8_BAR __builtin_amdgcn_s_barrier()
; #define PG8_SCHED __builtin_amdgcn_sched_barrier(0)
; template <class Epi>
; __device__ __forceinline__ void gemm_phase(LAS unsigned char* lds, const Gemm g, const int G, const int cidx, const int tid, const Epi& E) {
;     ...
;             PG8_WAIT_V(8); PG8_WAIT_L(0); PG8_BAR; PG8_MMA(1, 0, At, B0); PG8_MMA(1, 1, At, B1); PG8_BAR; PG8_SCHED;
;             PG8_LDB(B0, 1, 0); PG8_LDB(B1, 1, 1); PG8_SCHED; PG8_LDA(At, 1, 0); PG8_STAGE(PG8_SA(0, 1), a2 + hstepA, voffA);
;             PG8_WAIT_V(8); PG8_WAIT_L(0); PG8_BAR; PG8_MMA(0, 0, At, B0); PG8_MMA(0, 1, At, B1); PG8_BAR; PG8_SCHED;
	s_setprio 1
	s_waitcnt lgkmcnt(0)
	v_mfma_f32_16x16x32_bf16 v[92:95], v[108:111], v[218:221], v[92:95]
	v_mfma_f32_16x16x32_bf16 v[88:91], v[140:143], v[218:221], v[88:91]
	v_mfma_f32_16x16x32_bf16 v[84:87], v[108:111], v[226:229], v[84:87]
	v_mfma_f32_16x16x32_bf16 v[80:83], v[140:143], v[226:229], v[80:83]
	v_mfma_f32_16x16x32_bf16 v[76:79], v[108:111], v[234:237], v[76:79]
	v_mfma_f32_16x16x32_bf16 v[72:75], v[140:143], v[234:237], v[72:75]
	v_mfma_f32_16x16x32_bf16 v[68:71], v[108:111], v[242:245], v[68:71]
	v_mfma_f32_16x16x32_bf16 v[64:67], v[140:143], v[242:245], v[64:67]
	v_mfma_f32_16x16x32_bf16 v[92:95], v[136:139], v[222:225], v[92:95]
	v_mfma_f32_16x16x32_bf16 v[88:91], v[144:147], v[222:225], v[88:91]
	v_mfma_f32_16x16x32_bf16 v[84:87], v[136:139], v[230:233], v[84:87]
	v_mfma_f32_16x16x32_bf16 v[80:83], v[144:147], v[230:233], v[80:83]
	v_mfma_f32_16x16x32_bf16 v[76:79], v[136:139], v[238:241], v[76:79]
	v_mfma_f32_16x16x32_bf16 v[72:75], v[144:147], v[238:241], v[72:75]
	v_mfma_f32_16x16x32_bf16 v[68:71], v[136:139], v[246:249], v[68:71]
	v_mfma_f32_16x16x32_bf16 v[64:67], v[144:147], v[246:249], v[64:67]
	s_setprio 0
	s_setprio 1
	v_mfma_f32_16x16x32_bf16 v[28:31], v[148:151], v[218:221], v[28:31]
	v_mfma_f32_16x16x32_bf16 v[24:27], v[210:213], v[218:221], v[24:27]
	v_mfma_f32_16x16x32_bf16 v[20:23], v[148:151], v[226:229], v[20:23]
	v_mfma_f32_16x16x32_bf16 v[16:19], v[210:213], v[226:229], v[16:19]
	v_mfma_f32_16x16x32_bf16 v[12:15], v[148:151], v[234:237], v[12:15]
	v_mfma_f32_16x16x32_bf16 v[8:11], v[210:213], v[234:237], v[8:11]
	v_mfma_f32_16x16x32_bf16 v[4:7], v[148:151], v[242:245], v[4:7]
	v_mfma_f32_16x16x32_bf16 v[0:3], v[210:213], v[242:245], v[0:3]
	v_mfma_f32_16x16x32_bf16 v[28:31], v[182:185], v[222:225], v[28:31]
	v_mfma_f32_16x16x32_bf16 v[24:27], v[214:217], v[222:225], v[24:27]
	v_mfma_f32_16x16x32_bf16 v[20:23], v[182:185], v[230:233], v[20:23]
	v_mfma_f32_16x16x32_bf16 v[16:19], v[214:217], v[230:233], v[16:19]
	v_mfma_f32_16x16x32_bf16 v[12:15], v[182:185], v[238:241], v[12:15]
	v_mfma_f32_16x16x32_bf16 v[8:11], v[214:217], v[238:241], v[8:11]
	v_mfma_f32_16x16x32_bf16 v[4:7], v[182:185], v[246:249], v[4:7]
	v_mfma_f32_16x16x32_bf16 v[0:3], v[214:217], v[246:249], v[0:3]
	s_setprio 0
	s_barrier
	s_add_i32 s13, 0, 0x18000
	s_add_i32 s14, 0, 0x1c000
	v_add_u32_e32 v144, s13, v190
	v_add_u32_e32 v152, s14, v190
	ds_read_b128 v[108:111], v144
	ds_read_b128 v[136:139], v144 offset:1024
	ds_read_b128 v[140:143], v144 offset:2048
	ds_read_b128 v[144:147], v144 offset:3072
	ds_read_b128 v[148:151], v152
	ds_read_b128 v[182:185], v152 offset:1024
	ds_read_b128 v[210:213], v152 offset:2048
	ds_read_b128 v[214:217], v152 offset:3072
	v_lshl_add_u64 v[186:187], v[186:187], 0, s[18:19]
	s_mov_b32 m0, s62
	v_lshl_add_u64 v[158:159], v[186:187], 0, v[166:167]
	ds_read_b128 v[218:221], v191 offset:32768
	ds_read_b128 v[222:225], v191 offset:33792
	ds_read_b128 v[226:229], v191 offset:34816
	ds_read_b128 v[230:233], v191 offset:35840
	ds_read_b128 v[234:237], v191 offset:36864
	ds_read_b128 v[238:241], v191 offset:37888
	ds_read_b128 v[242:245], v191 offset:38912
	ds_read_b128 v[246:249], v191 offset:39936
	global_load_lds_dwordx4 v[158:159], off
	v_lshl_add_u64 v[158:159], v[186:187], 0, v[170:171]
	s_mov_b32 m0, s63
	s_nop 0
	global_load_lds_dwordx4 v[158:159], off
	s_waitcnt vmcnt(8)
	s_waitcnt lgkmcnt(0)
	s_barrier
	s_setprio 1
	s_waitcnt lgkmcnt(0)
	v_mfma_f32_16x16x32_bf16 v[132:135], v[108:111], v[218:221], v[132:135]
	v_mfma_f32_16x16x32_bf16 v[128:131], v[140:143], v[218:221], v[128:131]
	v_mfma_f32_16x16x32_bf16 v[124:127], v[108:111], v[226:229], v[124:127]
	v_mfma_f32_16x16x32_bf16 v[120:123], v[140:143], v[226:229], v[120:123]
	v_mfma_f32_16x16x32_bf16 v[116:119], v[108:111], v[234:237], v[116:119]
	v_mfma_f32_16x16x32_bf16 v[112:115], v[140:143], v[234:237], v[112:115]
	v_mfma_f32_16x16x32_bf16 v[100:103], v[108:111], v[242:245], v[100:103]
	v_mfma_f32_16x16x32_bf16 v[96:99], v[140:143], v[242:245], v[96:99]
	v_mfma_f32_16x16x32_bf16 v[132:135], v[136:139], v[222:225], v[132:135]
	v_mfma_f32_16x16x32_bf16 v[128:131], v[144:147], v[222:225], v[128:131]
	v_mfma_f32_16x16x32_bf16 v[124:127], v[136:139], v[230:233], v[124:127]
	v_mfma_f32_16x16x32_bf16 v[120:123], v[144:147], v[230:233], v[120:123]
	v_mfma_f32_16x16x32_bf16 v[116:119], v[136:139], v[238:241], v[116:119]
	v_mfma_f32_16x16x32_bf16 v[112:115], v[144:147], v[238:241], v[112:115]
	v_mfma_f32_16x16x32_bf16 v[100:103], v[136:139], v[246:249], v[100:103]
	v_mfma_f32_16x16x32_bf16 v[96:99], v[144:147], v[246:249], v[96:99]
	s_setprio 0
	s_setprio 1
	v_mfma_f32_16x16x32_bf16 v[60:63], v[148:151], v[218:221], v[60:63]
	v_mfma_f32_16x16x32_bf16 v[56:59], v[210:213], v[218:221], v[56:59]
	v_mfma_f32_16x16x32_bf16 v[52:55], v[148:151], v[226:229], v[52:55]
	v_mfma_f32_16x16x32_bf16 v[48:51], v[210:213], v[226:229], v[48:51]
	v_mfma_f32_16x16x32_bf16 v[44:47], v[148:151], v[234:237], v[44:47]
	v_mfma_f32_16x16x32_bf16 v[40:43], v[210:213], v[234:237], v[40:43]
	v_mfma_f32_16x16x32_bf16 v[36:39], v[148:151], v[242:245], v[36:39]
	v_mfma_f32_16x16x32_bf16 v[32:35], v[210:213], v[242:245], v[32:35]
	v_mfma_f32_16x16x32_bf16 v[60:63], v[182:185], v[222:225], v[60:63]
	v_mfma_f32_16x16x32_bf16 v[56:59], v[214:217], v[222:225], v[56:59]
	v_mfma_f32_16x16x32_bf16 v[52:55], v[182:185], v[230:233], v[52:55]
	v_mfma_f32_16x16x32_bf16 v[48:51], v[214:217], v[230:233], v[48:51]
	v_mfma_f32_16x16x32_bf16 v[44:47], v[182:185], v[238:241], v[44:47]
	v_mfma_f32_16x16x32_bf16 v[40:43], v[214:217], v[238:241], v[40:43]
	v_mfma_f32_16x16x32_bf16 v[36:39], v[182:185], v[246:249], v[36:39]
	v_mfma_f32_16x16x32_bf16 v[32:35], v[214:217], v[246:249], v[32:35]
	s_setprio 0
	s_barrier
; #define PG8_STAGE(bufoff, gbase, voff) do { _Pragma("unroll") for (int _i = 0; _i < 2; ++_i) \
;         __builtin_amdgcn_global_load_lds((const unsigned*)((const char*)(gbase) + (voff)[_i]), (LAS unsigned*)(lds + (bufoff) + ldsw + _i * 8192), 16, 0, 0); } while (0)
; #define PG8_LDA(dst, b, h) do { _Pragma("unroll") for (int m = 0; m < 4; ++m) _Pragma("unroll") for (int k = 0; k < 2; ++k) dst[m][k] = *(const LAS bf16x8*)(lds + PG8_SA(b, h) + aoff + m * 2048 + k * 1024); } while (0)
; #define PG8_MMA(ai, bj, At, Bt) do { __builtin_amdgcn_s_setprio(1); _Pragma("unroll") for (int m = 0; m < 4; ++m) _Pragma("unroll") for (int n = 0; n < 2; ++n) _Pragma("unroll") for (int k = 0; k < 2; ++k) \
;         acc[ai][bj][m][n] = __builtin_amdgcn_mfma_f32_16x16x32_bf16(Bt[n][k], At[m][k], acc[ai][bj][m][n], 0, 0, 0); __builtin_amdgcn_s_setprio(0); } while (0)
; #define PG8_WAIT_V(n) asm volatile("s_waitcnt vmcnt(" #n ")" ::: "memory")
; #define PG8_WAIT_L(n) asm volatile("s_waitcnt lgkmcnt(" #n ")" ::: "memory")
; #define PG8_BAR __builtin_amdgcn_s_barrier()
; #define PG8_SCHED __builtin_amdgcn_sched_barrier(0)
; template <class Epi>
; __device__ __forceinline__ void gemm_phase(LAS unsigned char* lds, const Gemm g, const int G, const int cidx, const int tid, const Epi& E) {
;     ...
;         for (int t = 0; t < nt; t += 2) {
;     ...
;             PG8_LDA(At, 1, 1); PG8_STAGE(PG8_SB(1, 0), b3, voffB); PG8_STAGE(PG8_SB(1, 1), b3 + hstepB, voffB); PG8_STAGE(PG8_SA(1, 0), a3, voffA);
;             PG8_WAIT_V(8); PG8_WAIT_L(0); PG8_BAR; PG8_MMA(1, 0, At, B0); PG8_MMA(1, 1, At, B1); PG8_BAR; PG8_SCHED;
	s_add_i32 s13, s13, s65
	v_lshl_add_u64 v[104:105], v[104:105], 0, s[96:97]
	s_mov_b32 m0, s13
	ds_read_b128 v[218:221], v191 offset:49152
	ds_read_b128 v[222:225], v191 offset:50176
	ds_read_b128 v[226:229], v191 offset:51200
	ds_read_b128 v[230:233], v191 offset:52224
	ds_read_b128 v[234:237], v191 offset:53248
	ds_read_b128 v[238:241], v191 offset:54272
	ds_read_b128 v[242:245], v191 offset:55296
	ds_read_b128 v[246:249], v191 offset:56320
	global_load_lds_dwordx4 v[104:105], off
	s_add_i32 m0, s13, 0x2000
	s_add_u32 s6, s6, 0x18080
	v_lshl_add_u64 v[104:105], v[192:193], 0, s[96:97]
	s_addc_u32 s7, s7, 0
	s_add_i32 s13, s14, s65
	global_load_lds_dwordx4 v[104:105], off
	v_lshl_add_u64 v[104:105], s[6:7], 0, v[168:169]
	s_mov_b32 m0, s13
	s_nop 0
	global_load_lds_dwordx4 v[104:105], off
	v_lshl_add_u64 v[104:105], s[6:7], 0, v[172:173]
	s_add_i32 m0, s13, 0x2000
	s_nop 0
	global_load_lds_dwordx4 v[104:105], off
	v_lshl_add_u64 v[104:105], v[250:251], 0, s[96:97]
	s_mov_b32 m0, s53
	s_nop 0
	global_load_lds_dwordx4 v[104:105], off
	v_lshl_add_u64 v[104:105], v[208:209], 0, s[96:97]
	s_mov_b32 m0, s20
	s_nop 0
	global_load_lds_dwordx4 v[104:105], off
	s_waitcnt vmcnt(8)
	s_waitcnt lgkmcnt(0)
	s_barrier
	s_setprio 1
	s_waitcnt lgkmcnt(0)
	v_mfma_f32_16x16x32_bf16 v[92:95], v[108:111], v[218:221], v[92:95]
	v_mfma_f32_16x16x32_bf16 v[88:91], v[140:143], v[218:221], v[88:91]
	v_mfma_f32_16x16x32_bf16 v[84:87], v[108:111], v[226:229], v[84:87]
	v_mfma_f32_16x16x32_bf16 v[80:83], v[140:143], v[226:229], v[80:83]
	v_mfma_f32_16x16x32_bf16 v[76:79], v[108:111], v[234:237], v[76:79]
	v_mfma_f32_16x16x32_bf16 v[72:75], v[140:143], v[234:237], v[72:75]
	v_mfma_f32_16x16x32_bf16 v[68:71], v[108:111], v[242:245], v[68:71]
	v_mfma_f32_16x16x32_bf16 v[64:67], v[140:143], v[242:245], v[64:67]
	v_mfma_f32_16x16x32_bf16 v[92:95], v[136:139], v[222:225], v[92:95]
	v_mfma_f32_16x16x32_bf16 v[88:91], v[144:147], v[222:225], v[88:91]
	v_mfma_f32_16x16x32_bf16 v[84:87], v[136:139], v[230:233], v[84:87]
	v_mfma_f32_16x16x32_bf16 v[80:83], v[144:147], v[230:233], v[80:83]
	v_mfma_f32_16x16x32_bf16 v[76:79], v[136:139], v[238:241], v[76:79]
	v_mfma_f32_16x16x32_bf16 v[72:75], v[144:147], v[238:241], v[72:75]
	v_mfma_f32_16x16x32_bf16 v[68:71], v[136:139], v[246:249], v[68:71]
	v_mfma_f32_16x16x32_bf16 v[64:67], v[144:147], v[246:249], v[64:67]
	s_setprio 0
	s_setprio 1
	v_mfma_f32_16x16x32_bf16 v[28:31], v[148:151], v[218:221], v[28:31]
	v_mfma_f32_16x16x32_bf16 v[24:27], v[210:213], v[218:221], v[24:27]
	v_mfma_f32_16x16x32_bf16 v[20:23], v[148:151], v[226:229], v[20:23]
	v_mfma_f32_16x16x32_bf16 v[16:19], v[210:213], v[226:229], v[16:19]
	v_mfma_f32_16x16x32_bf16 v[12:15], v[148:151], v[234:237], v[12:15]
	v_mfma_f32_16x16x32_bf16 v[8:11], v[210:213], v[234:237], v[8:11]
	v_mfma_f32_16x16x32_bf16 v[4:7], v[148:151], v[242:245], v[4:7]
	v_mfma_f32_16x16x32_bf16 v[0:3], v[210:213], v[242:245], v[0:3]
	v_mfma_f32_16x16x32_bf16 v[28:31], v[182:185], v[222:225], v[28:31]
	v_mfma_f32_16x16x32_bf16 v[24:27], v[214:217], v[222:225], v[24:27]
	v_mfma_f32_16x16x32_bf16 v[20:23], v[182:185], v[230:233], v[20:23]
	v_mfma_f32_16x16x32_bf16 v[16:19], v[214:217], v[230:233], v[16:19]
	v_mfma_f32_16x16x32_bf16 v[12:15], v[182:185], v[238:241], v[12:15]
	v_mfma_f32_16x16x32_bf16 v[8:11], v[214:217], v[238:241], v[8:11]
	v_mfma_f32_16x16x32_bf16 v[4:7], v[182:185], v[246:249], v[4:7]
	v_mfma_f32_16x16x32_bf16 v[0:3], v[214:217], v[246:249], v[0:3]
	s_setprio 0
	s_add_i32 s12, s12, 2
	s_add_u32 s10, s10, 0x100
	s_addc_u32 s11, s11, 0
	s_barrier
	s_cmp_gt_u32 s12, 3
	v_mov_b64_e32 v[104:105], v[106:107]
	s_cbranch_scc0 .LBB0_361
	s_and_b64 vcc, exec, s[54:55]
	s_cbranch_vccz .LBB0_364
	s_barrier

; #define PG8_STAGE(bufoff, gbase, voff) do { _Pragma("unroll") for (int _i = 0; _i < 2; ++_i) \
;         __builtin_amdgcn_global_load_lds((const unsigned*)((const char*)(gbase) + (voff)[_i]), (LAS unsigned*)(lds + (bufoff) + ldsw + _i * 8192), 16, 0, 0); } while (0)
; #define PG8_LDA(dst, b, h) do { _Pragma("unroll") for (int m = 0; m < 4; ++m) _Pragma("unroll") for (int k = 0; k < 2; ++k) dst[m][k] = *(const LAS bf16x8*)(lds + PG8_SA(b, h) + aoff + m * 2048 + k * 1024); } while (0)
; #define PG8_LDB(dst, b, h) do { _Pragma("unroll") for (int n = 0; n < 2; ++n) _Pragma("unroll") for (int k = 0; k < 2; ++k) dst[n][k] = *(const LAS bf16x8*)(lds + PG8_SB(b, h) + boff + n * 2048 + k * 1024); } while (0)
; #define PG8_MMA(ai, bj, At, Bt) do { __builtin_amdgcn_s_setprio(1); _Pragma("unroll") for (int m = 0; m < 4; ++m) _Pragma("unroll") for (int n = 0; n < 2; ++n) _Pragma("unroll") for (int k = 0; k < 2; ++k) \
;         acc[ai][bj][m][n] = __builtin_amdgcn_mfma_f32_16x16x32_bf16(Bt[n][k], At[m][k], acc[ai][bj][m][n], 0, 0, 0); __builtin_amdgcn_s_setprio(0); } while (0)
; #define PG8_WAIT_V(n) asm volatile("s_waitcnt vmcnt(" #n ")" ::: "memory")
; #define PG8_WAIT_L(n) asm volatile("s_waitcnt lgkmcnt(" #n ")" ::: "memory")
; #define PG8_BAR __builtin_amdgcn_s_barrier()
; #define PG8_SCHED __builtin_amdgcn_sched_barrier(0)
; template <class Epi>
; __device__ __forceinline__ void gemm_phase(LAS unsigned char* lds, const Gemm g, const int G, const int cidx, const int tid, const Epi& E) {
;     ...
;             const bool last = (t == nt - 2);
;             const char* a1 = cA + (size_t)(t + 1) * kstep;
;             const char* a2 = last ? nA : cA + (size_t)(t + 2) * kstep; const char* b2 = last ? nB : cB + (size_t)(t + 2) * kstep;
;             const char* a3 = a2 + kstep; const char* b3 = b2 + kstep;
;             PG8_LDB(B0, 0, 0); PG8_LDB(B1, 0, 1); PG8_SCHED; PG8_LDA(At, 0, 0); PG8_STAGE(PG8_SA(1, 1), a1 + hstepA, voffA);
;             PG8_WAIT_V(8); PG8_WAIT_L(0); PG8_BAR; PG8_MMA(0, 0, At, B0); PG8_MMA(0, 1, At, B1); PG8_BAR; PG8_SCHED;
;             PG8_LDA(At, 0, 1); PG8_STAGE(PG8_SB(0, 0), b2, voffB); PG8_STAGE(PG8_SB(0, 1), b2 + hstepB, voffB); PG8_STAGE(PG8_SA(0, 0), a2, voffA);
.LBB0_466:
	s_add_u32 s54, s52, 0xfffe0080
	s_addc_u32 s55, s53, -1
	s_add_i32 s66, 0, 0x10000
	s_cmp_eq_u32 s95, 4
	s_cselect_b32 s57, s13, s55
	s_cselect_b32 s56, s35, s54
	v_add_u32_e32 v158, s66, v163
	s_cselect_b32 s55, s11, s94
	s_cselect_b32 s54, s65, s92
	s_add_i32 s67, 0, 0x14000
	ds_read_b128 v[128:131], v158
	ds_read_b128 v[132:135], v158 offset:1024
	ds_read_b128 v[148:151], v158 offset:2048
	ds_read_b128 v[164:167], v158 offset:3072
	v_add_u32_e32 v158, s67, v163
	ds_read_b128 v[174:177], v158
	ds_read_b128 v[178:181], v158 offset:1024
	ds_read_b128 v[182:185], v158 offset:2048
	ds_read_b128 v[186:189], v158 offset:3072
	v_lshl_add_u64 v[158:159], s[52:53], 0, v[144:145]
	s_add_i32 m0, s19, 0xc000
	ds_read_b128 v[190:193], v172
	ds_read_b128 v[210:213], v172 offset:1024
	ds_read_b128 v[214:217], v172 offset:2048
	ds_read_b128 v[218:221], v172 offset:3072
	ds_read_b128 v[222:225], v172 offset:4096
	ds_read_b128 v[226:229], v172 offset:5120
	ds_read_b128 v[230:233], v172 offset:6144
	ds_read_b128 v[234:237], v172 offset:7168
	global_load_lds_dwordx4 v[158:159], off
	v_lshl_add_u64 v[158:159], s[52:53], 0, v[146:147]
	s_add_i32 m0, s19, 0xe000
	s_nop 0
	global_load_lds_dwordx4 v[158:159], off
	s_waitcnt vmcnt(8)
	s_waitcnt lgkmcnt(0)
	s_barrier
	s_setprio 1
	s_waitcnt lgkmcnt(0)
	v_mfma_f32_16x16x32_bf16 v[124:127], v[128:131], v[190:193], v[124:127]
	v_mfma_f32_16x16x32_bf16 v[120:123], v[148:151], v[190:193], v[120:123]
	v_mfma_f32_16x16x32_bf16 v[108:111], v[128:131], v[214:217], v[108:111]
	v_mfma_f32_16x16x32_bf16 v[104:107], v[148:151], v[214:217], v[104:107]
	v_mfma_f32_16x16x32_bf16 v[92:95], v[128:131], v[222:225], v[92:95]
	v_mfma_f32_16x16x32_bf16 v[88:91], v[148:151], v[222:225], v[88:91]
	v_mfma_f32_16x16x32_bf16 v[76:79], v[128:131], v[230:233], v[76:79]
	v_mfma_f32_16x16x32_bf16 v[72:75], v[148:151], v[230:233], v[72:75]
	v_mfma_f32_16x16x32_bf16 v[124:127], v[132:135], v[210:213], v[124:127]
	v_mfma_f32_16x16x32_bf16 v[120:123], v[164:167], v[210:213], v[120:123]
	v_mfma_f32_16x16x32_bf16 v[108:111], v[132:135], v[218:221], v[108:111]
	v_mfma_f32_16x16x32_bf16 v[104:107], v[164:167], v[218:221], v[104:107]
	v_mfma_f32_16x16x32_bf16 v[92:95], v[132:135], v[226:229], v[92:95]
	v_mfma_f32_16x16x32_bf16 v[88:91], v[164:167], v[226:229], v[88:91]
	v_mfma_f32_16x16x32_bf16 v[76:79], v[132:135], v[234:237], v[76:79]
	v_mfma_f32_16x16x32_bf16 v[72:75], v[164:167], v[234:237], v[72:75]
	s_setprio 0
	s_setprio 1
	v_mfma_f32_16x16x32_bf16 v[116:119], v[174:177], v[190:193], v[116:119]
	v_mfma_f32_16x16x32_bf16 v[112:115], v[182:185], v[190:193], v[112:115]
	v_mfma_f32_16x16x32_bf16 v[100:103], v[174:177], v[214:217], v[100:103]
	v_mfma_f32_16x16x32_bf16 v[96:99], v[182:185], v[214:217], v[96:99]
	v_mfma_f32_16x16x32_bf16 v[84:87], v[174:177], v[222:225], v[84:87]
	v_mfma_f32_16x16x32_bf16 v[80:83], v[182:185], v[222:225], v[80:83]
	v_mfma_f32_16x16x32_bf16 v[68:71], v[174:177], v[230:233], v[68:71]
	v_mfma_f32_16x16x32_bf16 v[64:67], v[182:185], v[230:233], v[64:67]
	v_mfma_f32_16x16x32_bf16 v[116:119], v[178:181], v[210:213], v[116:119]
	v_mfma_f32_16x16x32_bf16 v[112:115], v[186:189], v[210:213], v[112:115]
	v_mfma_f32_16x16x32_bf16 v[100:103], v[178:181], v[218:221], v[100:103]
	v_mfma_f32_16x16x32_bf16 v[96:99], v[186:189], v[218:221], v[96:99]
	v_mfma_f32_16x16x32_bf16 v[84:87], v[178:181], v[226:229], v[84:87]
	v_mfma_f32_16x16x32_bf16 v[80:83], v[186:189], v[226:229], v[80:83]
	v_mfma_f32_16x16x32_bf16 v[68:71], v[178:181], v[234:237], v[68:71]
	v_mfma_f32_16x16x32_bf16 v[64:67], v[186:189], v[234:237], v[64:67]
	s_setprio 0
	s_barrier
	s_add_i32 s66, s66, s29
	v_lshl_add_u64 v[158:159], s[54:55], 0, v[152:153]
	s_mov_b32 m0, s66
	ds_read_b128 v[190:193], v172 offset:16384
	ds_read_b128 v[210:213], v172 offset:17408
	ds_read_b128 v[214:217], v172 offset:18432
	ds_read_b128 v[218:221], v172 offset:19456
	ds_read_b128 v[222:225], v172 offset:20480
	ds_read_b128 v[226:229], v172 offset:21504
	ds_read_b128 v[230:233], v172 offset:22528
	ds_read_b128 v[234:237], v172 offset:23552
	global_load_lds_dwordx4 v[158:159], off
	s_add_i32 m0, s66, 0x2000
	s_add_u32 vcc_lo, s54, 0x20000
	v_lshl_add_u64 v[168:169], s[54:55], 0, v[140:141]
	s_addc_u32 vcc_hi, s55, 0
	s_add_i32 s66, s67, s29
	global_load_lds_dwordx4 v[168:169], off
	v_lshl_add_u64 v[208:209], vcc, 0, v[152:153]
	s_mov_b32 m0, s66
	v_lshl_add_u64 v[238:239], s[56:57], 0, v[138:139]
	global_load_lds_dwordx4 v[208:209], off
	v_lshl_add_u64 v[208:209], vcc, 0, v[140:141]
	s_add_i32 m0, s66, 0x2000
	s_nop 0
	global_load_lds_dwordx4 v[208:209], off
	v_lshl_add_u64 v[208:209], s[56:57], 0, v[136:137]
	s_mov_b32 m0, s19
	s_nop 0
	global_load_lds_dwordx4 v[208:209], off
	s_mov_b32 m0, s31
	s_nop 0
	global_load_lds_dwordx4 v[238:239], off
	s_waitcnt vmcnt(8)
	s_waitcnt lgkmcnt(0)
	s_barrier
; #define PG8_STAGE(bufoff, gbase, voff) do { _Pragma("unroll") for (int _i = 0; _i < 2; ++_i) \
;         __builtin_amdgcn_global_load_lds((const unsigned*)((const char*)(gbase) + (voff)[_i]), (LAS unsigned*)(lds + (bufoff) + ldsw + _i * 8192), 16, 0, 0); } while (0)
; #define PG8_LDA(dst, b, h) do { _Pragma("unroll") for (int m = 0; m < 4; ++m) _Pragma("unroll") for (int k = 0; k < 2; ++k) dst[m][k] = *(const LAS bf16x8*)(lds + PG8_SA(b, h) + aoff + m * 2048 + k * 1024); } while (0)
; #define PG8_LDB(dst, b, h) do { _Pragma("unroll") for (int n = 0; n < 2; ++n) _Pragma("unroll") for (int k = 0; k < 2; ++k) dst[n][k] = *(const LAS bf16x8*)(lds + PG8_SB(b, h) + boff + n * 2048 + k * 1024); } while (0)
; #define PG8_MMA(ai, bj, At, Bt) do { __builtin_amdgcn_s_setprio(1); _Pragma("unroll") for (int m = 0; m < 4; ++m) _Pragma("unroll") for (int n = 0; n < 2; ++n) _Pragma("unroll") for (int k = 0; k < 2; ++k) \
;         acc[ai][bj][m][n] = __builtin_amdgcn_mfma_f32_16x16x32_bf16(Bt[n][k], At[m][k], acc[ai][bj][m][n], 0, 0, 0); __builtin_amdgcn_s_setprio(0); } while (0)
; #define PG8_WAIT_V(n) asm volatile("s_waitcnt vmcnt(" #n ")" ::: "memory")
; #define PG8_WAIT_L(n) asm volatile("s_waitcnt lgkmcnt(" #n ")" ::: "memory")
; #define PG8_BAR __builtin_amdgcn_s_barrier()
; #define PG8_SCHED __builtin_amdgcn_sched_barrier(0)
; template <class Epi>
; __device__ __forceinline__ void gemm_phase(LAS unsigned char* lds, const Gemm g, const int G, const int cidx, const int tid, const Epi& E) {
;     ...
;             PG8_WAIT_V(8); PG8_WAIT_L(0); PG8_BAR; PG8_MMA(1, 0, At, B0); PG8_MMA(1, 1, At, B1); PG8_BAR; PG8_SCHED;
;             PG8_LDB(B0, 1, 0); PG8_LDB(B1, 1, 1); PG8_SCHED; PG8_LDA(At, 1, 0); PG8_STAGE(PG8_SA(0, 1), a2 + hstepA, voffA);
;             PG8_WAIT_V(8); PG8_WAIT_L(0); PG8_BAR; PG8_MMA(0, 0, At, B0); PG8_MMA(0, 1, At, B1); PG8_BAR; PG8_SCHED;
	s_setprio 1
	s_waitcnt lgkmcnt(0)
	v_mfma_f32_16x16x32_bf16 v[60:63], v[128:131], v[190:193], v[60:63]
	v_mfma_f32_16x16x32_bf16 v[56:59], v[148:151], v[190:193], v[56:59]
	v_mfma_f32_16x16x32_bf16 v[44:47], v[128:131], v[214:217], v[44:47]
	v_mfma_f32_16x16x32_bf16 v[40:43], v[148:151], v[214:217], v[40:43]
	v_mfma_f32_16x16x32_bf16 v[28:31], v[128:131], v[222:225], v[28:31]
	v_mfma_f32_16x16x32_bf16 v[24:27], v[148:151], v[222:225], v[24:27]
	v_mfma_f32_16x16x32_bf16 v[12:15], v[128:131], v[230:233], v[12:15]
	v_mfma_f32_16x16x32_bf16 v[8:11], v[148:151], v[230:233], v[8:11]
	v_mfma_f32_16x16x32_bf16 v[60:63], v[132:135], v[210:213], v[60:63]
	v_mfma_f32_16x16x32_bf16 v[56:59], v[164:167], v[210:213], v[56:59]
	v_mfma_f32_16x16x32_bf16 v[44:47], v[132:135], v[218:221], v[44:47]
	v_mfma_f32_16x16x32_bf16 v[40:43], v[164:167], v[218:221], v[40:43]
	v_mfma_f32_16x16x32_bf16 v[28:31], v[132:135], v[226:229], v[28:31]
	v_mfma_f32_16x16x32_bf16 v[24:27], v[164:167], v[226:229], v[24:27]
	v_mfma_f32_16x16x32_bf16 v[12:15], v[132:135], v[234:237], v[12:15]
	v_mfma_f32_16x16x32_bf16 v[8:11], v[164:167], v[234:237], v[8:11]
	s_setprio 0
	s_setprio 1
	v_mfma_f32_16x16x32_bf16 v[52:55], v[174:177], v[190:193], v[52:55]
	v_mfma_f32_16x16x32_bf16 v[48:51], v[182:185], v[190:193], v[48:51]
	v_mfma_f32_16x16x32_bf16 v[36:39], v[174:177], v[214:217], v[36:39]
	v_mfma_f32_16x16x32_bf16 v[32:35], v[182:185], v[214:217], v[32:35]
	v_mfma_f32_16x16x32_bf16 v[20:23], v[174:177], v[222:225], v[20:23]
	v_mfma_f32_16x16x32_bf16 v[16:19], v[182:185], v[222:225], v[16:19]
	v_mfma_f32_16x16x32_bf16 v[4:7], v[174:177], v[230:233], v[4:7]
	v_mfma_f32_16x16x32_bf16 v[0:3], v[182:185], v[230:233], v[0:3]
	v_mfma_f32_16x16x32_bf16 v[52:55], v[178:181], v[210:213], v[52:55]
	v_mfma_f32_16x16x32_bf16 v[48:51], v[186:189], v[210:213], v[48:51]
	v_mfma_f32_16x16x32_bf16 v[36:39], v[178:181], v[218:221], v[36:39]
	v_mfma_f32_16x16x32_bf16 v[32:35], v[186:189], v[218:221], v[32:35]
	v_mfma_f32_16x16x32_bf16 v[20:23], v[178:181], v[226:229], v[20:23]
	v_mfma_f32_16x16x32_bf16 v[16:19], v[186:189], v[226:229], v[16:19]
	v_mfma_f32_16x16x32_bf16 v[4:7], v[178:181], v[234:237], v[4:7]
	v_mfma_f32_16x16x32_bf16 v[0:3], v[186:189], v[234:237], v[0:3]
	s_setprio 0
	s_barrier
	s_add_i32 s66, 0, 0x18000
	s_add_i32 s67, 0, 0x1c000
	v_add_u32_e32 v164, s66, v163
	v_add_u32_e32 v173, s67, v163
	ds_read_b128 v[128:131], v164
	ds_read_b128 v[132:135], v164 offset:1024
	ds_read_b128 v[148:151], v164 offset:2048
	ds_read_b128 v[164:167], v164 offset:3072
	ds_read_b128 v[174:177], v173
	ds_read_b128 v[178:181], v173 offset:1024
	ds_read_b128 v[182:185], v173 offset:2048
	ds_read_b128 v[186:189], v173 offset:3072
	s_add_u32 s56, s56, 0x20000
	s_addc_u32 s57, s57, 0
	s_mov_b32 m0, s58
	v_lshl_add_u64 v[240:241], s[56:57], 0, v[136:137]
	ds_read_b128 v[190:193], v172 offset:32768
	ds_read_b128 v[210:213], v172 offset:33792
	ds_read_b128 v[214:217], v172 offset:34816
	ds_read_b128 v[218:221], v172 offset:35840
	ds_read_b128 v[222:225], v172 offset:36864
	ds_read_b128 v[226:229], v172 offset:37888
	ds_read_b128 v[230:233], v172 offset:38912
	ds_read_b128 v[234:237], v172 offset:39936
	global_load_lds_dwordx4 v[240:241], off
	v_lshl_add_u64 v[240:241], s[56:57], 0, v[138:139]
	s_mov_b32 m0, s59
	s_nop 0
	global_load_lds_dwordx4 v[240:241], off
	s_waitcnt vmcnt(8)
	s_waitcnt lgkmcnt(0)
	s_barrier
	s_setprio 1
	s_waitcnt lgkmcnt(0)
	v_mfma_f32_16x16x32_bf16 v[124:127], v[128:131], v[190:193], v[124:127]
	v_mfma_f32_16x16x32_bf16 v[120:123], v[148:151], v[190:193], v[120:123]
	v_mfma_f32_16x16x32_bf16 v[108:111], v[128:131], v[214:217], v[108:111]
	v_mfma_f32_16x16x32_bf16 v[104:107], v[148:151], v[214:217], v[104:107]
	v_mfma_f32_16x16x32_bf16 v[92:95], v[128:131], v[222:225], v[92:95]
	v_mfma_f32_16x16x32_bf16 v[88:91], v[148:151], v[222:225], v[88:91]
	v_mfma_f32_16x16x32_bf16 v[76:79], v[128:131], v[230:233], v[76:79]
	v_mfma_f32_16x16x32_bf16 v[72:75], v[148:151], v[230:233], v[72:75]
	v_mfma_f32_16x16x32_bf16 v[124:127], v[132:135], v[210:213], v[124:127]
	v_mfma_f32_16x16x32_bf16 v[120:123], v[164:167], v[210:213], v[120:123]
	v_mfma_f32_16x16x32_bf16 v[108:111], v[132:135], v[218:221], v[108:111]
	v_mfma_f32_16x16x32_bf16 v[104:107], v[164:167], v[218:221], v[104:107]
	v_mfma_f32_16x16x32_bf16 v[92:95], v[132:135], v[226:229], v[92:95]
	v_mfma_f32_16x16x32_bf16 v[88:91], v[164:167], v[226:229], v[88:91]
	v_mfma_f32_16x16x32_bf16 v[76:79], v[132:135], v[234:237], v[76:79]
	v_mfma_f32_16x16x32_bf16 v[72:75], v[164:167], v[234:237], v[72:75]
	s_setprio 0
	s_setprio 1
	v_mfma_f32_16x16x32_bf16 v[116:119], v[174:177], v[190:193], v[116:119]
	v_mfma_f32_16x16x32_bf16 v[112:115], v[182:185], v[190:193], v[112:115]
	v_mfma_f32_16x16x32_bf16 v[100:103], v[174:177], v[214:217], v[100:103]
	v_mfma_f32_16x16x32_bf16 v[96:99], v[182:185], v[214:217], v[96:99]
	v_mfma_f32_16x16x32_bf16 v[84:87], v[174:177], v[222:225], v[84:87]
	v_mfma_f32_16x16x32_bf16 v[80:83], v[182:185], v[222:225], v[80:83]
	v_mfma_f32_16x16x32_bf16 v[68:71], v[174:177], v[230:233], v[68:71]
	v_mfma_f32_16x16x32_bf16 v[64:67], v[182:185], v[230:233], v[64:67]
	v_mfma_f32_16x16x32_bf16 v[116:119], v[178:181], v[210:213], v[116:119]
	v_mfma_f32_16x16x32_bf16 v[112:115], v[186:189], v[210:213], v[112:115]
	v_mfma_f32_16x16x32_bf16 v[100:103], v[178:181], v[218:221], v[100:103]
	v_mfma_f32_16x16x32_bf16 v[96:99], v[186:189], v[218:221], v[96:99]
	v_mfma_f32_16x16x32_bf16 v[84:87], v[178:181], v[226:229], v[84:87]
	v_mfma_f32_16x16x32_bf16 v[80:83], v[186:189], v[226:229], v[80:83]
	v_mfma_f32_16x16x32_bf16 v[68:71], v[178:181], v[234:237], v[68:71]
	v_mfma_f32_16x16x32_bf16 v[64:67], v[186:189], v[234:237], v[64:67]
	s_setprio 0
	s_barrier
; #define PG8_STAGE(bufoff, gbase, voff) do { _Pragma("unroll") for (int _i = 0; _i < 2; ++_i) \
;         __builtin_amdgcn_global_load_lds((const unsigned*)((const char*)(gbase) + (voff)[_i]), (LAS unsigned*)(lds + (bufoff) + ldsw + _i * 8192), 16, 0, 0); } while (0)
; #define PG8_LDA(dst, b, h) do { _Pragma("unroll") for (int m = 0; m < 4; ++m) _Pragma("unroll") for (int k = 0; k < 2; ++k) dst[m][k] = *(const LAS bf16x8*)(lds + PG8_SA(b, h) + aoff + m * 2048 + k * 1024); } while (0)
; #define PG8_MMA(ai, bj, At, Bt) do { __builtin_amdgcn_s_setprio(1); _Pragma("unroll") for (int m = 0; m < 4; ++m) _Pragma("unroll") for (int n = 0; n < 2; ++n) _Pragma("unroll") for (int k = 0; k < 2; ++k) \
;         acc[ai][bj][m][n] = __builtin_amdgcn_mfma_f32_16x16x32_bf16(Bt[n][k], At[m][k], acc[ai][bj][m][n], 0, 0, 0); __builtin_amdgcn_s_setprio(0); } while (0)
; #define PG8_WAIT_V(n) asm volatile("s_waitcnt vmcnt(" #n ")" ::: "memory")
; #define PG8_WAIT_L(n) asm volatile("s_waitcnt lgkmcnt(" #n ")" ::: "memory")
; #define PG8_BAR __builtin_amdgcn_s_barrier()
; #define PG8_SCHED __builtin_amdgcn_sched_barrier(0)
; template <class Epi>
; __device__ __forceinline__ void gemm_phase(LAS unsigned char* lds, const Gemm g, const int G, const int cidx, const int tid, const Epi& E) {
;     ...
;         for (int t = 0; t < nt; t += 2) {
;     ...
;             PG8_LDA(At, 1, 1); PG8_STAGE(PG8_SB(1, 0), b3, voffB); PG8_STAGE(PG8_SB(1, 1), b3 + hstepB, voffB); PG8_STAGE(PG8_SA(1, 0), a3, voffA);
;             PG8_WAIT_V(8); PG8_WAIT_L(0); PG8_BAR; PG8_MMA(1, 0, At, B0); PG8_MMA(1, 1, At, B1); PG8_BAR; PG8_SCHED;
	s_add_i32 s56, s66, s29
	v_lshl_add_u64 v[158:159], v[158:159], 0, s[96:97]
	s_mov_b32 m0, s56
	ds_read_b128 v[190:193], v172 offset:49152
	ds_read_b128 v[210:213], v172 offset:50176
	ds_read_b128 v[214:217], v172 offset:51200
	ds_read_b128 v[218:221], v172 offset:52224
	ds_read_b128 v[222:225], v172 offset:53248
	ds_read_b128 v[226:229], v172 offset:54272
	ds_read_b128 v[230:233], v172 offset:55296
	ds_read_b128 v[234:237], v172 offset:56320
	global_load_lds_dwordx4 v[158:159], off
	s_add_i32 m0, s56, 0x2000
	s_add_u32 s54, s54, 0x20080
	v_lshl_add_u64 v[158:159], v[168:169], 0, s[96:97]
	s_addc_u32 s55, s55, 0
	s_add_i32 s56, s67, s29
	global_load_lds_dwordx4 v[158:159], off
	v_lshl_add_u64 v[158:159], s[54:55], 0, v[152:153]
	s_mov_b32 m0, s56
	s_nop 0
	global_load_lds_dwordx4 v[158:159], off
	v_lshl_add_u64 v[158:159], s[54:55], 0, v[140:141]
	s_add_i32 m0, s56, 0x2000
	s_nop 0
	global_load_lds_dwordx4 v[158:159], off
	v_lshl_add_u64 v[158:159], v[208:209], 0, s[96:97]
	s_mov_b32 m0, s62
	s_nop 0
	global_load_lds_dwordx4 v[158:159], off
	v_lshl_add_u64 v[158:159], v[238:239], 0, s[96:97]
	s_mov_b32 m0, s63
	s_nop 0
	global_load_lds_dwordx4 v[158:159], off
	s_waitcnt vmcnt(8)
	s_waitcnt lgkmcnt(0)
	s_barrier
	s_setprio 1
	s_waitcnt lgkmcnt(0)
	v_mfma_f32_16x16x32_bf16 v[60:63], v[128:131], v[190:193], v[60:63]
	v_mfma_f32_16x16x32_bf16 v[56:59], v[148:151], v[190:193], v[56:59]
	v_mfma_f32_16x16x32_bf16 v[44:47], v[128:131], v[214:217], v[44:47]
	v_mfma_f32_16x16x32_bf16 v[40:43], v[148:151], v[214:217], v[40:43]
	v_mfma_f32_16x16x32_bf16 v[28:31], v[128:131], v[222:225], v[28:31]
	v_mfma_f32_16x16x32_bf16 v[24:27], v[148:151], v[222:225], v[24:27]
	v_mfma_f32_16x16x32_bf16 v[12:15], v[128:131], v[230:233], v[12:15]
	v_mfma_f32_16x16x32_bf16 v[8:11], v[148:151], v[230:233], v[8:11]
	v_mfma_f32_16x16x32_bf16 v[60:63], v[132:135], v[210:213], v[60:63]
	v_mfma_f32_16x16x32_bf16 v[56:59], v[164:167], v[210:213], v[56:59]
	v_mfma_f32_16x16x32_bf16 v[44:47], v[132:135], v[218:221], v[44:47]
	v_mfma_f32_16x16x32_bf16 v[40:43], v[164:167], v[218:221], v[40:43]
	v_mfma_f32_16x16x32_bf16 v[28:31], v[132:135], v[226:229], v[28:31]
	v_mfma_f32_16x16x32_bf16 v[24:27], v[164:167], v[226:229], v[24:27]
	v_mfma_f32_16x16x32_bf16 v[12:15], v[132:135], v[234:237], v[12:15]
	v_mfma_f32_16x16x32_bf16 v[8:11], v[164:167], v[234:237], v[8:11]
	s_setprio 0
	s_setprio 1
	v_mfma_f32_16x16x32_bf16 v[52:55], v[174:177], v[190:193], v[52:55]
	v_mfma_f32_16x16x32_bf16 v[48:51], v[182:185], v[190:193], v[48:51]
	v_mfma_f32_16x16x32_bf16 v[36:39], v[174:177], v[214:217], v[36:39]
	v_mfma_f32_16x16x32_bf16 v[32:35], v[182:185], v[214:217], v[32:35]
	v_mfma_f32_16x16x32_bf16 v[20:23], v[174:177], v[222:225], v[20:23]
	v_mfma_f32_16x16x32_bf16 v[16:19], v[182:185], v[222:225], v[16:19]
	v_mfma_f32_16x16x32_bf16 v[4:7], v[174:177], v[230:233], v[4:7]
	v_mfma_f32_16x16x32_bf16 v[0:3], v[182:185], v[230:233], v[0:3]
	v_mfma_f32_16x16x32_bf16 v[52:55], v[178:181], v[210:213], v[52:55]
	v_mfma_f32_16x16x32_bf16 v[48:51], v[186:189], v[210:213], v[48:51]
	v_mfma_f32_16x16x32_bf16 v[36:39], v[178:181], v[218:221], v[36:39]
	v_mfma_f32_16x16x32_bf16 v[32:35], v[186:189], v[218:221], v[32:35]
	v_mfma_f32_16x16x32_bf16 v[20:23], v[178:181], v[226:229], v[20:23]
	v_mfma_f32_16x16x32_bf16 v[16:19], v[186:189], v[226:229], v[16:19]
	v_mfma_f32_16x16x32_bf16 v[4:7], v[178:181], v[234:237], v[4:7]
	v_mfma_f32_16x16x32_bf16 v[0:3], v[186:189], v[234:237], v[0:3]
	s_setprio 0
	s_add_i32 s95, s95, 2
	s_add_u32 s52, s52, 0x100
	s_addc_u32 s53, s53, 0
	s_add_u32 s92, s92, 0x100
	s_addc_u32 s94, s94, 0
	s_barrier
	s_cmp_gt_u32 s95, 5
	s_cbranch_scc0 .LBB0_466
	s_and_b64 vcc, exec, s[6:7]
	v_readlane_b32 s94, v255, 3
	v_readlane_b32 s92, v255, 5
	v_readlane_b32 s95, v255, 4
	s_cbranch_vccz .LBB0_469
	s_barrier

; #define PG8_STAGE(bufoff, gbase, voff) do { _Pragma("unroll") for (int _i = 0; _i < 2; ++_i) \
;         __builtin_amdgcn_global_load_lds((const unsigned*)((const char*)(gbase) + (voff)[_i]), (LAS unsigned*)(lds + (bufoff) + ldsw + _i * 8192), 16, 0, 0); } while (0)
; #define PG8_LDA(dst, b, h) do { _Pragma("unroll") for (int m = 0; m < 4; ++m) _Pragma("unroll") for (int k = 0; k < 2; ++k) dst[m][k] = *(const LAS bf16x8*)(lds + PG8_SA(b, h) + aoff + m * 2048 + k * 1024); } while (0)
; #define PG8_LDB(dst, b, h) do { _Pragma("unroll") for (int n = 0; n < 2; ++n) _Pragma("unroll") for (int k = 0; k < 2; ++k) dst[n][k] = *(const LAS bf16x8*)(lds + PG8_SB(b, h) + boff + n * 2048 + k * 1024); } while (0)
; #define PG8_MMA(ai, bj, At, Bt) do { __builtin_amdgcn_s_setprio(1); _Pragma("unroll") for (int m = 0; m < 4; ++m) _Pragma("unroll") for (int n = 0; n < 2; ++n) _Pragma("unroll") for (int k = 0; k < 2; ++k) \
;         acc[ai][bj][m][n] = __builtin_amdgcn_mfma_f32_16x16x32_bf16(Bt[n][k], At[m][k], acc[ai][bj][m][n], 0, 0, 0); __builtin_amdgcn_s_setprio(0); } while (0)
; #define PG8_WAIT_V(n) asm volatile("s_waitcnt vmcnt(" #n ")" ::: "memory")
; #define PG8_WAIT_L(n) asm volatile("s_waitcnt lgkmcnt(" #n ")" ::: "memory")
; #define PG8_BAR __builtin_amdgcn_s_barrier()
; #define PG8_SCHED __builtin_amdgcn_sched_barrier(0)
; template <class Epi>
; __device__ __forceinline__ void gemm_phase(LAS unsigned char* lds, const Gemm g, const int G, const int cidx, const int tid, const Epi& E) {
;     ...
;             const bool last = (t == nt - 2);
;             const char* a1 = cA + (size_t)(t + 1) * kstep;
;             const char* a2 = last ? nA : cA + (size_t)(t + 2) * kstep; const char* b2 = last ? nB : cB + (size_t)(t + 2) * kstep;
;             const char* a3 = a2 + kstep; const char* b3 = b2 + kstep;
;             PG8_LDB(B0, 0, 0); PG8_LDB(B1, 0, 1); PG8_SCHED; PG8_LDA(At, 0, 0); PG8_STAGE(PG8_SA(1, 1), a1 + hstepA, voffA);
;             PG8_WAIT_V(8); PG8_WAIT_L(0); PG8_BAR; PG8_MMA(0, 0, At, B0); PG8_MMA(0, 1, At, B1); PG8_BAR; PG8_SCHED;
;             PG8_LDA(At, 0, 1); PG8_STAGE(PG8_SB(0, 0), b2, voffB); PG8_STAGE(PG8_SB(0, 1), b2 + hstepB, voffB); PG8_STAGE(PG8_SA(0, 0), a2, voffA);
.LBB0_595:
	s_add_u32 s30, s54, 0xfff00080
	s_addc_u32 s56, s55, -1
	s_add_i32 s66, 0, 0x10000
	s_cmp_eq_u32 vcc_lo, 60
	s_cselect_b32 s59, s17, s56
	s_cselect_b32 s58, s34, s30
	s_cselect_b32 s57, s15, s95
	s_cselect_b32 s56, s35, s92
	s_add_i32 s30, 0, 0x14000
	v_add_u32_e32 v124, s66, v217
	v_add_u32_e32 v152, s30, v217
	ds_read_b128 v[112:115], v124
	ds_read_b128 v[116:119], v124 offset:1024
	ds_read_b128 v[120:123], v124 offset:2048
	ds_read_b128 v[124:127], v124 offset:3072
	ds_read_b128 v[128:131], v152
	ds_read_b128 v[140:143], v152 offset:1024
	ds_read_b128 v[178:181], v152 offset:2048
	ds_read_b128 v[182:185], v152 offset:3072
	v_lshl_add_u64 v[158:159], s[54:55], 0, v[174:175]
	s_add_i32 m0, s25, 0xc000
	ds_read_b128 v[186:189], v218
	ds_read_b128 v[190:193], v218 offset:1024
	ds_read_b128 v[220:223], v218 offset:2048
	ds_read_b128 v[224:227], v218 offset:3072
	ds_read_b128 v[228:231], v218 offset:4096
	ds_read_b128 v[232:235], v218 offset:5120
	ds_read_b128 v[236:239], v218 offset:6144
	ds_read_b128 v[240:243], v218 offset:7168
	global_load_lds_dwordx4 v[158:159], off
	v_lshl_add_u64 v[158:159], s[54:55], 0, v[176:177]
	s_add_i32 m0, s25, 0xe000
	s_nop 0
	global_load_lds_dwordx4 v[158:159], off
	s_waitcnt vmcnt(8)
	s_waitcnt lgkmcnt(0)
	s_barrier
	s_setprio 1
	s_waitcnt lgkmcnt(0)
	v_mfma_f32_16x16x32_bf16 v[148:151], v[112:115], v[186:189], v[148:151]
	v_mfma_f32_16x16x32_bf16 v[144:147], v[120:123], v[186:189], v[144:147]
	v_mfma_f32_16x16x32_bf16 v[108:111], v[112:115], v[220:223], v[108:111]
	v_mfma_f32_16x16x32_bf16 v[104:107], v[120:123], v[220:223], v[104:107]
	v_mfma_f32_16x16x32_bf16 v[92:95], v[112:115], v[228:231], v[92:95]
	v_mfma_f32_16x16x32_bf16 v[88:91], v[120:123], v[228:231], v[88:91]
	v_mfma_f32_16x16x32_bf16 v[76:79], v[112:115], v[236:239], v[76:79]
	v_mfma_f32_16x16x32_bf16 v[72:75], v[120:123], v[236:239], v[72:75]
	v_mfma_f32_16x16x32_bf16 v[148:151], v[116:119], v[190:193], v[148:151]
	v_mfma_f32_16x16x32_bf16 v[144:147], v[124:127], v[190:193], v[144:147]
	v_mfma_f32_16x16x32_bf16 v[108:111], v[116:119], v[224:227], v[108:111]
	v_mfma_f32_16x16x32_bf16 v[104:107], v[124:127], v[224:227], v[104:107]
	v_mfma_f32_16x16x32_bf16 v[92:95], v[116:119], v[232:235], v[92:95]
	v_mfma_f32_16x16x32_bf16 v[88:91], v[124:127], v[232:235], v[88:91]
	v_mfma_f32_16x16x32_bf16 v[76:79], v[116:119], v[240:243], v[76:79]
	v_mfma_f32_16x16x32_bf16 v[72:75], v[124:127], v[240:243], v[72:75]
	s_setprio 0
	s_setprio 1
	v_mfma_f32_16x16x32_bf16 v[136:139], v[128:131], v[186:189], v[136:139]
	v_mfma_f32_16x16x32_bf16 v[132:135], v[178:181], v[186:189], v[132:135]
	v_mfma_f32_16x16x32_bf16 v[100:103], v[128:131], v[220:223], v[100:103]
	v_mfma_f32_16x16x32_bf16 v[96:99], v[178:181], v[220:223], v[96:99]
	v_mfma_f32_16x16x32_bf16 v[84:87], v[128:131], v[228:231], v[84:87]
	v_mfma_f32_16x16x32_bf16 v[80:83], v[178:181], v[228:231], v[80:83]
	v_mfma_f32_16x16x32_bf16 v[68:71], v[128:131], v[236:239], v[68:71]
	v_mfma_f32_16x16x32_bf16 v[64:67], v[178:181], v[236:239], v[64:67]
	v_mfma_f32_16x16x32_bf16 v[136:139], v[140:143], v[190:193], v[136:139]
	v_mfma_f32_16x16x32_bf16 v[132:135], v[182:185], v[190:193], v[132:135]
	v_mfma_f32_16x16x32_bf16 v[100:103], v[140:143], v[224:227], v[100:103]
	v_mfma_f32_16x16x32_bf16 v[96:99], v[182:185], v[224:227], v[96:99]
	v_mfma_f32_16x16x32_bf16 v[84:87], v[140:143], v[232:235], v[84:87]
	v_mfma_f32_16x16x32_bf16 v[80:83], v[182:185], v[232:235], v[80:83]
	v_mfma_f32_16x16x32_bf16 v[68:71], v[140:143], v[240:243], v[68:71]
	v_mfma_f32_16x16x32_bf16 v[64:67], v[182:185], v[240:243], v[64:67]
	s_setprio 0
	s_barrier
	s_add_i32 s66, s66, s24
	v_lshl_add_u64 v[158:159], s[56:57], 0, v[168:169]
	s_mov_b32 m0, s66
	ds_read_b128 v[186:189], v218 offset:16384
	ds_read_b128 v[190:193], v218 offset:17408
	ds_read_b128 v[220:223], v218 offset:18432
	ds_read_b128 v[224:227], v218 offset:19456
	ds_read_b128 v[228:231], v218 offset:20480
	ds_read_b128 v[232:235], v218 offset:21504
	ds_read_b128 v[236:239], v218 offset:22528
	ds_read_b128 v[240:243], v218 offset:23552
	global_load_lds_dwordx4 v[158:159], off
	s_add_i32 m0, s66, 0x2000
	s_add_u32 s66, s56, 0x100000
	v_lshl_add_u64 v[244:245], s[56:57], 0, v[172:173]
	s_addc_u32 s67, s57, 0
	s_add_i32 s30, s30, s24
	global_load_lds_dwordx4 v[244:245], off
	v_lshl_add_u64 v[246:247], s[66:67], 0, v[168:169]
	s_mov_b32 m0, s30
	v_lshl_add_u64 v[248:249], s[58:59], 0, v[170:171]
	global_load_lds_dwordx4 v[246:247], off
	v_lshl_add_u64 v[246:247], s[66:67], 0, v[172:173]
	s_add_i32 m0, s30, 0x2000
	s_nop 0
	global_load_lds_dwordx4 v[246:247], off
	v_lshl_add_u64 v[246:247], s[58:59], 0, v[166:167]
	s_mov_b32 m0, s25
	s_nop 0
	global_load_lds_dwordx4 v[246:247], off
	s_mov_b32 m0, s29
	s_nop 0
	global_load_lds_dwordx4 v[248:249], off
	s_waitcnt vmcnt(8)
	s_waitcnt lgkmcnt(0)
	s_barrier
; #define PG8_STAGE(bufoff, gbase, voff) do { _Pragma("unroll") for (int _i = 0; _i < 2; ++_i) \
;         __builtin_amdgcn_global_load_lds((const unsigned*)((const char*)(gbase) + (voff)[_i]), (LAS unsigned*)(lds + (bufoff) + ldsw + _i * 8192), 16, 0, 0); } while (0)
; #define PG8_LDA(dst, b, h) do { _Pragma("unroll") for (int m = 0; m < 4; ++m) _Pragma("unroll") for (int k = 0; k < 2; ++k) dst[m][k] = *(const LAS bf16x8*)(lds + PG8_SA(b, h) + aoff + m * 2048 + k * 1024); } while (0)
; #define PG8_LDB(dst, b, h) do { _Pragma("unroll") for (int n = 0; n < 2; ++n) _Pragma("unroll") for (int k = 0; k < 2; ++k) dst[n][k] = *(const LAS bf16x8*)(lds + PG8_SB(b, h) + boff + n * 2048 + k * 1024); } while (0)
; #define PG8_MMA(ai, bj, At, Bt) do { __builtin_amdgcn_s_setprio(1); _Pragma("unroll") for (int m = 0; m < 4; ++m) _Pragma("unroll") for (int n = 0; n < 2; ++n) _Pragma("unroll") for (int k = 0; k < 2; ++k) \
;         acc[ai][bj][m][n] = __builtin_amdgcn_mfma_f32_16x16x32_bf16(Bt[n][k], At[m][k], acc[ai][bj][m][n], 0, 0, 0); __builtin_amdgcn_s_setprio(0); } while (0)
; #define PG8_WAIT_V(n) asm volatile("s_waitcnt vmcnt(" #n ")" ::: "memory")
; #define PG8_WAIT_L(n) asm volatile("s_waitcnt lgkmcnt(" #n ")" ::: "memory")
; #define PG8_BAR __builtin_amdgcn_s_barrier()
; #define PG8_SCHED __builtin_amdgcn_sched_barrier(0)
; template <class Epi>
; __device__ __forceinline__ void gemm_phase(LAS unsigned char* lds, const Gemm g, const int G, const int cidx, const int tid, const Epi& E) {
;     ...
;             PG8_WAIT_V(8); PG8_WAIT_L(0); PG8_BAR; PG8_MMA(1, 0, At, B0); PG8_MMA(1, 1, At, B1); PG8_BAR; PG8_SCHED;
;             PG8_LDB(B0, 1, 0); PG8_LDB(B1, 1, 1); PG8_SCHED; PG8_LDA(At, 1, 0); PG8_STAGE(PG8_SA(0, 1), a2 + hstepA, voffA);
;             PG8_WAIT_V(8); PG8_WAIT_L(0); PG8_BAR; PG8_MMA(0, 0, At, B0); PG8_MMA(0, 1, At, B1); PG8_BAR; PG8_SCHED;
	s_setprio 1
	s_waitcnt lgkmcnt(0)
	v_mfma_f32_16x16x32_bf16 v[60:63], v[112:115], v[186:189], v[60:63]
	v_mfma_f32_16x16x32_bf16 v[56:59], v[120:123], v[186:189], v[56:59]
	v_mfma_f32_16x16x32_bf16 v[44:47], v[112:115], v[220:223], v[44:47]
	v_mfma_f32_16x16x32_bf16 v[40:43], v[120:123], v[220:223], v[40:43]
	v_mfma_f32_16x16x32_bf16 v[28:31], v[112:115], v[228:231], v[28:31]
	v_mfma_f32_16x16x32_bf16 v[24:27], v[120:123], v[228:231], v[24:27]
	v_mfma_f32_16x16x32_bf16 v[12:15], v[112:115], v[236:239], v[12:15]
	v_mfma_f32_16x16x32_bf16 v[8:11], v[120:123], v[236:239], v[8:11]
	v_mfma_f32_16x16x32_bf16 v[60:63], v[116:119], v[190:193], v[60:63]
	v_mfma_f32_16x16x32_bf16 v[56:59], v[124:127], v[190:193], v[56:59]
	v_mfma_f32_16x16x32_bf16 v[44:47], v[116:119], v[224:227], v[44:47]
	v_mfma_f32_16x16x32_bf16 v[40:43], v[124:127], v[224:227], v[40:43]
	v_mfma_f32_16x16x32_bf16 v[28:31], v[116:119], v[232:235], v[28:31]
	v_mfma_f32_16x16x32_bf16 v[24:27], v[124:127], v[232:235], v[24:27]
	v_mfma_f32_16x16x32_bf16 v[12:15], v[116:119], v[240:243], v[12:15]
	v_mfma_f32_16x16x32_bf16 v[8:11], v[124:127], v[240:243], v[8:11]
	s_setprio 0
	s_setprio 1
	v_mfma_f32_16x16x32_bf16 v[52:55], v[128:131], v[186:189], v[52:55]
	v_mfma_f32_16x16x32_bf16 v[48:51], v[178:181], v[186:189], v[48:51]
	v_mfma_f32_16x16x32_bf16 v[36:39], v[128:131], v[220:223], v[36:39]
	v_mfma_f32_16x16x32_bf16 v[32:35], v[178:181], v[220:223], v[32:35]
	v_mfma_f32_16x16x32_bf16 v[20:23], v[128:131], v[228:231], v[20:23]
	v_mfma_f32_16x16x32_bf16 v[16:19], v[178:181], v[228:231], v[16:19]
	v_mfma_f32_16x16x32_bf16 v[4:7], v[128:131], v[236:239], v[4:7]
	v_mfma_f32_16x16x32_bf16 v[0:3], v[178:181], v[236:239], v[0:3]
	v_mfma_f32_16x16x32_bf16 v[52:55], v[140:143], v[190:193], v[52:55]
	v_mfma_f32_16x16x32_bf16 v[48:51], v[182:185], v[190:193], v[48:51]
	v_mfma_f32_16x16x32_bf16 v[36:39], v[140:143], v[224:227], v[36:39]
	v_mfma_f32_16x16x32_bf16 v[32:35], v[182:185], v[224:227], v[32:35]
	v_mfma_f32_16x16x32_bf16 v[20:23], v[140:143], v[232:235], v[20:23]
	v_mfma_f32_16x16x32_bf16 v[16:19], v[182:185], v[232:235], v[16:19]
	v_mfma_f32_16x16x32_bf16 v[4:7], v[140:143], v[240:243], v[4:7]
	v_mfma_f32_16x16x32_bf16 v[0:3], v[182:185], v[240:243], v[0:3]
	s_setprio 0
	s_barrier
	s_add_i32 s30, 0, 0x18000
	s_add_i32 s66, 0, 0x1c000
	v_add_u32_e32 v124, s30, v217
	v_add_u32_e32 v152, s66, v217
	ds_read_b128 v[112:115], v124
	ds_read_b128 v[116:119], v124 offset:1024
	ds_read_b128 v[120:123], v124 offset:2048
	ds_read_b128 v[124:127], v124 offset:3072
	ds_read_b128 v[128:131], v152
	ds_read_b128 v[140:143], v152 offset:1024
	ds_read_b128 v[178:181], v152 offset:2048
	ds_read_b128 v[182:185], v152 offset:3072
	s_add_u32 s58, s58, 0x100000
	s_addc_u32 s59, s59, 0
	s_mov_b32 m0, s31
	v_lshl_add_u64 v[250:251], s[58:59], 0, v[166:167]
	ds_read_b128 v[186:189], v218 offset:32768
	ds_read_b128 v[190:193], v218 offset:33792
	ds_read_b128 v[220:223], v218 offset:34816
	ds_read_b128 v[224:227], v218 offset:35840
	ds_read_b128 v[228:231], v218 offset:36864
	ds_read_b128 v[232:235], v218 offset:37888
	ds_read_b128 v[236:239], v218 offset:38912
	ds_read_b128 v[240:243], v218 offset:39936
	global_load_lds_dwordx4 v[250:251], off
	v_lshl_add_u64 v[250:251], s[58:59], 0, v[170:171]
	s_mov_b32 m0, s61
	s_nop 0
	global_load_lds_dwordx4 v[250:251], off
	s_waitcnt vmcnt(8)
	s_waitcnt lgkmcnt(0)
	s_barrier
	s_setprio 1
	s_waitcnt lgkmcnt(0)
	v_mfma_f32_16x16x32_bf16 v[148:151], v[112:115], v[186:189], v[148:151]
	v_mfma_f32_16x16x32_bf16 v[144:147], v[120:123], v[186:189], v[144:147]
	v_mfma_f32_16x16x32_bf16 v[108:111], v[112:115], v[220:223], v[108:111]
	v_mfma_f32_16x16x32_bf16 v[104:107], v[120:123], v[220:223], v[104:107]
	v_mfma_f32_16x16x32_bf16 v[92:95], v[112:115], v[228:231], v[92:95]
	v_mfma_f32_16x16x32_bf16 v[88:91], v[120:123], v[228:231], v[88:91]
	v_mfma_f32_16x16x32_bf16 v[76:79], v[112:115], v[236:239], v[76:79]
	v_mfma_f32_16x16x32_bf16 v[72:75], v[120:123], v[236:239], v[72:75]
	v_mfma_f32_16x16x32_bf16 v[148:151], v[116:119], v[190:193], v[148:151]
	v_mfma_f32_16x16x32_bf16 v[144:147], v[124:127], v[190:193], v[144:147]
	v_mfma_f32_16x16x32_bf16 v[108:111], v[116:119], v[224:227], v[108:111]
	v_mfma_f32_16x16x32_bf16 v[104:107], v[124:127], v[224:227], v[104:107]
	v_mfma_f32_16x16x32_bf16 v[92:95], v[116:119], v[232:235], v[92:95]
	v_mfma_f32_16x16x32_bf16 v[88:91], v[124:127], v[232:235], v[88:91]
	v_mfma_f32_16x16x32_bf16 v[76:79], v[116:119], v[240:243], v[76:79]
	v_mfma_f32_16x16x32_bf16 v[72:75], v[124:127], v[240:243], v[72:75]
	s_setprio 0
	s_setprio 1
	v_mfma_f32_16x16x32_bf16 v[136:139], v[128:131], v[186:189], v[136:139]
	v_mfma_f32_16x16x32_bf16 v[132:135], v[178:181], v[186:189], v[132:135]
	v_mfma_f32_16x16x32_bf16 v[100:103], v[128:131], v[220:223], v[100:103]
	v_mfma_f32_16x16x32_bf16 v[96:99], v[178:181], v[220:223], v[96:99]
	v_mfma_f32_16x16x32_bf16 v[84:87], v[128:131], v[228:231], v[84:87]
	v_mfma_f32_16x16x32_bf16 v[80:83], v[178:181], v[228:231], v[80:83]
	v_mfma_f32_16x16x32_bf16 v[68:71], v[128:131], v[236:239], v[68:71]
	v_mfma_f32_16x16x32_bf16 v[64:67], v[178:181], v[236:239], v[64:67]
	v_mfma_f32_16x16x32_bf16 v[136:139], v[140:143], v[190:193], v[136:139]
	v_mfma_f32_16x16x32_bf16 v[132:135], v[182:185], v[190:193], v[132:135]
	v_mfma_f32_16x16x32_bf16 v[100:103], v[140:143], v[224:227], v[100:103]
	v_mfma_f32_16x16x32_bf16 v[96:99], v[182:185], v[224:227], v[96:99]
	v_mfma_f32_16x16x32_bf16 v[84:87], v[140:143], v[232:235], v[84:87]
	v_mfma_f32_16x16x32_bf16 v[80:83], v[182:185], v[232:235], v[80:83]
	v_mfma_f32_16x16x32_bf16 v[68:71], v[140:143], v[240:243], v[68:71]
	v_mfma_f32_16x16x32_bf16 v[64:67], v[182:185], v[240:243], v[64:67]
	s_setprio 0
	s_barrier
; #define PG8_STAGE(bufoff, gbase, voff) do { _Pragma("unroll") for (int _i = 0; _i < 2; ++_i) \
;         __builtin_amdgcn_global_load_lds((const unsigned*)((const char*)(gbase) + (voff)[_i]), (LAS unsigned*)(lds + (bufoff) + ldsw + _i * 8192), 16, 0, 0); } while (0)
; #define PG8_LDA(dst, b, h) do { _Pragma("unroll") for (int m = 0; m < 4; ++m) _Pragma("unroll") for (int k = 0; k < 2; ++k) dst[m][k] = *(const LAS bf16x8*)(lds + PG8_SA(b, h) + aoff + m * 2048 + k * 1024); } while (0)
; #define PG8_MMA(ai, bj, At, Bt) do { __builtin_amdgcn_s_setprio(1); _Pragma("unroll") for (int m = 0; m < 4; ++m) _Pragma("unroll") for (int n = 0; n < 2; ++n) _Pragma("unroll") for (int k = 0; k < 2; ++k) \
;         acc[ai][bj][m][n] = __builtin_amdgcn_mfma_f32_16x16x32_bf16(Bt[n][k], At[m][k], acc[ai][bj][m][n], 0, 0, 0); __builtin_amdgcn_s_setprio(0); } while (0)
; #define PG8_WAIT_V(n) asm volatile("s_waitcnt vmcnt(" #n ")" ::: "memory")
; #define PG8_WAIT_L(n) asm volatile("s_waitcnt lgkmcnt(" #n ")" ::: "memory")
; #define PG8_BAR __builtin_amdgcn_s_barrier()
; #define PG8_SCHED __builtin_amdgcn_sched_barrier(0)
; template <class Epi>
; __device__ __forceinline__ void gemm_phase(LAS unsigned char* lds, const Gemm g, const int G, const int cidx, const int tid, const Epi& E) {
;     ...
;         for (int t = 0; t < nt; t += 2) {
;     ...
;             PG8_LDA(At, 1, 1); PG8_STAGE(PG8_SB(1, 0), b3, voffB); PG8_STAGE(PG8_SB(1, 1), b3 + hstepB, voffB); PG8_STAGE(PG8_SA(1, 0), a3, voffA);
;             PG8_WAIT_V(8); PG8_WAIT_L(0); PG8_BAR; PG8_MMA(1, 0, At, B0); PG8_MMA(1, 1, At, B1); PG8_BAR; PG8_SCHED;
	s_add_i32 s30, s30, s24
	v_lshl_add_u64 v[158:159], v[158:159], 0, s[96:97]
	s_mov_b32 m0, s30
	ds_read_b128 v[186:189], v218 offset:49152
	ds_read_b128 v[190:193], v218 offset:50176
	ds_read_b128 v[220:223], v218 offset:51200
	ds_read_b128 v[224:227], v218 offset:52224
	ds_read_b128 v[228:231], v218 offset:53248
	ds_read_b128 v[232:235], v218 offset:54272
	ds_read_b128 v[236:239], v218 offset:55296
	ds_read_b128 v[240:243], v218 offset:56320
	global_load_lds_dwordx4 v[158:159], off
	s_add_i32 m0, s30, 0x2000
	s_add_u32 s56, s56, 0x100080
	v_lshl_add_u64 v[158:159], v[244:245], 0, s[96:97]
	s_addc_u32 s57, s57, 0
	s_add_i32 s30, s66, s24
	global_load_lds_dwordx4 v[158:159], off
	v_lshl_add_u64 v[158:159], s[56:57], 0, v[168:169]
	s_mov_b32 m0, s30
	s_nop 0
	global_load_lds_dwordx4 v[158:159], off
	v_lshl_add_u64 v[158:159], s[56:57], 0, v[172:173]
	s_add_i32 m0, s30, 0x2000
	s_nop 0
	global_load_lds_dwordx4 v[158:159], off
	v_lshl_add_u64 v[158:159], v[246:247], 0, s[96:97]
	s_mov_b32 m0, s64
	s_nop 0
	global_load_lds_dwordx4 v[158:159], off
	v_lshl_add_u64 v[158:159], v[248:249], 0, s[96:97]
	s_mov_b32 m0, s65
	s_nop 0
	global_load_lds_dwordx4 v[158:159], off
	s_waitcnt vmcnt(8)
	s_waitcnt lgkmcnt(0)
	s_barrier
	s_setprio 1
	s_waitcnt lgkmcnt(0)
	v_mfma_f32_16x16x32_bf16 v[60:63], v[112:115], v[186:189], v[60:63]
	v_mfma_f32_16x16x32_bf16 v[56:59], v[120:123], v[186:189], v[56:59]
	v_mfma_f32_16x16x32_bf16 v[44:47], v[112:115], v[220:223], v[44:47]
	v_mfma_f32_16x16x32_bf16 v[40:43], v[120:123], v[220:223], v[40:43]
	v_mfma_f32_16x16x32_bf16 v[28:31], v[112:115], v[228:231], v[28:31]
	v_mfma_f32_16x16x32_bf16 v[24:27], v[120:123], v[228:231], v[24:27]
	v_mfma_f32_16x16x32_bf16 v[12:15], v[112:115], v[236:239], v[12:15]
	v_mfma_f32_16x16x32_bf16 v[8:11], v[120:123], v[236:239], v[8:11]
	v_mfma_f32_16x16x32_bf16 v[60:63], v[116:119], v[190:193], v[60:63]
	v_mfma_f32_16x16x32_bf16 v[56:59], v[124:127], v[190:193], v[56:59]
	v_mfma_f32_16x16x32_bf16 v[44:47], v[116:119], v[224:227], v[44:47]
	v_mfma_f32_16x16x32_bf16 v[40:43], v[124:127], v[224:227], v[40:43]
	v_mfma_f32_16x16x32_bf16 v[28:31], v[116:119], v[232:235], v[28:31]
	v_mfma_f32_16x16x32_bf16 v[24:27], v[124:127], v[232:235], v[24:27]
	v_mfma_f32_16x16x32_bf16 v[12:15], v[116:119], v[240:243], v[12:15]
	v_mfma_f32_16x16x32_bf16 v[8:11], v[124:127], v[240:243], v[8:11]
	s_setprio 0
	s_setprio 1
	v_mfma_f32_16x16x32_bf16 v[52:55], v[128:131], v[186:189], v[52:55]
	v_mfma_f32_16x16x32_bf16 v[48:51], v[178:181], v[186:189], v[48:51]
	v_mfma_f32_16x16x32_bf16 v[36:39], v[128:131], v[220:223], v[36:39]
	v_mfma_f32_16x16x32_bf16 v[32:35], v[178:181], v[220:223], v[32:35]
	v_mfma_f32_16x16x32_bf16 v[20:23], v[128:131], v[228:231], v[20:23]
	v_mfma_f32_16x16x32_bf16 v[16:19], v[178:181], v[228:231], v[16:19]
	v_mfma_f32_16x16x32_bf16 v[4:7], v[128:131], v[236:239], v[4:7]
	v_mfma_f32_16x16x32_bf16 v[0:3], v[178:181], v[236:239], v[0:3]
	v_mfma_f32_16x16x32_bf16 v[52:55], v[140:143], v[190:193], v[52:55]
	v_mfma_f32_16x16x32_bf16 v[48:51], v[182:185], v[190:193], v[48:51]
	v_mfma_f32_16x16x32_bf16 v[36:39], v[140:143], v[224:227], v[36:39]
	v_mfma_f32_16x16x32_bf16 v[32:35], v[182:185], v[224:227], v[32:35]
	v_mfma_f32_16x16x32_bf16 v[20:23], v[140:143], v[232:235], v[20:23]
	v_mfma_f32_16x16x32_bf16 v[16:19], v[182:185], v[232:235], v[16:19]
	v_mfma_f32_16x16x32_bf16 v[4:7], v[140:143], v[240:243], v[4:7]
	v_mfma_f32_16x16x32_bf16 v[0:3], v[182:185], v[240:243], v[0:3]
	s_setprio 0
	s_add_i32 vcc_lo, vcc_lo, 2
	s_add_u32 s54, s54, 0x100
	s_addc_u32 s55, s55, 0
	s_add_u32 s92, s92, 0x100
	s_addc_u32 s95, s95, 0
	s_barrier
	s_cmp_gt_u32 vcc_lo, 61
	s_cbranch_scc0 .LBB0_595
	s_and_b64 vcc, exec, s[12:13]
	s_cbranch_vccz .LBB0_598
	s_barrier

; #define PG8_STAGE(bufoff, gbase, voff) do { _Pragma("unroll") for (int _i = 0; _i < 2; ++_i) \
;         __builtin_amdgcn_global_load_lds((const unsigned*)((const char*)(gbase) + (voff)[_i]), (LAS unsigned*)(lds + (bufoff) + ldsw + _i * 8192), 16, 0, 0); } while (0)
; #define PG8_LDA(dst, b, h) do { _Pragma("unroll") for (int m = 0; m < 4; ++m) _Pragma("unroll") for (int k = 0; k < 2; ++k) dst[m][k] = *(const LAS bf16x8*)(lds + PG8_SA(b, h) + aoff + m * 2048 + k * 1024); } while (0)
; #define PG8_LDB(dst, b, h) do { _Pragma("unroll") for (int n = 0; n < 2; ++n) _Pragma("unroll") for (int k = 0; k < 2; ++k) dst[n][k] = *(const LAS bf16x8*)(lds + PG8_SB(b, h) + boff + n * 2048 + k * 1024); } while (0)
; #define PG8_MMA(ai, bj, At, Bt) do { __builtin_amdgcn_s_setprio(1); _Pragma("unroll") for (int m = 0; m < 4; ++m) _Pragma("unroll") for (int n = 0; n < 2; ++n) _Pragma("unroll") for (int k = 0; k < 2; ++k) \
;         acc[ai][bj][m][n] = __builtin_amdgcn_mfma_f32_16x16x32_bf16(Bt[n][k], At[m][k], acc[ai][bj][m][n], 0, 0, 0); __builtin_amdgcn_s_setprio(0); } while (0)
; #define PG8_WAIT_V(n) asm volatile("s_waitcnt vmcnt(" #n ")" ::: "memory")
; #define PG8_WAIT_L(n) asm volatile("s_waitcnt lgkmcnt(" #n ")" ::: "memory")
; #define PG8_BAR __builtin_amdgcn_s_barrier()
; #define PG8_SCHED __builtin_amdgcn_sched_barrier(0)
; template <class Epi>
; __device__ __forceinline__ void gemm_phase(LAS unsigned char* lds, const Gemm g, const int G, const int cidx, const int tid, const Epi& E) {
;     ...
;             const bool last = (t == nt - 2);
;             const char* a1 = cA + (size_t)(t + 1) * kstep;
;             const char* a2 = last ? nA : cA + (size_t)(t + 2) * kstep; const char* b2 = last ? nB : cB + (size_t)(t + 2) * kstep;
;             const char* a3 = a2 + kstep; const char* b3 = b2 + kstep;
;             PG8_LDB(B0, 0, 0); PG8_LDB(B1, 0, 1); PG8_SCHED; PG8_LDA(At, 0, 0); PG8_STAGE(PG8_SA(1, 1), a1 + hstepA, voffA);
;             PG8_WAIT_V(8); PG8_WAIT_L(0); PG8_BAR; PG8_MMA(0, 0, At, B0); PG8_MMA(0, 1, At, B1); PG8_BAR; PG8_SCHED;
;             PG8_LDA(At, 0, 1); PG8_STAGE(PG8_SB(0, 0), b2, voffB); PG8_STAGE(PG8_SB(0, 1), b2 + hstepB, voffB); PG8_STAGE(PG8_SA(0, 0), a2, voffA);
.LBB0_627:
	s_add_u32 s30, s54, 0xfff00080
	s_addc_u32 s35, s55, -1
	s_add_i32 s66, 0, 0x10000
	s_cmp_eq_u32 s15, 4
	s_cselect_b32 s59, s1, s35
	s_cselect_b32 s58, s0, s30
	s_cselect_b32 s57, s19, s13
	s_cselect_b32 s56, s18, s11
	s_add_i32 s30, 0, 0x14000
	v_add_u32_e32 v144, s66, v130
	v_add_u32_e32 v158, s30, v130
	ds_read_b128 v[132:135], v144
	ds_read_b128 v[136:139], v144 offset:1024
	ds_read_b128 v[140:143], v144 offset:2048
	ds_read_b128 v[144:147], v144 offset:3072
	ds_read_b128 v[148:151], v158
	ds_read_b128 v[174:177], v158 offset:1024
	ds_read_b128 v[178:181], v158 offset:2048
	ds_read_b128 v[182:185], v158 offset:3072
	v_lshl_add_u64 v[158:159], s[54:55], 0, v[152:153]
	s_add_i32 m0, s31, 0xc000
	ds_read_b128 v[186:189], v131
	ds_read_b128 v[190:193], v131 offset:1024
	ds_read_b128 v[210:213], v131 offset:2048
	ds_read_b128 v[214:217], v131 offset:3072
	ds_read_b128 v[218:221], v131 offset:4096
	ds_read_b128 v[222:225], v131 offset:5120
	ds_read_b128 v[226:229], v131 offset:6144
	ds_read_b128 v[230:233], v131 offset:7168
	global_load_lds_dwordx4 v[158:159], off
	v_lshl_add_u64 v[158:159], s[54:55], 0, v[128:129]
	s_add_i32 m0, s31, 0xe000
	s_nop 0
	global_load_lds_dwordx4 v[158:159], off
	s_waitcnt vmcnt(8)
	s_waitcnt lgkmcnt(0)
	s_barrier
	s_setprio 1
	s_waitcnt lgkmcnt(0)
	v_mfma_f32_16x16x32_bf16 v[124:127], v[132:135], v[186:189], v[124:127]
	v_mfma_f32_16x16x32_bf16 v[120:123], v[140:143], v[186:189], v[120:123]
	v_mfma_f32_16x16x32_bf16 v[116:119], v[132:135], v[210:213], v[116:119]
	v_mfma_f32_16x16x32_bf16 v[108:111], v[140:143], v[210:213], v[108:111]
	v_mfma_f32_16x16x32_bf16 v[100:103], v[132:135], v[218:221], v[100:103]
	v_mfma_f32_16x16x32_bf16 v[92:95], v[140:143], v[218:221], v[92:95]
	v_mfma_f32_16x16x32_bf16 v[84:87], v[132:135], v[226:229], v[84:87]
	v_mfma_f32_16x16x32_bf16 v[76:79], v[140:143], v[226:229], v[76:79]
	v_mfma_f32_16x16x32_bf16 v[124:127], v[136:139], v[190:193], v[124:127]
	v_mfma_f32_16x16x32_bf16 v[120:123], v[144:147], v[190:193], v[120:123]
	v_mfma_f32_16x16x32_bf16 v[116:119], v[136:139], v[214:217], v[116:119]
	v_mfma_f32_16x16x32_bf16 v[108:111], v[144:147], v[214:217], v[108:111]
	v_mfma_f32_16x16x32_bf16 v[100:103], v[136:139], v[222:225], v[100:103]
	v_mfma_f32_16x16x32_bf16 v[92:95], v[144:147], v[222:225], v[92:95]
	v_mfma_f32_16x16x32_bf16 v[84:87], v[136:139], v[230:233], v[84:87]
	v_mfma_f32_16x16x32_bf16 v[76:79], v[144:147], v[230:233], v[76:79]
	s_setprio 0
	s_setprio 1
	v_mfma_f32_16x16x32_bf16 v[112:115], v[148:151], v[186:189], v[112:115]
	v_mfma_f32_16x16x32_bf16 v[104:107], v[178:181], v[186:189], v[104:107]
	v_mfma_f32_16x16x32_bf16 v[96:99], v[148:151], v[210:213], v[96:99]
	v_mfma_f32_16x16x32_bf16 v[88:91], v[178:181], v[210:213], v[88:91]
	v_mfma_f32_16x16x32_bf16 v[80:83], v[148:151], v[218:221], v[80:83]
	v_mfma_f32_16x16x32_bf16 v[72:75], v[178:181], v[218:221], v[72:75]
	v_mfma_f32_16x16x32_bf16 v[68:71], v[148:151], v[226:229], v[68:71]
	v_mfma_f32_16x16x32_bf16 v[64:67], v[178:181], v[226:229], v[64:67]
	v_mfma_f32_16x16x32_bf16 v[112:115], v[174:177], v[190:193], v[112:115]
	v_mfma_f32_16x16x32_bf16 v[104:107], v[182:185], v[190:193], v[104:107]
	v_mfma_f32_16x16x32_bf16 v[96:99], v[174:177], v[214:217], v[96:99]
	v_mfma_f32_16x16x32_bf16 v[88:91], v[182:185], v[214:217], v[88:91]
	v_mfma_f32_16x16x32_bf16 v[80:83], v[174:177], v[222:225], v[80:83]
	v_mfma_f32_16x16x32_bf16 v[72:75], v[182:185], v[222:225], v[72:75]
	v_mfma_f32_16x16x32_bf16 v[68:71], v[174:177], v[230:233], v[68:71]
	v_mfma_f32_16x16x32_bf16 v[64:67], v[182:185], v[230:233], v[64:67]
	s_setprio 0
	s_barrier
	s_add_i32 s35, s66, s29
	v_lshl_add_u64 v[158:159], s[56:57], 0, v[168:169]
	s_mov_b32 m0, s35
	ds_read_b128 v[186:189], v131 offset:16384
	ds_read_b128 v[190:193], v131 offset:17408
	ds_read_b128 v[210:213], v131 offset:18432
	ds_read_b128 v[214:217], v131 offset:19456
	ds_read_b128 v[218:221], v131 offset:20480
	ds_read_b128 v[222:225], v131 offset:21504
	ds_read_b128 v[226:229], v131 offset:22528
	ds_read_b128 v[230:233], v131 offset:23552
	global_load_lds_dwordx4 v[158:159], off
	s_add_i32 m0, s35, 0x2000
	s_add_u32 s66, s56, 0x100000
	v_lshl_add_u64 v[208:209], s[56:57], 0, v[172:173]
	s_addc_u32 s67, s57, 0
	s_add_i32 s30, s30, s29
	global_load_lds_dwordx4 v[208:209], off
	v_lshl_add_u64 v[234:235], s[66:67], 0, v[168:169]
	s_mov_b32 m0, s30
	v_lshl_add_u64 v[236:237], s[58:59], 0, v[170:171]
	global_load_lds_dwordx4 v[234:235], off
	v_lshl_add_u64 v[234:235], s[66:67], 0, v[172:173]
	s_add_i32 m0, s30, 0x2000
	s_nop 0
	global_load_lds_dwordx4 v[234:235], off
	v_lshl_add_u64 v[234:235], s[58:59], 0, v[166:167]
	s_mov_b32 m0, s31
	s_nop 0
	global_load_lds_dwordx4 v[234:235], off
	s_mov_b32 m0, s53
	s_nop 0
	global_load_lds_dwordx4 v[236:237], off
	s_waitcnt vmcnt(8)
	s_waitcnt lgkmcnt(0)
	s_barrier
; #define PG8_STAGE(bufoff, gbase, voff) do { _Pragma("unroll") for (int _i = 0; _i < 2; ++_i) \
;         __builtin_amdgcn_global_load_lds((const unsigned*)((const char*)(gbase) + (voff)[_i]), (LAS unsigned*)(lds + (bufoff) + ldsw + _i * 8192), 16, 0, 0); } while (0)
; #define PG8_LDA(dst, b, h) do { _Pragma("unroll") for (int m = 0; m < 4; ++m) _Pragma("unroll") for (int k = 0; k < 2; ++k) dst[m][k] = *(const LAS bf16x8*)(lds + PG8_SA(b, h) + aoff + m * 2048 + k * 1024); } while (0)
; #define PG8_LDB(dst, b, h) do { _Pragma("unroll") for (int n = 0; n < 2; ++n) _Pragma("unroll") for (int k = 0; k < 2; ++k) dst[n][k] = *(const LAS bf16x8*)(lds + PG8_SB(b, h) + boff + n * 2048 + k * 1024); } while (0)
; #define PG8_MMA(ai, bj, At, Bt) do { __builtin_amdgcn_s_setprio(1); _Pragma("unroll") for (int m = 0; m < 4; ++m) _Pragma("unroll") for (int n = 0; n < 2; ++n) _Pragma("unroll") for (int k = 0; k < 2; ++k) \
;         acc[ai][bj][m][n] = __builtin_amdgcn_mfma_f32_16x16x32_bf16(Bt[n][k], At[m][k], acc[ai][bj][m][n], 0, 0, 0); __builtin_amdgcn_s_setprio(0); } while (0)
; #define PG8_WAIT_V(n) asm volatile("s_waitcnt vmcnt(" #n ")" ::: "memory")
; #define PG8_WAIT_L(n) asm volatile("s_waitcnt lgkmcnt(" #n ")" ::: "memory")
; #define PG8_BAR __builtin_amdgcn_s_barrier()
; #define PG8_SCHED __builtin_amdgcn_sched_barrier(0)
; template <class Epi>
; __device__ __forceinline__ void gemm_phase(LAS unsigned char* lds, const Gemm g, const int G, const int cidx, const int tid, const Epi& E) {
;     ...
;             PG8_WAIT_V(8); PG8_WAIT_L(0); PG8_BAR; PG8_MMA(1, 0, At, B0); PG8_MMA(1, 1, At, B1); PG8_BAR; PG8_SCHED;
;             PG8_LDB(B0, 1, 0); PG8_LDB(B1, 1, 1); PG8_SCHED; PG8_LDA(At, 1, 0); PG8_STAGE(PG8_SA(0, 1), a2 + hstepA, voffA);
;             PG8_WAIT_V(8); PG8_WAIT_L(0); PG8_BAR; PG8_MMA(0, 0, At, B0); PG8_MMA(0, 1, At, B1); PG8_BAR; PG8_SCHED;
	s_setprio 1
	s_waitcnt lgkmcnt(0)
	v_mfma_f32_16x16x32_bf16 v[60:63], v[132:135], v[186:189], v[60:63]
	v_mfma_f32_16x16x32_bf16 v[56:59], v[140:143], v[186:189], v[56:59]
	v_mfma_f32_16x16x32_bf16 v[52:55], v[132:135], v[210:213], v[52:55]
	v_mfma_f32_16x16x32_bf16 v[44:47], v[140:143], v[210:213], v[44:47]
	v_mfma_f32_16x16x32_bf16 v[36:39], v[132:135], v[218:221], v[36:39]
	v_mfma_f32_16x16x32_bf16 v[28:31], v[140:143], v[218:221], v[28:31]
	v_mfma_f32_16x16x32_bf16 v[20:23], v[132:135], v[226:229], v[20:23]
	v_mfma_f32_16x16x32_bf16 v[12:15], v[140:143], v[226:229], v[12:15]
	v_mfma_f32_16x16x32_bf16 v[60:63], v[136:139], v[190:193], v[60:63]
	v_mfma_f32_16x16x32_bf16 v[56:59], v[144:147], v[190:193], v[56:59]
	v_mfma_f32_16x16x32_bf16 v[52:55], v[136:139], v[214:217], v[52:55]
	v_mfma_f32_16x16x32_bf16 v[44:47], v[144:147], v[214:217], v[44:47]
	v_mfma_f32_16x16x32_bf16 v[36:39], v[136:139], v[222:225], v[36:39]
	v_mfma_f32_16x16x32_bf16 v[28:31], v[144:147], v[222:225], v[28:31]
	v_mfma_f32_16x16x32_bf16 v[20:23], v[136:139], v[230:233], v[20:23]
	v_mfma_f32_16x16x32_bf16 v[12:15], v[144:147], v[230:233], v[12:15]
	s_setprio 0
	s_setprio 1
	v_mfma_f32_16x16x32_bf16 v[48:51], v[148:151], v[186:189], v[48:51]
	v_mfma_f32_16x16x32_bf16 v[40:43], v[178:181], v[186:189], v[40:43]
	v_mfma_f32_16x16x32_bf16 v[32:35], v[148:151], v[210:213], v[32:35]
	v_mfma_f32_16x16x32_bf16 v[24:27], v[178:181], v[210:213], v[24:27]
	v_mfma_f32_16x16x32_bf16 v[16:19], v[148:151], v[218:221], v[16:19]
	v_mfma_f32_16x16x32_bf16 v[8:11], v[178:181], v[218:221], v[8:11]
	v_mfma_f32_16x16x32_bf16 v[4:7], v[148:151], v[226:229], v[4:7]
	v_mfma_f32_16x16x32_bf16 v[0:3], v[178:181], v[226:229], v[0:3]
	v_mfma_f32_16x16x32_bf16 v[48:51], v[174:177], v[190:193], v[48:51]
	v_mfma_f32_16x16x32_bf16 v[40:43], v[182:185], v[190:193], v[40:43]
	v_mfma_f32_16x16x32_bf16 v[32:35], v[174:177], v[214:217], v[32:35]
	v_mfma_f32_16x16x32_bf16 v[24:27], v[182:185], v[214:217], v[24:27]
	v_mfma_f32_16x16x32_bf16 v[16:19], v[174:177], v[222:225], v[16:19]
	v_mfma_f32_16x16x32_bf16 v[8:11], v[182:185], v[222:225], v[8:11]
	v_mfma_f32_16x16x32_bf16 v[4:7], v[174:177], v[230:233], v[4:7]
	v_mfma_f32_16x16x32_bf16 v[0:3], v[182:185], v[230:233], v[0:3]
	s_setprio 0
	s_barrier
	s_add_i32 s30, 0, 0x18000
	s_add_i32 s35, 0, 0x1c000
	v_add_u32_e32 v144, s30, v130
	v_add_u32_e32 v182, s35, v130
	ds_read_b128 v[132:135], v144
	ds_read_b128 v[136:139], v144 offset:1024
	ds_read_b128 v[140:143], v144 offset:2048
	ds_read_b128 v[144:147], v144 offset:3072
	ds_read_b128 v[148:151], v182
	ds_read_b128 v[174:177], v182 offset:1024
	ds_read_b128 v[178:181], v182 offset:2048
	ds_read_b128 v[182:185], v182 offset:3072
	s_add_u32 s58, s58, 0x100000
	s_addc_u32 s59, s59, 0
	s_mov_b32 m0, s61
	v_lshl_add_u64 v[238:239], s[58:59], 0, v[166:167]
	ds_read_b128 v[186:189], v131 offset:32768
	ds_read_b128 v[190:193], v131 offset:33792
	ds_read_b128 v[210:213], v131 offset:34816
	ds_read_b128 v[214:217], v131 offset:35840
	ds_read_b128 v[218:221], v131 offset:36864
	ds_read_b128 v[222:225], v131 offset:37888
	ds_read_b128 v[226:229], v131 offset:38912
	ds_read_b128 v[230:233], v131 offset:39936
	global_load_lds_dwordx4 v[238:239], off
	v_lshl_add_u64 v[238:239], s[58:59], 0, v[170:171]
	s_mov_b32 m0, s62
	s_nop 0
	global_load_lds_dwordx4 v[238:239], off
	s_waitcnt vmcnt(8)
	s_waitcnt lgkmcnt(0)
	s_barrier
	s_setprio 1
	s_waitcnt lgkmcnt(0)
	v_mfma_f32_16x16x32_bf16 v[124:127], v[132:135], v[186:189], v[124:127]
	v_mfma_f32_16x16x32_bf16 v[120:123], v[140:143], v[186:189], v[120:123]
	v_mfma_f32_16x16x32_bf16 v[116:119], v[132:135], v[210:213], v[116:119]
	v_mfma_f32_16x16x32_bf16 v[108:111], v[140:143], v[210:213], v[108:111]
	v_mfma_f32_16x16x32_bf16 v[100:103], v[132:135], v[218:221], v[100:103]
	v_mfma_f32_16x16x32_bf16 v[92:95], v[140:143], v[218:221], v[92:95]
	v_mfma_f32_16x16x32_bf16 v[84:87], v[132:135], v[226:229], v[84:87]
	v_mfma_f32_16x16x32_bf16 v[76:79], v[140:143], v[226:229], v[76:79]
	v_mfma_f32_16x16x32_bf16 v[124:127], v[136:139], v[190:193], v[124:127]
	v_mfma_f32_16x16x32_bf16 v[120:123], v[144:147], v[190:193], v[120:123]
	v_mfma_f32_16x16x32_bf16 v[116:119], v[136:139], v[214:217], v[116:119]
	v_mfma_f32_16x16x32_bf16 v[108:111], v[144:147], v[214:217], v[108:111]
	v_mfma_f32_16x16x32_bf16 v[100:103], v[136:139], v[222:225], v[100:103]
	v_mfma_f32_16x16x32_bf16 v[92:95], v[144:147], v[222:225], v[92:95]
	v_mfma_f32_16x16x32_bf16 v[84:87], v[136:139], v[230:233], v[84:87]
	v_mfma_f32_16x16x32_bf16 v[76:79], v[144:147], v[230:233], v[76:79]
	s_setprio 0
	s_setprio 1
	v_mfma_f32_16x16x32_bf16 v[112:115], v[148:151], v[186:189], v[112:115]
	v_mfma_f32_16x16x32_bf16 v[104:107], v[178:181], v[186:189], v[104:107]
	v_mfma_f32_16x16x32_bf16 v[96:99], v[148:151], v[210:213], v[96:99]
	v_mfma_f32_16x16x32_bf16 v[88:91], v[178:181], v[210:213], v[88:91]
	v_mfma_f32_16x16x32_bf16 v[80:83], v[148:151], v[218:221], v[80:83]
	v_mfma_f32_16x16x32_bf16 v[72:75], v[178:181], v[218:221], v[72:75]
	v_mfma_f32_16x16x32_bf16 v[68:71], v[148:151], v[226:229], v[68:71]
	v_mfma_f32_16x16x32_bf16 v[64:67], v[178:181], v[226:229], v[64:67]
	v_mfma_f32_16x16x32_bf16 v[112:115], v[174:177], v[190:193], v[112:115]
	v_mfma_f32_16x16x32_bf16 v[104:107], v[182:185], v[190:193], v[104:107]
	v_mfma_f32_16x16x32_bf16 v[96:99], v[174:177], v[214:217], v[96:99]
	v_mfma_f32_16x16x32_bf16 v[88:91], v[182:185], v[214:217], v[88:91]
	v_mfma_f32_16x16x32_bf16 v[80:83], v[174:177], v[222:225], v[80:83]
	v_mfma_f32_16x16x32_bf16 v[72:75], v[182:185], v[222:225], v[72:75]
	v_mfma_f32_16x16x32_bf16 v[68:71], v[174:177], v[230:233], v[68:71]
	v_mfma_f32_16x16x32_bf16 v[64:67], v[182:185], v[230:233], v[64:67]
	s_setprio 0
	s_barrier
; #define PG8_STAGE(bufoff, gbase, voff) do { _Pragma("unroll") for (int _i = 0; _i < 2; ++_i) \
;         __builtin_amdgcn_global_load_lds((const unsigned*)((const char*)(gbase) + (voff)[_i]), (LAS unsigned*)(lds + (bufoff) + ldsw + _i * 8192), 16, 0, 0); } while (0)
; #define PG8_LDA(dst, b, h) do { _Pragma("unroll") for (int m = 0; m < 4; ++m) _Pragma("unroll") for (int k = 0; k < 2; ++k) dst[m][k] = *(const LAS bf16x8*)(lds + PG8_SA(b, h) + aoff + m * 2048 + k * 1024); } while (0)
; #define PG8_MMA(ai, bj, At, Bt) do { __builtin_amdgcn_s_setprio(1); _Pragma("unroll") for (int m = 0; m < 4; ++m) _Pragma("unroll") for (int n = 0; n < 2; ++n) _Pragma("unroll") for (int k = 0; k < 2; ++k) \
;         acc[ai][bj][m][n] = __builtin_amdgcn_mfma_f32_16x16x32_bf16(Bt[n][k], At[m][k], acc[ai][bj][m][n], 0, 0, 0); __builtin_amdgcn_s_setprio(0); } while (0)
; #define PG8_WAIT_V(n) asm volatile("s_waitcnt vmcnt(" #n ")" ::: "memory")
; #define PG8_WAIT_L(n) asm volatile("s_waitcnt lgkmcnt(" #n ")" ::: "memory")
; #define PG8_BAR __builtin_amdgcn_s_barrier()
; #define PG8_SCHED __builtin_amdgcn_sched_barrier(0)
; template <class Epi>
; __device__ __forceinline__ void gemm_phase(LAS unsigned char* lds, const Gemm g, const int G, const int cidx, const int tid, const Epi& E) {
;     ...
;         for (int t = 0; t < nt; t += 2) {
;     ...
;             PG8_LDA(At, 1, 1); PG8_STAGE(PG8_SB(1, 0), b3, voffB); PG8_STAGE(PG8_SB(1, 1), b3 + hstepB, voffB); PG8_STAGE(PG8_SA(1, 0), a3, voffA);
;             PG8_WAIT_V(8); PG8_WAIT_L(0); PG8_BAR; PG8_MMA(1, 0, At, B0); PG8_MMA(1, 1, At, B1); PG8_BAR; PG8_SCHED;
	s_add_i32 s30, s30, s29
	v_lshl_add_u64 v[158:159], v[158:159], 0, s[96:97]
	s_mov_b32 m0, s30
	ds_read_b128 v[186:189], v131 offset:49152
	ds_read_b128 v[190:193], v131 offset:50176
	ds_read_b128 v[210:213], v131 offset:51200
	ds_read_b128 v[214:217], v131 offset:52224
	ds_read_b128 v[218:221], v131 offset:53248
	ds_read_b128 v[222:225], v131 offset:54272
	ds_read_b128 v[226:229], v131 offset:55296
	ds_read_b128 v[230:233], v131 offset:56320
	global_load_lds_dwordx4 v[158:159], off
	s_add_i32 m0, s30, 0x2000
	s_add_u32 s56, s56, 0x100080
	v_lshl_add_u64 v[158:159], v[208:209], 0, s[96:97]
	s_addc_u32 s57, s57, 0
	s_add_i32 s30, s35, s29
	global_load_lds_dwordx4 v[158:159], off
	v_lshl_add_u64 v[158:159], s[56:57], 0, v[168:169]
	s_mov_b32 m0, s30
	s_nop 0
	global_load_lds_dwordx4 v[158:159], off
	v_lshl_add_u64 v[158:159], s[56:57], 0, v[172:173]
	s_add_i32 m0, s30, 0x2000
	s_nop 0
	global_load_lds_dwordx4 v[158:159], off
	v_lshl_add_u64 v[158:159], v[234:235], 0, s[96:97]
	s_mov_b32 m0, s94
	s_nop 0
	global_load_lds_dwordx4 v[158:159], off
	v_lshl_add_u64 v[158:159], v[236:237], 0, s[96:97]
	s_mov_b32 m0, s95
	s_nop 0
	global_load_lds_dwordx4 v[158:159], off
	s_waitcnt vmcnt(8)
	s_waitcnt lgkmcnt(0)
	s_barrier
	s_setprio 1
	s_waitcnt lgkmcnt(0)
	v_mfma_f32_16x16x32_bf16 v[60:63], v[132:135], v[186:189], v[60:63]
	v_mfma_f32_16x16x32_bf16 v[56:59], v[140:143], v[186:189], v[56:59]
	v_mfma_f32_16x16x32_bf16 v[52:55], v[132:135], v[210:213], v[52:55]
	v_mfma_f32_16x16x32_bf16 v[44:47], v[140:143], v[210:213], v[44:47]
	v_mfma_f32_16x16x32_bf16 v[36:39], v[132:135], v[218:221], v[36:39]
	v_mfma_f32_16x16x32_bf16 v[28:31], v[140:143], v[218:221], v[28:31]
	v_mfma_f32_16x16x32_bf16 v[20:23], v[132:135], v[226:229], v[20:23]
	v_mfma_f32_16x16x32_bf16 v[12:15], v[140:143], v[226:229], v[12:15]
	v_mfma_f32_16x16x32_bf16 v[60:63], v[136:139], v[190:193], v[60:63]
	v_mfma_f32_16x16x32_bf16 v[56:59], v[144:147], v[190:193], v[56:59]
	v_mfma_f32_16x16x32_bf16 v[52:55], v[136:139], v[214:217], v[52:55]
	v_mfma_f32_16x16x32_bf16 v[44:47], v[144:147], v[214:217], v[44:47]
	v_mfma_f32_16x16x32_bf16 v[36:39], v[136:139], v[222:225], v[36:39]
	v_mfma_f32_16x16x32_bf16 v[28:31], v[144:147], v[222:225], v[28:31]
	v_mfma_f32_16x16x32_bf16 v[20:23], v[136:139], v[230:233], v[20:23]
	v_mfma_f32_16x16x32_bf16 v[12:15], v[144:147], v[230:233], v[12:15]
	s_setprio 0
	s_setprio 1
	v_mfma_f32_16x16x32_bf16 v[48:51], v[148:151], v[186:189], v[48:51]
	v_mfma_f32_16x16x32_bf16 v[40:43], v[178:181], v[186:189], v[40:43]
	v_mfma_f32_16x16x32_bf16 v[32:35], v[148:151], v[210:213], v[32:35]
	v_mfma_f32_16x16x32_bf16 v[24:27], v[178:181], v[210:213], v[24:27]
	v_mfma_f32_16x16x32_bf16 v[16:19], v[148:151], v[218:221], v[16:19]
	v_mfma_f32_16x16x32_bf16 v[8:11], v[178:181], v[218:221], v[8:11]
	v_mfma_f32_16x16x32_bf16 v[4:7], v[148:151], v[226:229], v[4:7]
	v_mfma_f32_16x16x32_bf16 v[0:3], v[178:181], v[226:229], v[0:3]
	v_mfma_f32_16x16x32_bf16 v[48:51], v[174:177], v[190:193], v[48:51]
	v_mfma_f32_16x16x32_bf16 v[40:43], v[182:185], v[190:193], v[40:43]
	v_mfma_f32_16x16x32_bf16 v[32:35], v[174:177], v[214:217], v[32:35]
	v_mfma_f32_16x16x32_bf16 v[24:27], v[182:185], v[214:217], v[24:27]
	v_mfma_f32_16x16x32_bf16 v[16:19], v[174:177], v[222:225], v[16:19]
	v_mfma_f32_16x16x32_bf16 v[8:11], v[182:185], v[222:225], v[8:11]
	v_mfma_f32_16x16x32_bf16 v[4:7], v[174:177], v[230:233], v[4:7]
	v_mfma_f32_16x16x32_bf16 v[0:3], v[182:185], v[230:233], v[0:3]
	s_setprio 0
	s_add_i32 s15, s15, 2
	s_add_u32 s54, s54, 0x100
	s_addc_u32 s55, s55, 0
	s_add_u32 s11, s11, 0x100
	s_addc_u32 s13, s13, 0
	s_barrier
	s_cmp_gt_u32 s15, 5
	s_cbranch_scc0 .LBB0_627
	s_and_b64 vcc, exec, s[8:9]
	s_cbranch_vccz .LBB0_630
	s_barrier

; #define PG8_STAGE(bufoff, gbase, voff) do { _Pragma("unroll") for (int _i = 0; _i < 2; ++_i) \
;         __builtin_amdgcn_global_load_lds((const unsigned*)((const char*)(gbase) + (voff)[_i]), (LAS unsigned*)(lds + (bufoff) + ldsw + _i * 8192), 16, 0, 0); } while (0)
; #define PG8_LDA(dst, b, h) do { _Pragma("unroll") for (int m = 0; m < 4; ++m) _Pragma("unroll") for (int k = 0; k < 2; ++k) dst[m][k] = *(const LAS bf16x8*)(lds + PG8_SA(b, h) + aoff + m * 2048 + k * 1024); } while (0)
; #define PG8_LDB(dst, b, h) do { _Pragma("unroll") for (int n = 0; n < 2; ++n) _Pragma("unroll") for (int k = 0; k < 2; ++k) dst[n][k] = *(const LAS bf16x8*)(lds + PG8_SB(b, h) + boff + n * 2048 + k * 1024); } while (0)
; #define PG8_MMA(ai, bj, At, Bt) do { __builtin_amdgcn_s_setprio(1); _Pragma("unroll") for (int m = 0; m < 4; ++m) _Pragma("unroll") for (int n = 0; n < 2; ++n) _Pragma("unroll") for (int k = 0; k < 2; ++k) \
;         acc[ai][bj][m][n] = __builtin_amdgcn_mfma_f32_16x16x32_bf16(Bt[n][k], At[m][k], acc[ai][bj][m][n], 0, 0, 0); __builtin_amdgcn_s_setprio(0); } while (0)
; #define PG8_WAIT_V(n) asm volatile("s_waitcnt vmcnt(" #n ")" ::: "memory")
; #define PG8_WAIT_L(n) asm volatile("s_waitcnt lgkmcnt(" #n ")" ::: "memory")
; #define PG8_BAR __builtin_amdgcn_s_barrier()
; #define PG8_SCHED __builtin_amdgcn_sched_barrier(0)
; template <class Epi>
; __device__ __forceinline__ void gemm_phase(LAS unsigned char* lds, const Gemm g, const int G, const int cidx, const int tid, const Epi& E) {
;     ...
;             const bool last = (t == nt - 2);
;             const char* a1 = cA + (size_t)(t + 1) * kstep;
;             const char* a2 = last ? nA : cA + (size_t)(t + 2) * kstep; const char* b2 = last ? nB : cB + (size_t)(t + 2) * kstep;
;             const char* a3 = a2 + kstep; const char* b3 = b2 + kstep;
;             PG8_LDB(B0, 0, 0); PG8_LDB(B1, 0, 1); PG8_SCHED; PG8_LDA(At, 0, 0); PG8_STAGE(PG8_SA(1, 1), a1 + hstepA, voffA);
;             PG8_WAIT_V(8); PG8_WAIT_L(0); PG8_BAR; PG8_MMA(0, 0, At, B0); PG8_MMA(0, 1, At, B1); PG8_BAR; PG8_SCHED;
;             PG8_LDA(At, 0, 1); PG8_STAGE(PG8_SB(0, 0), b2, voffB); PG8_STAGE(PG8_SB(0, 1), b2 + hstepB, voffB); PG8_STAGE(PG8_SA(0, 0), a2, voffA);
.LBB0_647:
	s_add_u32 s56, s54, 0xfffc0080
	s_addc_u32 s57, s55, -1
	s_add_i32 s66, 0, 0x10000
	s_cmp_eq_u32 s65, 12
	s_cselect_b32 s59, s7, s57
	s_cselect_b32 s58, s15, s56
	v_add_u32_e32 v148, s66, v150
	s_cselect_b32 s57, s13, s53
	s_cselect_b32 s56, s34, s35
	s_add_i32 s67, 0, 0x14000
	ds_read_b128 v[140:143], v148
	ds_read_b128 v[144:147], v148 offset:1024
	ds_read_b128 v[166:169], v148 offset:2048
	ds_read_b128 v[170:173], v148 offset:3072
	v_add_u32_e32 v148, s67, v150
	ds_read_b128 v[174:177], v148
	ds_read_b128 v[178:181], v148 offset:1024
	ds_read_b128 v[182:185], v148 offset:2048
	ds_read_b128 v[186:189], v148 offset:3072
	v_lshl_add_u64 v[238:239], s[54:55], 0, v[136:137]
	s_add_i32 m0, s21, 0xc000
	ds_read_b128 v[190:193], v151
	ds_read_b128 v[210:213], v151 offset:1024
	ds_read_b128 v[214:217], v151 offset:2048
	ds_read_b128 v[218:221], v151 offset:3072
	ds_read_b128 v[222:225], v151 offset:4096
	ds_read_b128 v[226:229], v151 offset:5120
	ds_read_b128 v[230:233], v151 offset:6144
	ds_read_b128 v[234:237], v151 offset:7168
	global_load_lds_dwordx4 v[238:239], off
	v_lshl_add_u64 v[238:239], s[54:55], 0, v[138:139]
	s_add_i32 m0, s21, 0xe000
	s_nop 0
	global_load_lds_dwordx4 v[238:239], off
	s_waitcnt vmcnt(8)
	s_waitcnt lgkmcnt(0)
	s_barrier
	s_setprio 1
	s_waitcnt lgkmcnt(0)
	v_mfma_f32_16x16x32_bf16 v[124:127], v[140:143], v[190:193], v[124:127]
	v_mfma_f32_16x16x32_bf16 v[120:123], v[166:169], v[190:193], v[120:123]
	v_mfma_f32_16x16x32_bf16 v[108:111], v[140:143], v[214:217], v[108:111]
	v_mfma_f32_16x16x32_bf16 v[104:107], v[166:169], v[214:217], v[104:107]
	v_mfma_f32_16x16x32_bf16 v[92:95], v[140:143], v[222:225], v[92:95]
	v_mfma_f32_16x16x32_bf16 v[88:91], v[166:169], v[222:225], v[88:91]
	v_mfma_f32_16x16x32_bf16 v[76:79], v[140:143], v[230:233], v[76:79]
	v_mfma_f32_16x16x32_bf16 v[72:75], v[166:169], v[230:233], v[72:75]
	v_mfma_f32_16x16x32_bf16 v[124:127], v[144:147], v[210:213], v[124:127]
	v_mfma_f32_16x16x32_bf16 v[120:123], v[170:173], v[210:213], v[120:123]
	v_mfma_f32_16x16x32_bf16 v[108:111], v[144:147], v[218:221], v[108:111]
	v_mfma_f32_16x16x32_bf16 v[104:107], v[170:173], v[218:221], v[104:107]
	v_mfma_f32_16x16x32_bf16 v[92:95], v[144:147], v[226:229], v[92:95]
	v_mfma_f32_16x16x32_bf16 v[88:91], v[170:173], v[226:229], v[88:91]
	v_mfma_f32_16x16x32_bf16 v[76:79], v[144:147], v[234:237], v[76:79]
	v_mfma_f32_16x16x32_bf16 v[72:75], v[170:173], v[234:237], v[72:75]
	s_setprio 0
	s_setprio 1
	v_mfma_f32_16x16x32_bf16 v[116:119], v[174:177], v[190:193], v[116:119]
	v_mfma_f32_16x16x32_bf16 v[112:115], v[182:185], v[190:193], v[112:115]
	v_mfma_f32_16x16x32_bf16 v[100:103], v[174:177], v[214:217], v[100:103]
	v_mfma_f32_16x16x32_bf16 v[96:99], v[182:185], v[214:217], v[96:99]
	v_mfma_f32_16x16x32_bf16 v[84:87], v[174:177], v[222:225], v[84:87]
	v_mfma_f32_16x16x32_bf16 v[80:83], v[182:185], v[222:225], v[80:83]
	v_mfma_f32_16x16x32_bf16 v[68:71], v[174:177], v[230:233], v[68:71]
	v_mfma_f32_16x16x32_bf16 v[64:67], v[182:185], v[230:233], v[64:67]
	v_mfma_f32_16x16x32_bf16 v[116:119], v[178:181], v[210:213], v[116:119]
	v_mfma_f32_16x16x32_bf16 v[112:115], v[186:189], v[210:213], v[112:115]
	v_mfma_f32_16x16x32_bf16 v[100:103], v[178:181], v[218:221], v[100:103]
	v_mfma_f32_16x16x32_bf16 v[96:99], v[186:189], v[218:221], v[96:99]
	v_mfma_f32_16x16x32_bf16 v[84:87], v[178:181], v[226:229], v[84:87]
	v_mfma_f32_16x16x32_bf16 v[80:83], v[186:189], v[226:229], v[80:83]
	v_mfma_f32_16x16x32_bf16 v[68:71], v[178:181], v[234:237], v[68:71]
	v_mfma_f32_16x16x32_bf16 v[64:67], v[186:189], v[234:237], v[64:67]
	s_setprio 0
	s_barrier
	s_add_i32 s66, s66, s20
	v_lshl_add_u64 v[238:239], s[56:57], 0, v[130:131]
	s_mov_b32 m0, s66
	ds_read_b128 v[190:193], v151 offset:16384
	ds_read_b128 v[210:213], v151 offset:17408
	ds_read_b128 v[214:217], v151 offset:18432
	ds_read_b128 v[218:221], v151 offset:19456
	ds_read_b128 v[222:225], v151 offset:20480
	ds_read_b128 v[226:229], v151 offset:21504
	ds_read_b128 v[230:233], v151 offset:22528
	ds_read_b128 v[234:237], v151 offset:23552
	global_load_lds_dwordx4 v[238:239], off
	s_add_i32 m0, s66, 0x2000
	s_add_u32 s94, s56, 0x40000
	v_lshl_add_u64 v[240:241], s[56:57], 0, v[134:135]
	s_addc_u32 s95, s57, 0
	s_add_i32 s66, s67, s20
	global_load_lds_dwordx4 v[240:241], off
	v_lshl_add_u64 v[242:243], s[94:95], 0, v[130:131]
	s_mov_b32 m0, s66
	v_lshl_add_u64 v[244:245], s[58:59], 0, v[132:133]
	global_load_lds_dwordx4 v[242:243], off
	v_lshl_add_u64 v[242:243], s[94:95], 0, v[134:135]
	s_add_i32 m0, s66, 0x2000
	s_nop 0
	global_load_lds_dwordx4 v[242:243], off
	v_lshl_add_u64 v[242:243], s[58:59], 0, v[128:129]
	s_mov_b32 m0, s21
	s_nop 0
	global_load_lds_dwordx4 v[242:243], off
	s_mov_b32 m0, s24
	s_nop 0
	global_load_lds_dwordx4 v[244:245], off
	s_waitcnt vmcnt(8)
	s_waitcnt lgkmcnt(0)
	s_barrier
; #define PG8_STAGE(bufoff, gbase, voff) do { _Pragma("unroll") for (int _i = 0; _i < 2; ++_i) \
;         __builtin_amdgcn_global_load_lds((const unsigned*)((const char*)(gbase) + (voff)[_i]), (LAS unsigned*)(lds + (bufoff) + ldsw + _i * 8192), 16, 0, 0); } while (0)
; #define PG8_LDA(dst, b, h) do { _Pragma("unroll") for (int m = 0; m < 4; ++m) _Pragma("unroll") for (int k = 0; k < 2; ++k) dst[m][k] = *(const LAS bf16x8*)(lds + PG8_SA(b, h) + aoff + m * 2048 + k * 1024); } while (0)
; #define PG8_LDB(dst, b, h) do { _Pragma("unroll") for (int n = 0; n < 2; ++n) _Pragma("unroll") for (int k = 0; k < 2; ++k) dst[n][k] = *(const LAS bf16x8*)(lds + PG8_SB(b, h) + boff + n * 2048 + k * 1024); } while (0)
; #define PG8_MMA(ai, bj, At, Bt) do { __builtin_amdgcn_s_setprio(1); _Pragma("unroll") for (int m = 0; m < 4; ++m) _Pragma("unroll") for (int n = 0; n < 2; ++n) _Pragma("unroll") for (int k = 0; k < 2; ++k) \
;         acc[ai][bj][m][n] = __builtin_amdgcn_mfma_f32_16x16x32_bf16(Bt[n][k], At[m][k], acc[ai][bj][m][n], 0, 0, 0); __builtin_amdgcn_s_setprio(0); } while (0)
; #define PG8_WAIT_V(n) asm volatile("s_waitcnt vmcnt(" #n ")" ::: "memory")
; #define PG8_WAIT_L(n) asm volatile("s_waitcnt lgkmcnt(" #n ")" ::: "memory")
; #define PG8_BAR __builtin_amdgcn_s_barrier()
; #define PG8_SCHED __builtin_amdgcn_sched_barrier(0)
; template <class Epi>
; __device__ __forceinline__ void gemm_phase(LAS unsigned char* lds, const Gemm g, const int G, const int cidx, const int tid, const Epi& E) {
;     ...
;             PG8_WAIT_V(8); PG8_WAIT_L(0); PG8_BAR; PG8_MMA(1, 0, At, B0); PG8_MMA(1, 1, At, B1); PG8_BAR; PG8_SCHED;
;             PG8_LDB(B0, 1, 0); PG8_LDB(B1, 1, 1); PG8_SCHED; PG8_LDA(At, 1, 0); PG8_STAGE(PG8_SA(0, 1), a2 + hstepA, voffA);
;             PG8_WAIT_V(8); PG8_WAIT_L(0); PG8_BAR; PG8_MMA(0, 0, At, B0); PG8_MMA(0, 1, At, B1); PG8_BAR; PG8_SCHED;
	s_setprio 1
	s_waitcnt lgkmcnt(0)
	v_mfma_f32_16x16x32_bf16 v[60:63], v[140:143], v[190:193], v[60:63]
	v_mfma_f32_16x16x32_bf16 v[56:59], v[166:169], v[190:193], v[56:59]
	v_mfma_f32_16x16x32_bf16 v[44:47], v[140:143], v[214:217], v[44:47]
	v_mfma_f32_16x16x32_bf16 v[40:43], v[166:169], v[214:217], v[40:43]
	v_mfma_f32_16x16x32_bf16 v[28:31], v[140:143], v[222:225], v[28:31]
	v_mfma_f32_16x16x32_bf16 v[24:27], v[166:169], v[222:225], v[24:27]
	v_mfma_f32_16x16x32_bf16 v[12:15], v[140:143], v[230:233], v[12:15]
	v_mfma_f32_16x16x32_bf16 v[8:11], v[166:169], v[230:233], v[8:11]
	v_mfma_f32_16x16x32_bf16 v[60:63], v[144:147], v[210:213], v[60:63]
	v_mfma_f32_16x16x32_bf16 v[56:59], v[170:173], v[210:213], v[56:59]
	v_mfma_f32_16x16x32_bf16 v[44:47], v[144:147], v[218:221], v[44:47]
	v_mfma_f32_16x16x32_bf16 v[40:43], v[170:173], v[218:221], v[40:43]
	v_mfma_f32_16x16x32_bf16 v[28:31], v[144:147], v[226:229], v[28:31]
	v_mfma_f32_16x16x32_bf16 v[24:27], v[170:173], v[226:229], v[24:27]
	v_mfma_f32_16x16x32_bf16 v[12:15], v[144:147], v[234:237], v[12:15]
	v_mfma_f32_16x16x32_bf16 v[8:11], v[170:173], v[234:237], v[8:11]
	s_setprio 0
	s_setprio 1
	v_mfma_f32_16x16x32_bf16 v[52:55], v[174:177], v[190:193], v[52:55]
	v_mfma_f32_16x16x32_bf16 v[48:51], v[182:185], v[190:193], v[48:51]
	v_mfma_f32_16x16x32_bf16 v[36:39], v[174:177], v[214:217], v[36:39]
	v_mfma_f32_16x16x32_bf16 v[32:35], v[182:185], v[214:217], v[32:35]
	v_mfma_f32_16x16x32_bf16 v[20:23], v[174:177], v[222:225], v[20:23]
	v_mfma_f32_16x16x32_bf16 v[16:19], v[182:185], v[222:225], v[16:19]
	v_mfma_f32_16x16x32_bf16 v[4:7], v[174:177], v[230:233], v[4:7]
	v_mfma_f32_16x16x32_bf16 v[0:3], v[182:185], v[230:233], v[0:3]
	v_mfma_f32_16x16x32_bf16 v[52:55], v[178:181], v[210:213], v[52:55]
	v_mfma_f32_16x16x32_bf16 v[48:51], v[186:189], v[210:213], v[48:51]
	v_mfma_f32_16x16x32_bf16 v[36:39], v[178:181], v[218:221], v[36:39]
	v_mfma_f32_16x16x32_bf16 v[32:35], v[186:189], v[218:221], v[32:35]
	v_mfma_f32_16x16x32_bf16 v[20:23], v[178:181], v[226:229], v[20:23]
	v_mfma_f32_16x16x32_bf16 v[16:19], v[186:189], v[226:229], v[16:19]
	v_mfma_f32_16x16x32_bf16 v[4:7], v[178:181], v[234:237], v[4:7]
	v_mfma_f32_16x16x32_bf16 v[0:3], v[186:189], v[234:237], v[0:3]
	s_setprio 0
	s_barrier
	s_add_i32 s66, 0, 0x18000
	v_add_u32_e32 v148, s66, v150
	s_add_i32 s67, 0, 0x1c000
	ds_read_b128 v[140:143], v148
	ds_read_b128 v[144:147], v148 offset:1024
	ds_read_b128 v[166:169], v148 offset:2048
	ds_read_b128 v[170:173], v148 offset:3072
	v_add_u32_e32 v148, s67, v150
	ds_read_b128 v[174:177], v148
	ds_read_b128 v[178:181], v148 offset:1024
	ds_read_b128 v[182:185], v148 offset:2048
	ds_read_b128 v[186:189], v148 offset:3072
	s_add_u32 s58, s58, 0x40000
	s_addc_u32 s59, s59, 0
	s_mov_b32 m0, s25
	v_lshl_add_u64 v[246:247], s[58:59], 0, v[128:129]
	ds_read_b128 v[190:193], v151 offset:32768
	ds_read_b128 v[210:213], v151 offset:33792
	ds_read_b128 v[214:217], v151 offset:34816
	ds_read_b128 v[218:221], v151 offset:35840
	ds_read_b128 v[222:225], v151 offset:36864
	ds_read_b128 v[226:229], v151 offset:37888
	ds_read_b128 v[230:233], v151 offset:38912
	ds_read_b128 v[234:237], v151 offset:39936
	global_load_lds_dwordx4 v[246:247], off
	v_lshl_add_u64 v[246:247], s[58:59], 0, v[132:133]
	s_mov_b32 m0, s29
	s_nop 0
	global_load_lds_dwordx4 v[246:247], off
	s_waitcnt vmcnt(8)
	s_waitcnt lgkmcnt(0)
	s_barrier
	s_setprio 1
	s_waitcnt lgkmcnt(0)
	v_mfma_f32_16x16x32_bf16 v[124:127], v[140:143], v[190:193], v[124:127]
	v_mfma_f32_16x16x32_bf16 v[120:123], v[166:169], v[190:193], v[120:123]
	v_mfma_f32_16x16x32_bf16 v[108:111], v[140:143], v[214:217], v[108:111]
	v_mfma_f32_16x16x32_bf16 v[104:107], v[166:169], v[214:217], v[104:107]
	v_mfma_f32_16x16x32_bf16 v[92:95], v[140:143], v[222:225], v[92:95]
	v_mfma_f32_16x16x32_bf16 v[88:91], v[166:169], v[222:225], v[88:91]
	v_mfma_f32_16x16x32_bf16 v[76:79], v[140:143], v[230:233], v[76:79]
	v_mfma_f32_16x16x32_bf16 v[72:75], v[166:169], v[230:233], v[72:75]
	v_mfma_f32_16x16x32_bf16 v[124:127], v[144:147], v[210:213], v[124:127]
	v_mfma_f32_16x16x32_bf16 v[120:123], v[170:173], v[210:213], v[120:123]
	v_mfma_f32_16x16x32_bf16 v[108:111], v[144:147], v[218:221], v[108:111]
	v_mfma_f32_16x16x32_bf16 v[104:107], v[170:173], v[218:221], v[104:107]
	v_mfma_f32_16x16x32_bf16 v[92:95], v[144:147], v[226:229], v[92:95]
	v_mfma_f32_16x16x32_bf16 v[88:91], v[170:173], v[226:229], v[88:91]
	v_mfma_f32_16x16x32_bf16 v[76:79], v[144:147], v[234:237], v[76:79]
	v_mfma_f32_16x16x32_bf16 v[72:75], v[170:173], v[234:237], v[72:75]
	s_setprio 0
	s_setprio 1
	v_mfma_f32_16x16x32_bf16 v[116:119], v[174:177], v[190:193], v[116:119]
	v_mfma_f32_16x16x32_bf16 v[112:115], v[182:185], v[190:193], v[112:115]
	v_mfma_f32_16x16x32_bf16 v[100:103], v[174:177], v[214:217], v[100:103]
	v_mfma_f32_16x16x32_bf16 v[96:99], v[182:185], v[214:217], v[96:99]
	v_mfma_f32_16x16x32_bf16 v[84:87], v[174:177], v[222:225], v[84:87]
	v_mfma_f32_16x16x32_bf16 v[80:83], v[182:185], v[222:225], v[80:83]
	v_mfma_f32_16x16x32_bf16 v[68:71], v[174:177], v[230:233], v[68:71]
	v_mfma_f32_16x16x32_bf16 v[64:67], v[182:185], v[230:233], v[64:67]
	v_mfma_f32_16x16x32_bf16 v[116:119], v[178:181], v[210:213], v[116:119]
	v_mfma_f32_16x16x32_bf16 v[112:115], v[186:189], v[210:213], v[112:115]
	v_mfma_f32_16x16x32_bf16 v[100:103], v[178:181], v[218:221], v[100:103]
	v_mfma_f32_16x16x32_bf16 v[96:99], v[186:189], v[218:221], v[96:99]
	v_mfma_f32_16x16x32_bf16 v[84:87], v[178:181], v[226:229], v[84:87]
	v_mfma_f32_16x16x32_bf16 v[80:83], v[186:189], v[226:229], v[80:83]
	v_mfma_f32_16x16x32_bf16 v[68:71], v[178:181], v[234:237], v[68:71]
	v_mfma_f32_16x16x32_bf16 v[64:67], v[186:189], v[234:237], v[64:67]
	s_setprio 0
	s_barrier
; #define PG8_STAGE(bufoff, gbase, voff) do { _Pragma("unroll") for (int _i = 0; _i < 2; ++_i) \
;         __builtin_amdgcn_global_load_lds((const unsigned*)((const char*)(gbase) + (voff)[_i]), (LAS unsigned*)(lds + (bufoff) + ldsw + _i * 8192), 16, 0, 0); } while (0)
; #define PG8_LDA(dst, b, h) do { _Pragma("unroll") for (int m = 0; m < 4; ++m) _Pragma("unroll") for (int k = 0; k < 2; ++k) dst[m][k] = *(const LAS bf16x8*)(lds + PG8_SA(b, h) + aoff + m * 2048 + k * 1024); } while (0)
; #define PG8_MMA(ai, bj, At, Bt) do { __builtin_amdgcn_s_setprio(1); _Pragma("unroll") for (int m = 0; m < 4; ++m) _Pragma("unroll") for (int n = 0; n < 2; ++n) _Pragma("unroll") for (int k = 0; k < 2; ++k) \
;         acc[ai][bj][m][n] = __builtin_amdgcn_mfma_f32_16x16x32_bf16(Bt[n][k], At[m][k], acc[ai][bj][m][n], 0, 0, 0); __builtin_amdgcn_s_setprio(0); } while (0)
; #define PG8_WAIT_V(n) asm volatile("s_waitcnt vmcnt(" #n ")" ::: "memory")
; #define PG8_WAIT_L(n) asm volatile("s_waitcnt lgkmcnt(" #n ")" ::: "memory")
; #define PG8_BAR __builtin_amdgcn_s_barrier()
; #define PG8_SCHED __builtin_amdgcn_sched_barrier(0)
; template <class Epi>
; __device__ __forceinline__ void gemm_phase(LAS unsigned char* lds, const Gemm g, const int G, const int cidx, const int tid, const Epi& E) {
;     ...
;         for (int t = 0; t < nt; t += 2) {
;     ...
;             PG8_LDA(At, 1, 1); PG8_STAGE(PG8_SB(1, 0), b3, voffB); PG8_STAGE(PG8_SB(1, 1), b3 + hstepB, voffB); PG8_STAGE(PG8_SA(1, 0), a3, voffA);
;             PG8_WAIT_V(8); PG8_WAIT_L(0); PG8_BAR; PG8_MMA(1, 0, At, B0); PG8_MMA(1, 1, At, B1); PG8_BAR; PG8_SCHED;
	s_add_i32 s58, s66, s20
	v_lshl_add_u64 v[238:239], v[238:239], 0, s[96:97]
	s_mov_b32 m0, s58
	ds_read_b128 v[190:193], v151 offset:49152
	ds_read_b128 v[210:213], v151 offset:50176
	ds_read_b128 v[214:217], v151 offset:51200
	ds_read_b128 v[218:221], v151 offset:52224
	ds_read_b128 v[222:225], v151 offset:53248
	ds_read_b128 v[226:229], v151 offset:54272
	ds_read_b128 v[230:233], v151 offset:55296
	ds_read_b128 v[234:237], v151 offset:56320
	global_load_lds_dwordx4 v[238:239], off
	s_add_i32 m0, s58, 0x2000
	s_add_u32 s56, s56, 0x40080
	v_lshl_add_u64 v[238:239], v[240:241], 0, s[96:97]
	s_addc_u32 s57, s57, 0
	s_add_i32 s58, s67, s20
	global_load_lds_dwordx4 v[238:239], off
	v_lshl_add_u64 v[238:239], s[56:57], 0, v[130:131]
	s_mov_b32 m0, s58
	s_nop 0
	global_load_lds_dwordx4 v[238:239], off
	v_lshl_add_u64 v[238:239], s[56:57], 0, v[134:135]
	s_add_i32 m0, s58, 0x2000
	s_nop 0
	global_load_lds_dwordx4 v[238:239], off
	v_lshl_add_u64 v[238:239], v[242:243], 0, s[96:97]
	s_mov_b32 m0, s62
	s_nop 0
	global_load_lds_dwordx4 v[238:239], off
	v_lshl_add_u64 v[238:239], v[244:245], 0, s[96:97]
	s_mov_b32 m0, s63
	s_nop 0
	global_load_lds_dwordx4 v[238:239], off
	s_waitcnt vmcnt(8)
	s_waitcnt lgkmcnt(0)
	s_barrier
	s_setprio 1
	s_waitcnt lgkmcnt(0)
	v_mfma_f32_16x16x32_bf16 v[60:63], v[140:143], v[190:193], v[60:63]
	v_mfma_f32_16x16x32_bf16 v[56:59], v[166:169], v[190:193], v[56:59]
	v_mfma_f32_16x16x32_bf16 v[44:47], v[140:143], v[214:217], v[44:47]
	v_mfma_f32_16x16x32_bf16 v[40:43], v[166:169], v[214:217], v[40:43]
	v_mfma_f32_16x16x32_bf16 v[28:31], v[140:143], v[222:225], v[28:31]
	v_mfma_f32_16x16x32_bf16 v[24:27], v[166:169], v[222:225], v[24:27]
	v_mfma_f32_16x16x32_bf16 v[12:15], v[140:143], v[230:233], v[12:15]
	v_mfma_f32_16x16x32_bf16 v[8:11], v[166:169], v[230:233], v[8:11]
	v_mfma_f32_16x16x32_bf16 v[60:63], v[144:147], v[210:213], v[60:63]
	v_mfma_f32_16x16x32_bf16 v[56:59], v[170:173], v[210:213], v[56:59]
	v_mfma_f32_16x16x32_bf16 v[44:47], v[144:147], v[218:221], v[44:47]
	v_mfma_f32_16x16x32_bf16 v[40:43], v[170:173], v[218:221], v[40:43]
	v_mfma_f32_16x16x32_bf16 v[28:31], v[144:147], v[226:229], v[28:31]
	v_mfma_f32_16x16x32_bf16 v[24:27], v[170:173], v[226:229], v[24:27]
	v_mfma_f32_16x16x32_bf16 v[12:15], v[144:147], v[234:237], v[12:15]
	v_mfma_f32_16x16x32_bf16 v[8:11], v[170:173], v[234:237], v[8:11]
	s_setprio 0
	s_setprio 1
	v_mfma_f32_16x16x32_bf16 v[52:55], v[174:177], v[190:193], v[52:55]
	v_mfma_f32_16x16x32_bf16 v[48:51], v[182:185], v[190:193], v[48:51]
	v_mfma_f32_16x16x32_bf16 v[36:39], v[174:177], v[214:217], v[36:39]
	v_mfma_f32_16x16x32_bf16 v[32:35], v[182:185], v[214:217], v[32:35]
	v_mfma_f32_16x16x32_bf16 v[20:23], v[174:177], v[222:225], v[20:23]
	v_mfma_f32_16x16x32_bf16 v[16:19], v[182:185], v[222:225], v[16:19]
	v_mfma_f32_16x16x32_bf16 v[4:7], v[174:177], v[230:233], v[4:7]
	v_mfma_f32_16x16x32_bf16 v[0:3], v[182:185], v[230:233], v[0:3]
	v_mfma_f32_16x16x32_bf16 v[52:55], v[178:181], v[210:213], v[52:55]
	v_mfma_f32_16x16x32_bf16 v[48:51], v[186:189], v[210:213], v[48:51]
	v_mfma_f32_16x16x32_bf16 v[36:39], v[178:181], v[218:221], v[36:39]
	v_mfma_f32_16x16x32_bf16 v[32:35], v[186:189], v[218:221], v[32:35]
	v_mfma_f32_16x16x32_bf16 v[20:23], v[178:181], v[226:229], v[20:23]
	v_mfma_f32_16x16x32_bf16 v[16:19], v[186:189], v[226:229], v[16:19]
	v_mfma_f32_16x16x32_bf16 v[4:7], v[178:181], v[234:237], v[4:7]
	v_mfma_f32_16x16x32_bf16 v[0:3], v[186:189], v[234:237], v[0:3]
	s_setprio 0
	s_add_i32 s65, s65, 2
	s_add_u32 s54, s54, 0x100
	s_addc_u32 s55, s55, 0
	s_add_u32 s35, s35, 0x100
	s_addc_u32 s53, s53, 0
	s_barrier
	s_cmp_gt_u32 s65, 13
	s_cbranch_scc0 .LBB0_647
	s_and_b64 vcc, exec, s[10:11]
	s_cbranch_vccz .LBB0_650
	s_barrier
